# DNT triangular solve and DNCONV l2norm: quad/row shuffles via DPP adds instead of ds_bpermute round trips (bit-identical sums)
# speedup vs baseline: 1.0299x; 1.0190x over previous
; __device__ __forceinline__ int crow(int r, int hi) { return (r & 3) + 8 * (r >> 2) + 4 * hi; }
; #define LAS __attribute__((address_space(3)))
; #define BAR_LDS() do { asm volatile("s_waitcnt lgkmcnt(0)" ::: "memory"); __builtin_amdgcn_s_barrier(); asm volatile("" ::: "memory"); } while (0)
; __device__ __forceinline__ int crow(int x, int h) { return (x & 3) + 8 * (x >> 2) + 4 * h; }
; template <int W> __device__ __forceinline__ void dn_solve(const LAS float* Mf, float (&t)[16], int lane) {
;     const int j = 16 * W + (lane >> 2), q = lane & 3;
; #pragma unroll
;     for (int s = 0; s < 16; ++s) t[s] = 0.f;
; #pragma unroll
;     for (int i = 16 * W; i < 64; ++i) {
;         float acc = 0.f;
; #pragma unroll
;         for (int s = 4 * W; s <= (i - 1) / 4 && i > 16 * W; ++s) acc += Mf[i * 64 + 4 * s + q] * t[s];
;         acc += __shfl_xor(acc, 1); acc += __shfl_xor(acc, 2);
;         const float val = (i == j ? 1.f : 0.f) - acc;
;         if (q == (i & 3)) t[i >> 2] = val;
;         asm volatile("" : "+v"(t[0]), "+v"(t[1]), "+v"(t[2]), "+v"(t[3]), "+v"(t[4]), "+v"(t[5]), "+v"(t[6]), "+v"(t[7]), "+v"(t[8]), "+v"(t[9]), "+v"(t[10]), "+v"(t[11]), "+v"(t[12]), "+v"(t[13]), "+v"(t[14]), "+v"(t[15]));
;     }
; }
; __device__ __forceinline__ void dn_t_phase(LAS unsigned char* lds, const bf16_t* P, float* AB, bf16_t* TP, const float* a_log, const float* dt_bias, int G) {
;     ...
;             const int j = 32 * tj + r; const float gj = sc_gc[j];
; #pragma unroll
;             for (int x = 0; x < 16; ++x) { const int i = 32 * ti + crow(x, h);
;                 Mf[i * 64 + j] = (i > j) ? sc_beta[i] * acc[x] * __expf(sc_gc[i] - gj) : 0.f; }
;         }
;         BAR_LDS();
;         float tc[16];
;         if (w == 0) dn_solve<0>(Mf, tc, lane); else if (w == 1) dn_solve<1>(Mf, tc, lane); else if (w == 2) dn_solve<2>(Mf, tc, lane); else dn_solve<3>(Mf, tc, lane);
.LBB0_108:
	s_or_b64 exec, exec, s[0:1]
	v_lshl_add_u32 v3, v3, 8, v36
	ds_write_b32 v3, v2 offset:17408
	v_and_b32_e32 v3, 64, v190
	v_xor_b32_e32 v2, 1, v190
	v_add_u32_e32 v3, 64, v3
	v_cmp_lt_i32_e32 vcc, v2, v3
	v_and_b32_e32 v52, 3, v49
	s_waitcnt lgkmcnt(0)
	s_barrier
	v_cndmask_b32_e32 v2, v190, v2, vcc
	v_lshlrev_b32_e32 v54, 2, v2
	v_xor_b32_e32 v2, 2, v190
	v_cmp_lt_i32_e32 vcc, v2, v3
	v_cmp_eq_u32_e64 s[42:43], 0, v52
	v_lshrrev_b32_e32 v53, 2, v34
	v_cndmask_b32_e32 v2, v190, v2, vcc
	v_cmp_gt_u32_e32 vcc, 4, v34
	s_and_b64 s[0:1], s[42:43], vcc
	v_lshl_add_u32 v56, v52, 2, s19
	v_lshlrev_b32_e32 v55, 2, v2
	v_cndmask_b32_e64 v57, 0, 1.0, s[0:1]
	s_cmp_lt_i32 s80, 2
	s_mov_b64 s[0:1], -1
	s_cbranch_scc1 .LBB0_114
	s_cmp_gt_i32 s80, 2
	s_cbranch_scc0 .LBB0_111
	v_mov_b32_e32 v2, v1
	v_mov_b32_e32 v4, v1
	v_mov_b32_e32 v6, v1
	v_mov_b32_e32 v8, v1
	v_mov_b32_e32 v10, v1
	v_mov_b32_e32 v12, v1
	v_mov_b32_e32 v14, v1
	v_mov_b32_e32 v16, v1
	v_mov_b32_e32 v34, v1
	v_mov_b32_e32 v36, v1
	v_mov_b32_e32 v38, v1
	v_mov_b32_e32 v40, v1
	v_mov_b32_e32 v5, v1
	v_mov_b32_e32 v7, v1
	v_mov_b32_e32 v3, v1
	v_mov_b32_e32 v9, v57
	ds_read_b32 v11, v56 offset:30144
	v_cmp_eq_u32_e32 vcc, 1, v53
	v_cmp_eq_u32_e64 s[44:45], 1, v52
	v_cmp_eq_u32_e64 s[0:1], 2, v52
	v_cndmask_b32_e64 v15, 0, 1.0, vcc
	s_waitcnt lgkmcnt(0)
	v_fma_f32 v11, v11, v9, 0
	v_cmp_eq_u32_e32 vcc, 2, v53
	v_cmp_eq_u32_e64 s[46:47], 4, v53
	s_waitcnt lgkmcnt(0)
	s_nop 1
	v_add_f32_dpp v11, v11, v11 quad_perm:[1,0,3,2] row_mask:0xf bank_mask:0xf
	s_nop 1
	v_add_f32_dpp v11, v11, v11 quad_perm:[2,3,0,1] row_mask:0xf bank_mask:0xf
	v_sub_f32_e32 v11, v15, v11
	v_cndmask_b32_e64 v9, v9, v11, s[44:45]
	ds_read_b32 v11, v56 offset:30400
	v_cndmask_b32_e64 v15, 0, 1.0, vcc
	v_cmp_eq_u32_e32 vcc, 3, v53
	s_waitcnt lgkmcnt(0)
	v_fma_f32 v11, v11, v9, 0
	s_nop 1
	v_add_f32_dpp v11, v11, v11 quad_perm:[1,0,3,2] row_mask:0xf bank_mask:0xf
	s_nop 1
	v_add_f32_dpp v11, v11, v11 quad_perm:[2,3,0,1] row_mask:0xf bank_mask:0xf
	v_sub_f32_e32 v11, v15, v11
	v_cndmask_b32_e64 v9, v9, v11, s[0:1]
	ds_read_b32 v11, v56 offset:30656
	v_cndmask_b32_e64 v15, 0, 1.0, vcc
	v_cmp_eq_u32_e32 vcc, 3, v52
	s_waitcnt lgkmcnt(0)
	v_fma_f32 v11, v11, v9, 0
	s_nop 1
	v_add_f32_dpp v11, v11, v11 quad_perm:[1,0,3,2] row_mask:0xf bank_mask:0xf
	s_nop 1
	v_add_f32_dpp v11, v11, v11 quad_perm:[2,3,0,1] row_mask:0xf bank_mask:0xf
	v_sub_f32_e32 v11, v15, v11
	v_cndmask_b32_e32 v42, v9, v11, vcc
	ds_read_b32 v9, v56 offset:30912
	v_cndmask_b32_e64 v13, 0, 1.0, s[46:47]
	v_add_u32_e32 v15, 0x7800, v56
	v_cmp_eq_u32_e64 s[46:47], 5, v53
	s_waitcnt lgkmcnt(0)
	v_fma_f32 v9, v9, v42, 0
	s_nop 1
	v_add_f32_dpp v9, v9, v9 quad_perm:[1,0,3,2] row_mask:0xf bank_mask:0xf
	s_nop 1
	v_add_f32_dpp v9, v9, v9 quad_perm:[2,3,0,1] row_mask:0xf bank_mask:0xf
	v_sub_f32_e32 v9, v13, v9
	v_cndmask_b32_e64 v43, v5, v9, s[42:43]
	ds_read2_b32 v[44:45], v15 offset0:112 offset1:116
	v_cndmask_b32_e64 v11, 0, 1.0, s[46:47]
	v_cmp_eq_u32_e64 s[46:47], 6, v53
	v_add_u32_e32 v13, 0x7c00, v56
	s_waitcnt lgkmcnt(0)
	v_pk_mul_f32 v[44:45], v[44:45], v[42:43]
	s_nop 0
	v_add_f32_e32 v5, 0, v44
	v_add_f32_e32 v5, v5, v45
	s_nop 1
	v_add_f32_dpp v5, v5, v5 quad_perm:[1,0,3,2] row_mask:0xf bank_mask:0xf
	s_nop 1
	v_add_f32_dpp v5, v5, v5 quad_perm:[2,3,0,1] row_mask:0xf bank_mask:0xf
	v_sub_f32_e32 v5, v11, v5
	v_cndmask_b32_e64 v43, v43, v5, s[44:45]
	ds_read2_b32 v[44:45], v15 offset0:176 offset1:180
	v_cndmask_b32_e64 v11, 0, 1.0, s[46:47]
	v_cmp_eq_u32_e64 s[46:47], 7, v53
	s_waitcnt lgkmcnt(0)
	v_pk_mul_f32 v[44:45], v[44:45], v[42:43]
	s_nop 0
	v_add_f32_e32 v5, 0, v44
	v_add_f32_e32 v5, v5, v45
	s_nop 1
	v_add_f32_dpp v5, v5, v5 quad_perm:[1,0,3,2] row_mask:0xf bank_mask:0xf
	s_nop 1
	v_add_f32_dpp v5, v5, v5 quad_perm:[2,3,0,1] row_mask:0xf bank_mask:0xf
	v_sub_f32_e32 v5, v11, v5
	v_cndmask_b32_e64 v43, v43, v5, s[0:1]
	ds_read2_b32 v[44:45], v15 offset0:240 offset1:244
	v_cndmask_b32_e64 v11, 0, 1.0, s[46:47]
	v_cmp_eq_u32_e64 s[46:47], 8, v53
	s_waitcnt lgkmcnt(0)
	v_pk_mul_f32 v[44:45], v[44:45], v[42:43]
	s_nop 0
	v_add_f32_e32 v5, 0, v44
	v_add_f32_e32 v5, v5, v45
	s_nop 1
	v_add_f32_dpp v5, v5, v5 quad_perm:[1,0,3,2] row_mask:0xf bank_mask:0xf
	s_nop 1
	v_add_f32_dpp v5, v5, v5 quad_perm:[2,3,0,1] row_mask:0xf bank_mask:0xf
	v_sub_f32_e32 v5, v11, v5
	v_cndmask_b32_e32 v44, v43, v5, vcc
	ds_read2_b32 v[46:47], v13 offset0:48 offset1:52
	v_mov_b32_e32 v43, v44
	v_cndmask_b32_e64 v11, 0, 1.0, s[46:47]
	v_cmp_eq_u32_e64 s[46:47], 9, v53
	s_waitcnt lgkmcnt(0)
	v_pk_mul_f32 v[46:47], v[46:47], v[42:43]
	s_nop 0
	v_add_f32_e32 v5, 0, v46
	v_add_f32_e32 v5, v5, v47
	s_nop 1
	v_add_f32_dpp v5, v5, v5 quad_perm:[1,0,3,2] row_mask:0xf bank_mask:0xf
	s_nop 1
	v_add_f32_dpp v5, v5, v5 quad_perm:[2,3,0,1] row_mask:0xf bank_mask:0xf
	v_sub_f32_e32 v5, v11, v5
	v_cndmask_b32_e64 v45, v7, v5, s[42:43]
	ds_read2_b32 v[46:47], v13 offset0:112 offset1:116
	ds_read_b32 v59, v56 offset:32224
	v_cndmask_b32_e64 v9, 0, 1.0, s[46:47]
	v_cmp_eq_u32_e64 s[46:47], 10, v53
	v_add_u32_e32 v11, 0x8000, v56
	s_waitcnt lgkmcnt(1)
	v_mov_b32_e32 v58, v47
	v_fma_f32 v5, v46, v42, 0
	s_waitcnt lgkmcnt(0)
	v_pk_mul_f32 v[46:47], v[44:45], v[58:59]
	s_nop 0
	v_add_f32_e32 v5, v5, v46
	v_add_f32_e32 v5, v5, v47
	s_nop 1
	v_add_f32_dpp v5, v5, v5 quad_perm:[1,0,3,2] row_mask:0xf bank_mask:0xf
	s_nop 1
	v_add_f32_dpp v5, v5, v5 quad_perm:[2,3,0,1] row_mask:0xf bank_mask:0xf
	v_sub_f32_e32 v5, v9, v5
	v_cndmask_b32_e64 v45, v45, v5, s[44:45]
	ds_read2_b32 v[46:47], v13 offset0:176 offset1:180
	ds_read_b32 v59, v56 offset:32480
	v_cndmask_b32_e64 v9, 0, 1.0, s[46:47]
	v_cmp_eq_u32_e64 s[46:47], 11, v53
	s_waitcnt lgkmcnt(1)
; #define LAS __attribute__((address_space(3)))
; template <int W> __device__ __forceinline__ void dn_solve(const LAS float* Mf, float (&t)[16], int lane) {
;     const int j = 16 * W + (lane >> 2), q = lane & 3;
; #pragma unroll
;     for (int s = 0; s < 16; ++s) t[s] = 0.f;
; #pragma unroll
;     for (int i = 16 * W; i < 64; ++i) {
;         float acc = 0.f;
; #pragma unroll
;         for (int s = 4 * W; s <= (i - 1) / 4 && i > 16 * W; ++s) acc += Mf[i * 64 + 4 * s + q] * t[s];
;         acc += __shfl_xor(acc, 1); acc += __shfl_xor(acc, 2);
;         const float val = (i == j ? 1.f : 0.f) - acc;
;         if (q == (i & 3)) t[i >> 2] = val;
;         asm volatile("" : "+v"(t[0]), "+v"(t[1]), "+v"(t[2]), "+v"(t[3]), "+v"(t[4]), "+v"(t[5]), "+v"(t[6]), "+v"(t[7]), "+v"(t[8]), "+v"(t[9]), "+v"(t[10]), "+v"(t[11]), "+v"(t[12]), "+v"(t[13]), "+v"(t[14]), "+v"(t[15]));
;     }
; }
	v_mov_b32_e32 v58, v47
	v_fma_f32 v5, v46, v42, 0
	s_waitcnt lgkmcnt(0)
	v_pk_mul_f32 v[46:47], v[44:45], v[58:59]
	s_nop 0
	v_add_f32_e32 v5, v5, v46
	v_add_f32_e32 v5, v5, v47
	s_nop 1
	v_add_f32_dpp v5, v5, v5 quad_perm:[1,0,3,2] row_mask:0xf bank_mask:0xf
	s_nop 1
	v_add_f32_dpp v5, v5, v5 quad_perm:[2,3,0,1] row_mask:0xf bank_mask:0xf
	v_sub_f32_e32 v5, v9, v5
	v_cndmask_b32_e64 v45, v45, v5, s[0:1]
	ds_read2_b32 v[46:47], v13 offset0:240 offset1:244
	ds_read_b32 v59, v56 offset:32736
	v_cndmask_b32_e64 v9, 0, 1.0, s[46:47]
	v_cmp_eq_u32_e64 s[46:47], 12, v53
	s_waitcnt lgkmcnt(1)
	v_mov_b32_e32 v58, v47
	v_fma_f32 v5, v46, v42, 0
	s_waitcnt lgkmcnt(0)
	v_pk_mul_f32 v[46:47], v[44:45], v[58:59]
	s_nop 0
	v_add_f32_e32 v5, v5, v46
	v_add_f32_e32 v5, v5, v47
	s_nop 1
	v_add_f32_dpp v5, v5, v5 quad_perm:[1,0,3,2] row_mask:0xf bank_mask:0xf
	s_nop 1
	v_add_f32_dpp v5, v5, v5 quad_perm:[2,3,0,1] row_mask:0xf bank_mask:0xf
	v_sub_f32_e32 v5, v9, v5
	v_cndmask_b32_e32 v46, v45, v5, vcc
	ds_read2_b32 v[58:59], v11 offset0:48 offset1:52
	ds_read_b32 v61, v56 offset:32992
	v_mov_b32_e32 v45, v46
	v_cndmask_b32_e64 v9, 0, 1.0, s[46:47]
	v_cmp_eq_u32_e64 s[46:47], 13, v53
	s_waitcnt lgkmcnt(1)
	v_mov_b32_e32 v60, v59
	v_fma_f32 v5, v58, v42, 0
	s_waitcnt lgkmcnt(0)
	v_pk_mul_f32 v[58:59], v[44:45], v[60:61]
	s_nop 0
	v_add_f32_e32 v5, v5, v58
	v_add_f32_e32 v5, v5, v59
	s_nop 1
	v_add_f32_dpp v5, v5, v5 quad_perm:[1,0,3,2] row_mask:0xf bank_mask:0xf
	s_nop 1
	v_add_f32_dpp v5, v5, v5 quad_perm:[2,3,0,1] row_mask:0xf bank_mask:0xf
	v_sub_f32_e32 v5, v9, v5
	v_cndmask_b32_e64 v47, v3, v5, s[42:43]
	ds_read2_b32 v[58:59], v11 offset0:112 offset1:116
	ds_read2_b32 v[60:61], v11 offset0:120 offset1:124
	v_mov_b32_e32 v43, v44
	v_cndmask_b32_e64 v7, 0, 1.0, s[46:47]
	s_waitcnt lgkmcnt(1)
	v_pk_mul_f32 v[58:59], v[58:59], v[42:43]
	s_nop 0
	v_add_f32_e32 v3, 0, v58
	s_waitcnt lgkmcnt(0)
	v_pk_mul_f32 v[60:61], v[46:47], v[60:61]
	v_add_f32_e32 v3, v3, v59
	v_add_f32_e32 v3, v3, v60
	v_add_f32_e32 v3, v3, v61
	s_nop 1
	v_add_f32_dpp v3, v3, v3 quad_perm:[1,0,3,2] row_mask:0xf bank_mask:0xf
	s_nop 1
	v_add_f32_dpp v3, v3, v3 quad_perm:[2,3,0,1] row_mask:0xf bank_mask:0xf
	v_sub_f32_e32 v3, v7, v3
	v_cndmask_b32_e64 v47, v47, v3, s[44:45]
	ds_read2_b32 v[58:59], v11 offset0:176 offset1:180
	ds_read2_b32 v[60:61], v11 offset0:184 offset1:188
	v_mov_b32_e32 v43, v44
	v_cmp_eq_u32_e64 s[44:45], 14, v53
	s_waitcnt lgkmcnt(1)
	v_pk_mul_f32 v[58:59], v[58:59], v[42:43]
	s_nop 0
	v_add_f32_e32 v3, 0, v58
	s_waitcnt lgkmcnt(0)
	v_pk_mul_f32 v[60:61], v[46:47], v[60:61]
	v_add_f32_e32 v3, v3, v59
	v_add_f32_e32 v3, v3, v60
	v_add_f32_e32 v3, v3, v61
	v_cndmask_b32_e64 v7, 0, 1.0, s[44:45]
	s_waitcnt lgkmcnt(0)
	s_nop 1
	v_add_f32_dpp v3, v3, v3 quad_perm:[1,0,3,2] row_mask:0xf bank_mask:0xf
	s_nop 1
	v_add_f32_dpp v3, v3, v3 quad_perm:[2,3,0,1] row_mask:0xf bank_mask:0xf
	v_sub_f32_e32 v3, v7, v3
	v_cndmask_b32_e64 v47, v47, v3, s[0:1]
	ds_read2_b32 v[58:59], v11 offset0:240 offset1:244
	ds_read2_b32 v[60:61], v11 offset0:248 offset1:252
	v_mov_b32_e32 v43, v44
	v_cmp_eq_u32_e64 s[0:1], 15, v53
	s_waitcnt lgkmcnt(1)
	v_pk_mul_f32 v[58:59], v[58:59], v[42:43]
	s_nop 0
	v_add_f32_e32 v3, 0, v58
	s_waitcnt lgkmcnt(0)
	v_pk_mul_f32 v[60:61], v[46:47], v[60:61]
	v_add_f32_e32 v3, v3, v59
	v_add_f32_e32 v3, v3, v60
	v_add_f32_e32 v3, v3, v61
	v_cndmask_b32_e64 v7, 0, 1.0, s[0:1]
	s_mov_b64 s[0:1], 0
	s_waitcnt lgkmcnt(0)
	s_nop 1
	v_add_f32_dpp v3, v3, v3 quad_perm:[1,0,3,2] row_mask:0xf bank_mask:0xf
	s_nop 1
	v_add_f32_dpp v3, v3, v3 quad_perm:[2,3,0,1] row_mask:0xf bank_mask:0xf
	v_sub_f32_e32 v3, v7, v3
	v_cndmask_b32_e32 v3, v47, v3, vcc
.LBB0_111:
	s_andn2_b64 vcc, exec, s[0:1]
	s_cbranch_vccnz .LBB0_113
	v_mov_b32_e32 v2, v1
	v_mov_b32_e32 v4, v1
	v_mov_b32_e32 v6, v1
	v_mov_b32_e32 v8, v1
	v_mov_b32_e32 v10, v1
	v_mov_b32_e32 v12, v1
	v_mov_b32_e32 v14, v1
	v_mov_b32_e32 v16, v1
	v_mov_b32_e32 v13, v1
	v_mov_b32_e32 v15, v1
	v_mov_b32_e32 v11, v1
	v_mov_b32_e32 v9, v1
	v_mov_b32_e32 v7, v1
	v_mov_b32_e32 v5, v1
	v_mov_b32_e32 v3, v1
	v_mov_b32_e32 v17, v57
	ds_read_b32 v34, v56 offset:25984
	v_cmp_eq_u32_e32 vcc, 1, v53
	v_cmp_eq_u32_e64 s[46:47], 1, v52
	v_cmp_eq_u32_e64 s[44:45], 2, v52
	v_cndmask_b32_e64 v36, 0, 1.0, vcc
	s_waitcnt lgkmcnt(0)
	v_fma_f32 v34, v34, v17, 0
	v_cmp_eq_u32_e32 vcc, 2, v53
	v_cmp_eq_u32_e64 s[0:1], 4, v53
	v_add_u32_e32 v38, 0x6800, v56
	v_add_u32_e32 v42, 0x6c00, v56
	s_waitcnt lgkmcnt(0)
	s_nop 1
	v_add_f32_dpp v34, v34, v34 quad_perm:[1,0,3,2] row_mask:0xf bank_mask:0xf
	v_add_u32_e32 v44, 0x7000, v56
	s_waitcnt lgkmcnt(0)
	s_nop 1
	v_add_f32_dpp v34, v34, v34 quad_perm:[2,3,0,1] row_mask:0xf bank_mask:0xf
	v_sub_f32_e32 v34, v36, v34
	v_cndmask_b32_e64 v17, v17, v34, s[46:47]
	ds_read_b32 v34, v56 offset:26240
	v_cndmask_b32_e64 v36, 0, 1.0, vcc
	v_cmp_eq_u32_e32 vcc, 3, v53
	s_waitcnt lgkmcnt(0)
	v_fma_f32 v34, v34, v17, 0
	s_nop 1
	v_add_f32_dpp v34, v34, v34 quad_perm:[1,0,3,2] row_mask:0xf bank_mask:0xf
	s_nop 1
	v_add_f32_dpp v34, v34, v34 quad_perm:[2,3,0,1] row_mask:0xf bank_mask:0xf
	v_sub_f32_e32 v34, v36, v34
	v_cndmask_b32_e64 v17, v17, v34, s[44:45]
	ds_read_b32 v34, v56 offset:26496
	v_cndmask_b32_e64 v36, 0, 1.0, vcc
	v_cmp_eq_u32_e32 vcc, 3, v52
	s_waitcnt lgkmcnt(0)
	v_fma_f32 v34, v34, v17, 0
	s_nop 1
	v_add_f32_dpp v34, v34, v34 quad_perm:[1,0,3,2] row_mask:0xf bank_mask:0xf
	s_nop 1
	v_add_f32_dpp v34, v34, v34 quad_perm:[2,3,0,1] row_mask:0xf bank_mask:0xf
	v_sub_f32_e32 v34, v36, v34
	v_cndmask_b32_e32 v34, v17, v34, vcc
	ds_read_b32 v17, v56 offset:26752
	v_cndmask_b32_e64 v36, 0, 1.0, s[0:1]
	v_cmp_eq_u32_e64 s[0:1], 5, v53
	s_waitcnt lgkmcnt(0)
; #define LAS __attribute__((address_space(3)))
; template <int W> __device__ __forceinline__ void dn_solve(const LAS float* Mf, float (&t)[16], int lane) {
;     const int j = 16 * W + (lane >> 2), q = lane & 3;
; #pragma unroll
;     for (int s = 0; s < 16; ++s) t[s] = 0.f;
; #pragma unroll
;     for (int i = 16 * W; i < 64; ++i) {
;         float acc = 0.f;
; #pragma unroll
;         for (int s = 4 * W; s <= (i - 1) / 4 && i > 16 * W; ++s) acc += Mf[i * 64 + 4 * s + q] * t[s];
;         acc += __shfl_xor(acc, 1); acc += __shfl_xor(acc, 2);
;         const float val = (i == j ? 1.f : 0.f) - acc;
;         if (q == (i & 3)) t[i >> 2] = val;
;         asm volatile("" : "+v"(t[0]), "+v"(t[1]), "+v"(t[2]), "+v"(t[3]), "+v"(t[4]), "+v"(t[5]), "+v"(t[6]), "+v"(t[7]), "+v"(t[8]), "+v"(t[9]), "+v"(t[10]), "+v"(t[11]), "+v"(t[12]), "+v"(t[13]), "+v"(t[14]), "+v"(t[15]));
;     }
; }
	v_fma_f32 v17, v17, v34, 0
	s_nop 1
	v_add_f32_dpp v17, v17, v17 quad_perm:[1,0,3,2] row_mask:0xf bank_mask:0xf
	s_nop 1
	v_add_f32_dpp v17, v17, v17 quad_perm:[2,3,0,1] row_mask:0xf bank_mask:0xf
	v_sub_f32_e32 v17, v36, v17
	v_cndmask_b32_e64 v35, v13, v17, s[42:43]
	ds_read2_b32 v[36:37], v38 offset0:96 offset1:100
	s_waitcnt lgkmcnt(0)
	v_pk_mul_f32 v[36:37], v[36:37], v[34:35]
	s_nop 0
	v_add_f32_e32 v13, 0, v36
	v_add_f32_e32 v13, v13, v37
	v_cndmask_b32_e64 v36, 0, 1.0, s[0:1]
	v_cmp_eq_u32_e64 s[0:1], 6, v53
	s_waitcnt lgkmcnt(0)
	s_nop 1
	v_add_f32_dpp v13, v13, v13 quad_perm:[1,0,3,2] row_mask:0xf bank_mask:0xf
	s_nop 1
	v_add_f32_dpp v13, v13, v13 quad_perm:[2,3,0,1] row_mask:0xf bank_mask:0xf
	v_sub_f32_e32 v13, v36, v13
	v_cndmask_b32_e64 v35, v35, v13, s[46:47]
	ds_read2_b32 v[36:37], v38 offset0:160 offset1:164
	s_waitcnt lgkmcnt(0)
	v_pk_mul_f32 v[36:37], v[36:37], v[34:35]
	s_nop 0
	v_add_f32_e32 v13, 0, v36
	v_add_f32_e32 v13, v13, v37
	v_cndmask_b32_e64 v36, 0, 1.0, s[0:1]
	v_cmp_eq_u32_e64 s[0:1], 7, v53
	s_waitcnt lgkmcnt(0)
	s_nop 1
	v_add_f32_dpp v13, v13, v13 quad_perm:[1,0,3,2] row_mask:0xf bank_mask:0xf
	s_nop 1
	v_add_f32_dpp v13, v13, v13 quad_perm:[2,3,0,1] row_mask:0xf bank_mask:0xf
	v_sub_f32_e32 v13, v36, v13
	v_cndmask_b32_e64 v35, v35, v13, s[44:45]
	ds_read2_b32 v[36:37], v38 offset0:224 offset1:228
	s_waitcnt lgkmcnt(0)
	v_pk_mul_f32 v[36:37], v[36:37], v[34:35]
	s_nop 0
	v_add_f32_e32 v13, 0, v36
	v_add_f32_e32 v13, v13, v37
	v_cndmask_b32_e64 v36, 0, 1.0, s[0:1]
	v_cmp_eq_u32_e64 s[0:1], 8, v53
	s_waitcnt lgkmcnt(0)
	s_nop 1
	v_add_f32_dpp v13, v13, v13 quad_perm:[1,0,3,2] row_mask:0xf bank_mask:0xf
	s_nop 1
	v_add_f32_dpp v13, v13, v13 quad_perm:[2,3,0,1] row_mask:0xf bank_mask:0xf
	v_sub_f32_e32 v13, v36, v13
	v_cndmask_b32_e32 v36, v35, v13, vcc
	ds_read2_b32 v[38:39], v42 offset0:32 offset1:36
	v_mov_b32_e32 v35, v36
	s_waitcnt lgkmcnt(0)
	v_pk_mul_f32 v[38:39], v[38:39], v[34:35]
	s_nop 0
	v_add_f32_e32 v13, 0, v38
	v_add_f32_e32 v13, v13, v39
	v_cndmask_b32_e64 v35, 0, 1.0, s[0:1]
	v_cmp_eq_u32_e64 s[0:1], 9, v53
	s_waitcnt lgkmcnt(0)
	s_nop 1
	v_add_f32_dpp v13, v13, v13 quad_perm:[1,0,3,2] row_mask:0xf bank_mask:0xf
	s_nop 1
	v_add_f32_dpp v13, v13, v13 quad_perm:[2,3,0,1] row_mask:0xf bank_mask:0xf
	v_sub_f32_e32 v13, v35, v13
	v_cndmask_b32_e64 v37, v15, v13, s[42:43]
	ds_read2_b32 v[38:39], v42 offset0:96 offset1:100
	ds_read_b32 v41, v56 offset:28064
	v_cndmask_b32_e64 v17, 0, 1.0, s[0:1]
	v_cmp_eq_u32_e64 s[0:1], 10, v53
	s_waitcnt lgkmcnt(1)
	v_mov_b32_e32 v40, v39
	v_fma_f32 v13, v38, v34, 0
	s_waitcnt lgkmcnt(0)
	v_pk_mul_f32 v[38:39], v[36:37], v[40:41]
	s_nop 0
	v_add_f32_e32 v13, v13, v38
	v_add_f32_e32 v13, v13, v39
	s_nop 1
	v_add_f32_dpp v13, v13, v13 quad_perm:[1,0,3,2] row_mask:0xf bank_mask:0xf
	s_nop 1
	v_add_f32_dpp v13, v13, v13 quad_perm:[2,3,0,1] row_mask:0xf bank_mask:0xf
	v_sub_f32_e32 v13, v17, v13
	v_cndmask_b32_e64 v37, v37, v13, s[46:47]
	ds_read2_b32 v[38:39], v42 offset0:160 offset1:164
	ds_read_b32 v41, v56 offset:28320
	v_cndmask_b32_e64 v17, 0, 1.0, s[0:1]
	v_cmp_eq_u32_e64 s[0:1], 11, v53
	s_waitcnt lgkmcnt(1)
	v_mov_b32_e32 v40, v39
	v_fma_f32 v13, v38, v34, 0
	s_waitcnt lgkmcnt(0)
	v_pk_mul_f32 v[38:39], v[36:37], v[40:41]
	s_nop 0
	v_add_f32_e32 v13, v13, v38
	v_add_f32_e32 v13, v13, v39
	s_nop 1
	v_add_f32_dpp v13, v13, v13 quad_perm:[1,0,3,2] row_mask:0xf bank_mask:0xf
	s_nop 1
	v_add_f32_dpp v13, v13, v13 quad_perm:[2,3,0,1] row_mask:0xf bank_mask:0xf
	v_sub_f32_e32 v13, v17, v13
	v_cndmask_b32_e64 v37, v37, v13, s[44:45]
	ds_read2_b32 v[38:39], v42 offset0:224 offset1:228
	ds_read_b32 v41, v56 offset:28576
	v_cndmask_b32_e64 v17, 0, 1.0, s[0:1]
	v_cmp_eq_u32_e64 s[0:1], 12, v53
	s_waitcnt lgkmcnt(1)
	v_mov_b32_e32 v40, v39
	v_fma_f32 v13, v38, v34, 0
	s_waitcnt lgkmcnt(0)
	v_pk_mul_f32 v[38:39], v[36:37], v[40:41]
	s_nop 0
	v_add_f32_e32 v13, v13, v38
	v_add_f32_e32 v13, v13, v39
	s_nop 1
	v_add_f32_dpp v13, v13, v13 quad_perm:[1,0,3,2] row_mask:0xf bank_mask:0xf
	s_nop 1
	v_add_f32_dpp v13, v13, v13 quad_perm:[2,3,0,1] row_mask:0xf bank_mask:0xf
	v_sub_f32_e32 v13, v17, v13
	v_cndmask_b32_e32 v38, v37, v13, vcc
	ds_read2_b32 v[40:41], v44 offset0:32 offset1:36
	ds_read_b32 v43, v56 offset:28832
	v_mov_b32_e32 v37, v38
	v_cndmask_b32_e64 v17, 0, 1.0, s[0:1]
	v_cmp_eq_u32_e64 s[0:1], 13, v53
	s_waitcnt lgkmcnt(1)
	v_mov_b32_e32 v42, v41
	v_fma_f32 v13, v40, v34, 0
	s_waitcnt lgkmcnt(0)
	v_pk_mul_f32 v[40:41], v[36:37], v[42:43]
	s_nop 0
	v_add_f32_e32 v13, v13, v40
	v_add_f32_e32 v13, v13, v41
	s_nop 1
	v_add_f32_dpp v13, v13, v13 quad_perm:[1,0,3,2] row_mask:0xf bank_mask:0xf
	s_nop 1
	v_add_f32_dpp v13, v13, v13 quad_perm:[2,3,0,1] row_mask:0xf bank_mask:0xf
	v_sub_f32_e32 v13, v17, v13
	v_cndmask_b32_e64 v39, v11, v13, s[42:43]
	ds_read2_b32 v[40:41], v44 offset0:96 offset1:100
	ds_read2_b32 v[42:43], v44 offset0:104 offset1:108
	v_mov_b32_e32 v35, v36
	v_cndmask_b32_e64 v15, 0, 1.0, s[0:1]
	v_cmp_eq_u32_e64 s[0:1], 14, v53
	s_waitcnt lgkmcnt(1)
	v_pk_mul_f32 v[40:41], v[40:41], v[34:35]
	s_waitcnt lgkmcnt(0)
	v_pk_mul_f32 v[42:43], v[38:39], v[42:43]
	v_add_f32_e32 v11, 0, v40
	v_add_f32_e32 v11, v11, v41
	v_add_f32_e32 v11, v11, v42
	v_add_f32_e32 v11, v11, v43
	v_add_u32_e32 v17, 0x7400, v56
	s_waitcnt lgkmcnt(0)
	s_nop 1
	v_add_f32_dpp v11, v11, v11 quad_perm:[1,0,3,2] row_mask:0xf bank_mask:0xf
	s_nop 1
	v_add_f32_dpp v11, v11, v11 quad_perm:[2,3,0,1] row_mask:0xf bank_mask:0xf
	v_sub_f32_e32 v11, v15, v11
	v_cndmask_b32_e64 v39, v39, v11, s[46:47]
	ds_read2_b32 v[40:41], v44 offset0:160 offset1:164
	ds_read2_b32 v[42:43], v44 offset0:168 offset1:172
	v_mov_b32_e32 v35, v36
	v_cndmask_b32_e64 v15, 0, 1.0, s[0:1]
	v_cmp_eq_u32_e64 s[0:1], 15, v53
	s_waitcnt lgkmcnt(1)
; #define LAS __attribute__((address_space(3)))
; template <int W> __device__ __forceinline__ void dn_solve(const LAS float* Mf, float (&t)[16], int lane) {
;     const int j = 16 * W + (lane >> 2), q = lane & 3;
; #pragma unroll
;     for (int s = 0; s < 16; ++s) t[s] = 0.f;
; #pragma unroll
;     for (int i = 16 * W; i < 64; ++i) {
;         float acc = 0.f;
; #pragma unroll
;         for (int s = 4 * W; s <= (i - 1) / 4 && i > 16 * W; ++s) acc += Mf[i * 64 + 4 * s + q] * t[s];
;         acc += __shfl_xor(acc, 1); acc += __shfl_xor(acc, 2);
;         const float val = (i == j ? 1.f : 0.f) - acc;
;         if (q == (i & 3)) t[i >> 2] = val;
;         asm volatile("" : "+v"(t[0]), "+v"(t[1]), "+v"(t[2]), "+v"(t[3]), "+v"(t[4]), "+v"(t[5]), "+v"(t[6]), "+v"(t[7]), "+v"(t[8]), "+v"(t[9]), "+v"(t[10]), "+v"(t[11]), "+v"(t[12]), "+v"(t[13]), "+v"(t[14]), "+v"(t[15]));
;     }
; }
	v_pk_mul_f32 v[40:41], v[40:41], v[34:35]
	s_waitcnt lgkmcnt(0)
	v_pk_mul_f32 v[42:43], v[38:39], v[42:43]
	v_add_f32_e32 v11, 0, v40
	v_add_f32_e32 v11, v11, v41
	v_add_f32_e32 v11, v11, v42
	v_add_f32_e32 v11, v11, v43
	s_nop 1
	v_add_f32_dpp v11, v11, v11 quad_perm:[1,0,3,2] row_mask:0xf bank_mask:0xf
	s_nop 1
	v_add_f32_dpp v11, v11, v11 quad_perm:[2,3,0,1] row_mask:0xf bank_mask:0xf
	v_sub_f32_e32 v11, v15, v11
	v_cndmask_b32_e64 v39, v39, v11, s[44:45]
	ds_read2_b32 v[40:41], v44 offset0:224 offset1:228
	ds_read2_b32 v[42:43], v44 offset0:232 offset1:236
	v_mov_b32_e32 v35, v36
	v_cndmask_b32_e64 v15, 0, 1.0, s[0:1]
	s_waitcnt lgkmcnt(1)
	v_pk_mul_f32 v[40:41], v[40:41], v[34:35]
	s_nop 0
	v_add_f32_e32 v11, 0, v40
	s_waitcnt lgkmcnt(0)
	v_pk_mul_f32 v[42:43], v[38:39], v[42:43]
	v_add_f32_e32 v11, v11, v41
	v_add_f32_e32 v11, v11, v42
	v_add_f32_e32 v11, v11, v43
	s_nop 1
	v_add_f32_dpp v11, v11, v11 quad_perm:[1,0,3,2] row_mask:0xf bank_mask:0xf
	s_nop 1
	v_add_f32_dpp v11, v11, v11 quad_perm:[2,3,0,1] row_mask:0xf bank_mask:0xf
	v_sub_f32_e32 v11, v15, v11
	v_cndmask_b32_e32 v40, v39, v11, vcc
	ds_read2_b32 v[42:43], v17 offset0:32 offset1:36
	ds_read2_b32 v[44:45], v17 offset0:40 offset1:44
	v_mov_b32_e32 v35, v36
	v_mov_b32_e32 v39, v40
	s_waitcnt lgkmcnt(1)
	v_pk_mul_f32 v[42:43], v[42:43], v[34:35]
	s_nop 0
	v_add_f32_e32 v11, 0, v42
	s_waitcnt lgkmcnt(0)
	v_pk_mul_f32 v[44:45], v[38:39], v[44:45]
	v_add_f32_e32 v11, v11, v43
	v_add_f32_e32 v11, v11, v44
	v_add_f32_e32 v11, v11, v45
	s_nop 1
	v_add_f32_dpp v11, v11, v11 quad_perm:[1,0,3,2] row_mask:0xf bank_mask:0xf
	s_nop 1
	v_add_f32_dpp v11, v11, v11 quad_perm:[2,3,0,1] row_mask:0xf bank_mask:0xf
	v_sub_f32_e32 v11, 0, v11
	v_cndmask_b32_e64 v41, v9, v11, s[42:43]
	ds_read2_b32 v[42:43], v17 offset0:96 offset1:100
	ds_read2_b32 v[44:45], v17 offset0:104 offset1:108
	ds_read_b32 v47, v56 offset:30144
	v_mov_b32_e32 v37, v38
	v_add_u32_e32 v13, 0x7800, v56
	s_waitcnt lgkmcnt(2)
	v_fma_f32 v9, v42, v34, 0
	v_mov_b32_e32 v42, v43
	s_waitcnt lgkmcnt(1)
	v_mov_b32_e32 v43, v44
	v_pk_mul_f32 v[42:43], v[36:37], v[42:43]
	v_mov_b32_e32 v46, v45
	v_add_f32_e32 v9, v9, v42
	s_waitcnt lgkmcnt(0)
	v_pk_mul_f32 v[44:45], v[40:41], v[46:47]
	v_add_f32_e32 v9, v9, v43
	v_add_f32_e32 v9, v9, v44
	v_add_f32_e32 v9, v9, v45
	s_nop 1
	v_add_f32_dpp v9, v9, v9 quad_perm:[1,0,3,2] row_mask:0xf bank_mask:0xf
	s_nop 1
	v_add_f32_dpp v9, v9, v9 quad_perm:[2,3,0,1] row_mask:0xf bank_mask:0xf
	v_sub_f32_e32 v9, 0, v9
	v_cndmask_b32_e64 v41, v41, v9, s[46:47]
	ds_read2_b32 v[42:43], v17 offset0:160 offset1:164
	ds_read2_b32 v[44:45], v17 offset0:168 offset1:172
	ds_read_b32 v47, v56 offset:30400
	v_mov_b32_e32 v37, v38
	s_waitcnt lgkmcnt(2)
	v_fma_f32 v9, v42, v34, 0
	v_mov_b32_e32 v42, v43
	s_waitcnt lgkmcnt(1)
	v_mov_b32_e32 v43, v44
	v_pk_mul_f32 v[42:43], v[36:37], v[42:43]
	v_mov_b32_e32 v46, v45
	v_add_f32_e32 v9, v9, v42
	s_waitcnt lgkmcnt(0)
	v_pk_mul_f32 v[44:45], v[40:41], v[46:47]
	v_add_f32_e32 v9, v9, v43
	v_add_f32_e32 v9, v9, v44
	v_add_f32_e32 v9, v9, v45
	s_nop 1
	v_add_f32_dpp v9, v9, v9 quad_perm:[1,0,3,2] row_mask:0xf bank_mask:0xf
	s_nop 1
	v_add_f32_dpp v9, v9, v9 quad_perm:[2,3,0,1] row_mask:0xf bank_mask:0xf
	v_sub_f32_e32 v9, 0, v9
	v_cndmask_b32_e64 v41, v41, v9, s[44:45]
	ds_read2_b32 v[42:43], v17 offset0:224 offset1:228
	ds_read2_b32 v[44:45], v17 offset0:232 offset1:236
	ds_read_b32 v47, v56 offset:30656
	v_mov_b32_e32 v37, v38
	s_waitcnt lgkmcnt(2)
	v_fma_f32 v9, v42, v34, 0
	v_mov_b32_e32 v42, v43
	s_waitcnt lgkmcnt(1)
	v_mov_b32_e32 v43, v44
	v_pk_mul_f32 v[42:43], v[36:37], v[42:43]
	v_mov_b32_e32 v46, v45
	v_add_f32_e32 v9, v9, v42
	s_waitcnt lgkmcnt(0)
	v_pk_mul_f32 v[44:45], v[40:41], v[46:47]
	v_add_f32_e32 v9, v9, v43
	v_add_f32_e32 v9, v9, v44
	v_add_f32_e32 v9, v9, v45
	s_nop 1
	v_add_f32_dpp v9, v9, v9 quad_perm:[1,0,3,2] row_mask:0xf bank_mask:0xf
	s_nop 1
	v_add_f32_dpp v9, v9, v9 quad_perm:[2,3,0,1] row_mask:0xf bank_mask:0xf
	v_sub_f32_e32 v9, 0, v9
	v_cndmask_b32_e32 v42, v41, v9, vcc
	ds_read2_b32 v[44:45], v13 offset0:32 offset1:36
	ds_read2_b32 v[46:47], v13 offset0:40 offset1:44
	ds_read_b32 v59, v56 offset:30912
	v_mov_b32_e32 v37, v38
	v_mov_b32_e32 v41, v42
	s_waitcnt lgkmcnt(2)
	v_fma_f32 v9, v44, v34, 0
	v_mov_b32_e32 v44, v45
	s_waitcnt lgkmcnt(1)
	v_mov_b32_e32 v45, v46
	v_pk_mul_f32 v[44:45], v[36:37], v[44:45]
	v_mov_b32_e32 v58, v47
	v_add_f32_e32 v9, v9, v44
	s_waitcnt lgkmcnt(0)
	v_pk_mul_f32 v[46:47], v[40:41], v[58:59]
	v_add_f32_e32 v9, v9, v45
	v_add_f32_e32 v9, v9, v46
	v_add_f32_e32 v9, v9, v47
	s_nop 1
	v_add_f32_dpp v9, v9, v9 quad_perm:[1,0,3,2] row_mask:0xf bank_mask:0xf
	s_nop 1
	v_add_f32_dpp v9, v9, v9 quad_perm:[2,3,0,1] row_mask:0xf bank_mask:0xf
	v_sub_f32_e32 v9, 0, v9
	v_cndmask_b32_e64 v43, v7, v9, s[42:43]
	ds_read2_b32 v[44:45], v13 offset0:96 offset1:100
	ds_read2_b32 v[46:47], v13 offset0:104 offset1:108
	ds_read2_b32 v[58:59], v13 offset0:112 offset1:116
	v_mov_b32_e32 v39, v40
	v_add_u32_e32 v11, 0x7c00, v56
	s_waitcnt lgkmcnt(2)
	v_fma_f32 v7, v44, v34, 0
	s_waitcnt lgkmcnt(1)
	v_pk_mul_f32 v[46:47], v[38:39], v[46:47]
	v_fmac_f32_e32 v7, v36, v45
	v_add_f32_e32 v7, v7, v46
	s_waitcnt lgkmcnt(0)
	v_pk_mul_f32 v[58:59], v[42:43], v[58:59]
	v_add_f32_e32 v7, v7, v47
	v_add_f32_e32 v7, v7, v58
	v_add_f32_e32 v7, v7, v59
	s_nop 1
	v_add_f32_dpp v7, v7, v7 quad_perm:[1,0,3,2] row_mask:0xf bank_mask:0xf
	s_nop 1
	v_add_f32_dpp v7, v7, v7 quad_perm:[2,3,0,1] row_mask:0xf bank_mask:0xf
	v_sub_f32_e32 v7, 0, v7
	v_cndmask_b32_e64 v43, v43, v7, s[46:47]
	ds_read2_b32 v[44:45], v13 offset0:160 offset1:164
	ds_read2_b32 v[46:47], v13 offset0:168 offset1:172
	ds_read2_b32 v[58:59], v13 offset0:176 offset1:180
	v_mov_b32_e32 v39, v40
	s_waitcnt lgkmcnt(2)
; #define LAS __attribute__((address_space(3)))
; template <int W> __device__ __forceinline__ void dn_solve(const LAS float* Mf, float (&t)[16], int lane) {
;     const int j = 16 * W + (lane >> 2), q = lane & 3;
; #pragma unroll
;     for (int s = 0; s < 16; ++s) t[s] = 0.f;
; #pragma unroll
;     for (int i = 16 * W; i < 64; ++i) {
;         float acc = 0.f;
; #pragma unroll
;         for (int s = 4 * W; s <= (i - 1) / 4 && i > 16 * W; ++s) acc += Mf[i * 64 + 4 * s + q] * t[s];
;         acc += __shfl_xor(acc, 1); acc += __shfl_xor(acc, 2);
;         const float val = (i == j ? 1.f : 0.f) - acc;
;         if (q == (i & 3)) t[i >> 2] = val;
;         asm volatile("" : "+v"(t[0]), "+v"(t[1]), "+v"(t[2]), "+v"(t[3]), "+v"(t[4]), "+v"(t[5]), "+v"(t[6]), "+v"(t[7]), "+v"(t[8]), "+v"(t[9]), "+v"(t[10]), "+v"(t[11]), "+v"(t[12]), "+v"(t[13]), "+v"(t[14]), "+v"(t[15]));
;     }
; }
	v_fma_f32 v7, v44, v34, 0
	s_waitcnt lgkmcnt(1)
	v_pk_mul_f32 v[46:47], v[38:39], v[46:47]
	v_fmac_f32_e32 v7, v36, v45
	v_add_f32_e32 v7, v7, v46
	s_waitcnt lgkmcnt(0)
	v_pk_mul_f32 v[58:59], v[42:43], v[58:59]
	v_add_f32_e32 v7, v7, v47
	v_add_f32_e32 v7, v7, v58
	v_add_f32_e32 v7, v7, v59
	s_nop 1
	v_add_f32_dpp v7, v7, v7 quad_perm:[1,0,3,2] row_mask:0xf bank_mask:0xf
	s_nop 1
	v_add_f32_dpp v7, v7, v7 quad_perm:[2,3,0,1] row_mask:0xf bank_mask:0xf
	v_sub_f32_e32 v7, 0, v7
	v_cndmask_b32_e64 v43, v43, v7, s[44:45]
	ds_read2_b32 v[44:45], v13 offset0:224 offset1:228
	ds_read2_b32 v[46:47], v13 offset0:232 offset1:236
	ds_read2_b32 v[58:59], v13 offset0:240 offset1:244
	v_mov_b32_e32 v39, v40
	s_waitcnt lgkmcnt(2)
	v_fma_f32 v7, v44, v34, 0
	s_waitcnt lgkmcnt(1)
	v_pk_mul_f32 v[46:47], v[38:39], v[46:47]
	v_fmac_f32_e32 v7, v36, v45
	v_add_f32_e32 v7, v7, v46
	s_waitcnt lgkmcnt(0)
	v_pk_mul_f32 v[58:59], v[42:43], v[58:59]
	v_add_f32_e32 v7, v7, v47
	v_add_f32_e32 v7, v7, v58
	v_add_f32_e32 v7, v7, v59
	s_nop 1
	v_add_f32_dpp v7, v7, v7 quad_perm:[1,0,3,2] row_mask:0xf bank_mask:0xf
	s_nop 1
	v_add_f32_dpp v7, v7, v7 quad_perm:[2,3,0,1] row_mask:0xf bank_mask:0xf
	v_sub_f32_e32 v7, 0, v7
	v_cndmask_b32_e32 v44, v43, v7, vcc
	ds_read2_b32 v[46:47], v11 offset0:32 offset1:36
	ds_read2_b32 v[58:59], v11 offset0:40 offset1:44
	ds_read2_b32 v[60:61], v11 offset0:48 offset1:52
	v_mov_b32_e32 v39, v40
	v_mov_b32_e32 v43, v44
	s_waitcnt lgkmcnt(2)
	v_fma_f32 v7, v46, v34, 0
	s_waitcnt lgkmcnt(1)
	v_pk_mul_f32 v[58:59], v[38:39], v[58:59]
	v_fmac_f32_e32 v7, v36, v47
	v_add_f32_e32 v7, v7, v58
	s_waitcnt lgkmcnt(0)
	v_pk_mul_f32 v[60:61], v[42:43], v[60:61]
	v_add_f32_e32 v7, v7, v59
	v_add_f32_e32 v7, v7, v60
	v_add_f32_e32 v7, v7, v61
	s_nop 1
	v_add_f32_dpp v7, v7, v7 quad_perm:[1,0,3,2] row_mask:0xf bank_mask:0xf
	s_nop 1
	v_add_f32_dpp v7, v7, v7 quad_perm:[2,3,0,1] row_mask:0xf bank_mask:0xf
	v_sub_f32_e32 v7, 0, v7
	v_cndmask_b32_e64 v45, v5, v7, s[42:43]
	ds_read2_b32 v[46:47], v11 offset0:96 offset1:100
	ds_read2_b32 v[58:59], v11 offset0:104 offset1:108
	ds_read2_b32 v[60:61], v11 offset0:112 offset1:116
	ds_read_b32 v63, v56 offset:32224
	v_mov_b32_e32 v41, v42
	s_waitcnt lgkmcnt(3)
	v_fma_f32 v5, v46, v34, 0
	s_waitcnt lgkmcnt(2)
	v_mov_b32_e32 v64, v59
	s_waitcnt lgkmcnt(1)
	v_mov_b32_e32 v65, v60
	v_fmac_f32_e32 v5, v36, v47
	v_pk_mul_f32 v[46:47], v[40:41], v[64:65]
	v_fmac_f32_e32 v5, v38, v58
	v_mov_b32_e32 v62, v61
	v_add_f32_e32 v5, v5, v46
	s_waitcnt lgkmcnt(0)
	v_pk_mul_f32 v[60:61], v[44:45], v[62:63]
	v_add_f32_e32 v5, v5, v47
	v_add_f32_e32 v5, v5, v60
	v_add_f32_e32 v5, v5, v61
	v_add_u32_e32 v9, 0x8000, v56
	s_waitcnt lgkmcnt(0)
	s_nop 1
	v_add_f32_dpp v5, v5, v5 quad_perm:[1,0,3,2] row_mask:0xf bank_mask:0xf
	s_nop 1
	v_add_f32_dpp v5, v5, v5 quad_perm:[2,3,0,1] row_mask:0xf bank_mask:0xf
	v_sub_f32_e32 v5, 0, v5
	v_cndmask_b32_e64 v45, v45, v5, s[46:47]
	ds_read2_b32 v[46:47], v11 offset0:160 offset1:164
	ds_read2_b32 v[58:59], v11 offset0:168 offset1:172
	ds_read2_b32 v[60:61], v11 offset0:176 offset1:180
	ds_read_b32 v63, v56 offset:32480
	v_mov_b32_e32 v41, v42
	s_waitcnt lgkmcnt(3)
	v_fma_f32 v5, v46, v34, 0
	s_waitcnt lgkmcnt(2)
	v_mov_b32_e32 v64, v59
	s_waitcnt lgkmcnt(1)
	v_mov_b32_e32 v65, v60
	v_fmac_f32_e32 v5, v36, v47
	v_pk_mul_f32 v[46:47], v[40:41], v[64:65]
	v_fmac_f32_e32 v5, v38, v58
	v_mov_b32_e32 v62, v61
	v_add_f32_e32 v5, v5, v46
	s_waitcnt lgkmcnt(0)
	v_pk_mul_f32 v[60:61], v[44:45], v[62:63]
	v_add_f32_e32 v5, v5, v47
	v_add_f32_e32 v5, v5, v60
	v_add_f32_e32 v5, v5, v61
	s_nop 1
	v_add_f32_dpp v5, v5, v5 quad_perm:[1,0,3,2] row_mask:0xf bank_mask:0xf
	s_nop 1
	v_add_f32_dpp v5, v5, v5 quad_perm:[2,3,0,1] row_mask:0xf bank_mask:0xf
	v_sub_f32_e32 v5, 0, v5
	v_cndmask_b32_e64 v45, v45, v5, s[44:45]
	ds_read2_b32 v[46:47], v11 offset0:224 offset1:228
	ds_read2_b32 v[58:59], v11 offset0:232 offset1:236
	ds_read2_b32 v[60:61], v11 offset0:240 offset1:244
	ds_read_b32 v63, v56 offset:32736
	v_mov_b32_e32 v41, v42
	s_waitcnt lgkmcnt(3)
	v_fma_f32 v5, v46, v34, 0
	s_waitcnt lgkmcnt(2)
; #define LAS __attribute__((address_space(3)))
; template <int W> __device__ __forceinline__ void dn_solve(const LAS float* Mf, float (&t)[16], int lane) {
;     const int j = 16 * W + (lane >> 2), q = lane & 3;
; #pragma unroll
;     for (int s = 0; s < 16; ++s) t[s] = 0.f;
; #pragma unroll
;     for (int i = 16 * W; i < 64; ++i) {
;         float acc = 0.f;
; #pragma unroll
;         for (int s = 4 * W; s <= (i - 1) / 4 && i > 16 * W; ++s) acc += Mf[i * 64 + 4 * s + q] * t[s];
;         acc += __shfl_xor(acc, 1); acc += __shfl_xor(acc, 2);
;         const float val = (i == j ? 1.f : 0.f) - acc;
;         if (q == (i & 3)) t[i >> 2] = val;
;         asm volatile("" : "+v"(t[0]), "+v"(t[1]), "+v"(t[2]), "+v"(t[3]), "+v"(t[4]), "+v"(t[5]), "+v"(t[6]), "+v"(t[7]), "+v"(t[8]), "+v"(t[9]), "+v"(t[10]), "+v"(t[11]), "+v"(t[12]), "+v"(t[13]), "+v"(t[14]), "+v"(t[15]));
;     }
; }
	v_mov_b32_e32 v64, v59
	s_waitcnt lgkmcnt(1)
	v_mov_b32_e32 v65, v60
	v_fmac_f32_e32 v5, v36, v47
	v_pk_mul_f32 v[46:47], v[40:41], v[64:65]
	v_fmac_f32_e32 v5, v38, v58
	v_mov_b32_e32 v62, v61
	v_add_f32_e32 v5, v5, v46
	s_waitcnt lgkmcnt(0)
	v_pk_mul_f32 v[60:61], v[44:45], v[62:63]
	v_add_f32_e32 v5, v5, v47
	v_add_f32_e32 v5, v5, v60
	v_add_f32_e32 v5, v5, v61
	s_nop 1
	v_add_f32_dpp v5, v5, v5 quad_perm:[1,0,3,2] row_mask:0xf bank_mask:0xf
	s_nop 1
	v_add_f32_dpp v5, v5, v5 quad_perm:[2,3,0,1] row_mask:0xf bank_mask:0xf
	v_sub_f32_e32 v5, 0, v5
	v_cndmask_b32_e32 v46, v45, v5, vcc
	ds_read2_b32 v[58:59], v9 offset0:32 offset1:36
	ds_read2_b32 v[60:61], v9 offset0:40 offset1:44
	ds_read2_b32 v[62:63], v9 offset0:48 offset1:52
	ds_read_b32 v65, v56 offset:32992
	v_mov_b32_e32 v41, v42
	s_waitcnt lgkmcnt(3)
	v_fma_f32 v5, v58, v34, 0
	s_waitcnt lgkmcnt(2)
	v_mov_b32_e32 v66, v61
	s_waitcnt lgkmcnt(1)
	v_mov_b32_e32 v67, v62
	v_fmac_f32_e32 v5, v36, v59
	v_pk_mul_f32 v[58:59], v[40:41], v[66:67]
	v_fmac_f32_e32 v5, v38, v60
	v_mov_b32_e32 v45, v46
	v_mov_b32_e32 v64, v63
	v_add_f32_e32 v5, v5, v58
	s_waitcnt lgkmcnt(0)
	v_pk_mul_f32 v[62:63], v[44:45], v[64:65]
	v_add_f32_e32 v5, v5, v59
	v_add_f32_e32 v5, v5, v62
	v_add_f32_e32 v5, v5, v63
	s_nop 1
	v_add_f32_dpp v5, v5, v5 quad_perm:[1,0,3,2] row_mask:0xf bank_mask:0xf
	s_nop 1
	v_add_f32_dpp v5, v5, v5 quad_perm:[2,3,0,1] row_mask:0xf bank_mask:0xf
	v_sub_f32_e32 v5, 0, v5
	v_cndmask_b32_e64 v47, v3, v5, s[42:43]
	ds_read2_b32 v[58:59], v9 offset0:96 offset1:100
	ds_read2_b32 v[60:61], v9 offset0:112 offset1:116
	ds_read2_b32 v[62:63], v9 offset0:120 offset1:124
	ds_read2_b32 v[64:65], v9 offset0:104 offset1:108
	v_mov_b32_e32 v43, v44
	s_waitcnt lgkmcnt(3)
	v_fma_f32 v3, v58, v34, 0
	v_fmac_f32_e32 v3, v36, v59
	s_waitcnt lgkmcnt(2)
	v_pk_mul_f32 v[60:61], v[42:43], v[60:61]
	s_waitcnt lgkmcnt(0)
	v_fmac_f32_e32 v3, v38, v64
	v_fmac_f32_e32 v3, v40, v65
	v_add_f32_e32 v3, v3, v60
	v_pk_mul_f32 v[62:63], v[46:47], v[62:63]
	v_add_f32_e32 v3, v3, v61
	v_add_f32_e32 v3, v3, v62
	v_add_f32_e32 v3, v3, v63
	s_nop 1
	v_add_f32_dpp v3, v3, v3 quad_perm:[1,0,3,2] row_mask:0xf bank_mask:0xf
	s_nop 1
	v_add_f32_dpp v3, v3, v3 quad_perm:[2,3,0,1] row_mask:0xf bank_mask:0xf
	v_sub_f32_e32 v3, 0, v3
	v_cndmask_b32_e64 v47, v47, v3, s[46:47]
	ds_read2_b32 v[58:59], v9 offset0:160 offset1:164
	ds_read2_b32 v[60:61], v9 offset0:176 offset1:180
	ds_read2_b32 v[62:63], v9 offset0:184 offset1:188
	ds_read2_b32 v[64:65], v9 offset0:168 offset1:172
	v_mov_b32_e32 v43, v44
	s_waitcnt lgkmcnt(3)
	v_fma_f32 v3, v58, v34, 0
	v_fmac_f32_e32 v3, v36, v59
	s_waitcnt lgkmcnt(2)
	v_pk_mul_f32 v[60:61], v[42:43], v[60:61]
	s_waitcnt lgkmcnt(0)
	v_fmac_f32_e32 v3, v38, v64
	v_fmac_f32_e32 v3, v40, v65
	v_add_f32_e32 v3, v3, v60
	v_pk_mul_f32 v[62:63], v[46:47], v[62:63]
	v_add_f32_e32 v3, v3, v61
	v_add_f32_e32 v3, v3, v62
	v_add_f32_e32 v3, v3, v63
	s_nop 1
	v_add_f32_dpp v3, v3, v3 quad_perm:[1,0,3,2] row_mask:0xf bank_mask:0xf
	s_nop 1
	v_add_f32_dpp v3, v3, v3 quad_perm:[2,3,0,1] row_mask:0xf bank_mask:0xf
	v_sub_f32_e32 v3, 0, v3
	v_cndmask_b32_e64 v47, v47, v3, s[44:45]
	ds_read2_b32 v[58:59], v9 offset0:224 offset1:228
	ds_read2_b32 v[60:61], v9 offset0:232 offset1:236
	ds_read2_b32 v[62:63], v9 offset0:240 offset1:244
	ds_read2_b32 v[64:65], v9 offset0:248 offset1:252
	v_mov_b32_e32 v35, v36
	s_waitcnt lgkmcnt(3)
	v_pk_mul_f32 v[58:59], v[58:59], v[34:35]
	v_mov_b32_e32 v39, v40
	v_add_f32_e32 v3, 0, v58
	s_waitcnt lgkmcnt(2)
	v_pk_mul_f32 v[60:61], v[38:39], v[60:61]
	v_add_f32_e32 v3, v3, v59
	v_mov_b32_e32 v43, v44
	v_add_f32_e32 v3, v3, v60
	s_waitcnt lgkmcnt(1)
	v_pk_mul_f32 v[62:63], v[42:43], v[62:63]
	v_add_f32_e32 v3, v3, v61
	v_add_f32_e32 v3, v3, v62
	v_add_f32_e32 v3, v3, v63
	s_waitcnt lgkmcnt(0)
	v_pk_mul_f32 v[58:59], v[46:47], v[64:65]
	s_nop 0
	v_add_f32_e32 v3, v3, v58
	v_add_f32_e32 v3, v3, v59
	s_nop 1
	v_add_f32_dpp v3, v3, v3 quad_perm:[1,0,3,2] row_mask:0xf bank_mask:0xf
	s_nop 1
	v_add_f32_dpp v3, v3, v3 quad_perm:[2,3,0,1] row_mask:0xf bank_mask:0xf
	v_sub_f32_e32 v3, 0, v3
	v_cndmask_b32_e32 v3, v47, v3, vcc

; #define LAS __attribute__((address_space(3)))
; template <int W> __device__ __forceinline__ void dn_solve(const LAS float* Mf, float (&t)[16], int lane) {
;     const int j = 16 * W + (lane >> 2), q = lane & 3;
; #pragma unroll
;     for (int s = 0; s < 16; ++s) t[s] = 0.f;
; #pragma unroll
;     for (int i = 16 * W; i < 64; ++i) {
;         float acc = 0.f;
; #pragma unroll
;         for (int s = 4 * W; s <= (i - 1) / 4 && i > 16 * W; ++s) acc += Mf[i * 64 + 4 * s + q] * t[s];
;         acc += __shfl_xor(acc, 1); acc += __shfl_xor(acc, 2);
;         const float val = (i == j ? 1.f : 0.f) - acc;
;         if (q == (i & 3)) t[i >> 2] = val;
;         asm volatile("" : "+v"(t[0]), "+v"(t[1]), "+v"(t[2]), "+v"(t[3]), "+v"(t[4]), "+v"(t[5]), "+v"(t[6]), "+v"(t[7]), "+v"(t[8]), "+v"(t[9]), "+v"(t[10]), "+v"(t[11]), "+v"(t[12]), "+v"(t[13]), "+v"(t[14]), "+v"(t[15]));
;     }
; }
.LBB0_114:
	s_andn2_b64 vcc, exec, s[0:1]
	s_cbranch_vccnz .LBB0_120
	s_mov_b64 s[86:87], -1
	s_cmp_eq_u32 s80, 1
	v_cmp_eq_u32_e64 s[46:47], 1, v52
	v_cmp_eq_u32_e64 s[76:77], 1, v53
	v_cmp_eq_u32_e64 s[44:45], 2, v52
	v_cmp_eq_u32_e64 s[74:75], 2, v53
	v_cmp_eq_u32_e32 vcc, 3, v52
	v_cmp_eq_u32_e64 s[72:73], 3, v53
	v_cmp_eq_u32_e64 s[70:71], 4, v53
	v_cmp_eq_u32_e64 s[68:69], 5, v53
	v_cmp_eq_u32_e64 s[66:67], 6, v53
	v_cmp_eq_u32_e64 s[64:65], 7, v53
	v_cmp_eq_u32_e64 s[62:63], 8, v53
	v_cmp_eq_u32_e64 s[60:61], 9, v53
	v_cmp_eq_u32_e64 s[58:59], 10, v53
	v_cmp_eq_u32_e64 s[56:57], 11, v53
	v_cmp_eq_u32_e64 s[54:55], 12, v53
	v_cmp_eq_u32_e64 s[52:53], 13, v53
	v_cmp_eq_u32_e64 s[0:1], 14, v53
	v_cmp_eq_u32_e64 s[48:49], 15, v53
	s_cbranch_scc1 .LBB0_117
	v_mov_b32_e32 v3, v1
	v_mov_b32_e32 v6, v1
	v_mov_b32_e32 v7, v1
	v_mov_b32_e32 v9, v1
	v_mov_b32_e32 v11, v1
	v_mov_b32_e32 v13, v1
	v_mov_b32_e32 v15, v1
	v_mov_b32_e32 v17, v1
	v_mov_b32_e32 v35, v1
	s_waitcnt lgkmcnt(14)
	v_mov_b32_e32 v37, v1
	v_mov_b32_e32 v39, v1
	v_mov_b32_e32 v41, v1
	v_mov_b32_e32 v43, v1
	v_mov_b32_e32 v45, v1
	v_mov_b32_e32 v47, v1
	v_mov_b32_e32 v2, v57
	ds_read_b32 v4, v56 offset:17664
	v_cndmask_b32_e64 v8, 0, 1.0, s[76:77]
	v_add_u32_e32 v10, 0x4800, v56
	v_add_u32_e32 v12, 0x5800, v56
	v_add_u32_e32 v14, 0x5c00, v56
	s_waitcnt lgkmcnt(0)
	v_fma_f32 v4, v4, v2, 0
	s_mov_b64 s[86:87], 0
	s_waitcnt lgkmcnt(0)
	s_nop 1
	v_add_f32_dpp v4, v4, v4 quad_perm:[1,0,3,2] row_mask:0xf bank_mask:0xf
	s_nop 1
	v_add_f32_dpp v4, v4, v4 quad_perm:[2,3,0,1] row_mask:0xf bank_mask:0xf
	v_sub_f32_e32 v4, v8, v4
	v_cndmask_b32_e64 v2, v2, v4, s[46:47]
	ds_read_b32 v4, v56 offset:17920
	v_cndmask_b32_e64 v8, 0, 1.0, s[74:75]
	s_waitcnt lgkmcnt(0)
	v_fma_f32 v4, v4, v2, 0
	s_nop 1
	v_add_f32_dpp v4, v4, v4 quad_perm:[1,0,3,2] row_mask:0xf bank_mask:0xf
	s_nop 1
	v_add_f32_dpp v4, v4, v4 quad_perm:[2,3,0,1] row_mask:0xf bank_mask:0xf
	v_sub_f32_e32 v4, v8, v4
	v_cndmask_b32_e64 v2, v2, v4, s[44:45]
	ds_read_b32 v4, v56 offset:18176
	v_cndmask_b32_e64 v8, 0, 1.0, s[72:73]
	s_waitcnt lgkmcnt(0)
	v_fma_f32 v4, v4, v2, 0
	s_nop 1
	v_add_f32_dpp v4, v4, v4 quad_perm:[1,0,3,2] row_mask:0xf bank_mask:0xf
	s_nop 1
	v_add_f32_dpp v4, v4, v4 quad_perm:[2,3,0,1] row_mask:0xf bank_mask:0xf
	v_sub_f32_e32 v4, v8, v4
	v_cndmask_b32_e32 v2, v2, v4, vcc
	ds_read_b32 v4, v56 offset:18432
	v_cndmask_b32_e64 v8, 0, 1.0, s[70:71]
	s_waitcnt lgkmcnt(0)
	v_fma_f32 v4, v4, v2, 0
	s_nop 1
	v_add_f32_dpp v4, v4, v4 quad_perm:[1,0,3,2] row_mask:0xf bank_mask:0xf
	s_waitcnt lgkmcnt(0)
	s_nop 1
	v_add_f32_dpp v4, v4, v4 quad_perm:[2,3,0,1] row_mask:0xf bank_mask:0xf
	v_sub_f32_e32 v4, v8, v4
	v_cndmask_b32_e64 v3, v3, v4, s[42:43]
	ds_read2_b32 v[4:5], v10 offset0:64 offset1:68
	v_cndmask_b32_e64 v8, 0, 1.0, s[68:69]
	s_waitcnt lgkmcnt(0)
	v_pk_mul_f32 v[4:5], v[4:5], v[2:3]
	s_nop 0
	v_add_f32_e32 v4, 0, v4
	v_add_f32_e32 v4, v4, v5
	s_nop 1
	v_add_f32_dpp v4, v4, v4 quad_perm:[1,0,3,2] row_mask:0xf bank_mask:0xf
	s_waitcnt lgkmcnt(0)
	s_nop 1
	v_add_f32_dpp v4, v4, v4 quad_perm:[2,3,0,1] row_mask:0xf bank_mask:0xf
	v_sub_f32_e32 v4, v8, v4
	v_cndmask_b32_e64 v3, v3, v4, s[46:47]
	ds_read2_b32 v[4:5], v10 offset0:128 offset1:132
	v_cndmask_b32_e64 v8, 0, 1.0, s[66:67]
	s_waitcnt lgkmcnt(0)
	v_pk_mul_f32 v[4:5], v[4:5], v[2:3]
	s_nop 0
	v_add_f32_e32 v4, 0, v4
	v_add_f32_e32 v4, v4, v5
	s_nop 1
	v_add_f32_dpp v4, v4, v4 quad_perm:[1,0,3,2] row_mask:0xf bank_mask:0xf
	s_waitcnt lgkmcnt(0)
	s_nop 1
	v_add_f32_dpp v4, v4, v4 quad_perm:[2,3,0,1] row_mask:0xf bank_mask:0xf
	v_sub_f32_e32 v4, v8, v4
	v_cndmask_b32_e64 v3, v3, v4, s[44:45]
	ds_read2_b32 v[4:5], v10 offset0:192 offset1:196
	v_cndmask_b32_e64 v8, 0, 1.0, s[64:65]
	v_add_u32_e32 v10, 0x4c00, v56
	s_waitcnt lgkmcnt(0)
	v_pk_mul_f32 v[4:5], v[4:5], v[2:3]
	s_nop 0
	v_add_f32_e32 v4, 0, v4
	v_add_f32_e32 v4, v4, v5
	s_nop 1
	v_add_f32_dpp v4, v4, v4 quad_perm:[1,0,3,2] row_mask:0xf bank_mask:0xf
	s_nop 1
	v_add_f32_dpp v4, v4, v4 quad_perm:[2,3,0,1] row_mask:0xf bank_mask:0xf
	v_sub_f32_e32 v4, v8, v4
	v_cndmask_b32_e32 v4, v3, v4, vcc
	ds_read2_b32 v[58:59], v10 offset1:4
	v_mov_b32_e32 v3, v4
	v_cndmask_b32_e64 v8, 0, 1.0, s[62:63]
	s_waitcnt lgkmcnt(0)
	v_pk_mul_f32 v[58:59], v[58:59], v[2:3]
	s_nop 0
	v_add_f32_e32 v3, 0, v58
	v_add_f32_e32 v3, v3, v59
	s_nop 1
	v_add_f32_dpp v3, v3, v3 quad_perm:[1,0,3,2] row_mask:0xf bank_mask:0xf
	s_nop 1
	v_add_f32_dpp v3, v3, v3 quad_perm:[2,3,0,1] row_mask:0xf bank_mask:0xf
	v_sub_f32_e32 v3, v8, v3
	v_cndmask_b32_e64 v5, v6, v3, s[42:43]
	ds_read2_b32 v[58:59], v10 offset0:64 offset1:68
	ds_read_b32 v61, v56 offset:19744
	v_cndmask_b32_e64 v8, 0, 1.0, s[60:61]
	s_waitcnt lgkmcnt(1)
	v_mov_b32_e32 v60, v59
	v_fma_f32 v3, v58, v2, 0
	s_waitcnt lgkmcnt(0)
	v_pk_mul_f32 v[58:59], v[4:5], v[60:61]
	s_nop 0
	v_add_f32_e32 v3, v3, v58
	v_add_f32_e32 v3, v3, v59
	s_nop 1
	v_add_f32_dpp v3, v3, v3 quad_perm:[1,0,3,2] row_mask:0xf bank_mask:0xf
	s_nop 1
	v_add_f32_dpp v3, v3, v3 quad_perm:[2,3,0,1] row_mask:0xf bank_mask:0xf
	v_sub_f32_e32 v3, v8, v3
	v_cndmask_b32_e64 v5, v5, v3, s[46:47]
	ds_read2_b32 v[58:59], v10 offset0:128 offset1:132
	ds_read_b32 v61, v56 offset:20000
	v_cndmask_b32_e64 v8, 0, 1.0, s[58:59]
	s_waitcnt lgkmcnt(1)
	v_mov_b32_e32 v60, v59
	v_fma_f32 v3, v58, v2, 0
	s_waitcnt lgkmcnt(0)
	v_pk_mul_f32 v[58:59], v[4:5], v[60:61]
	s_nop 0
	v_add_f32_e32 v3, v3, v58
	v_add_f32_e32 v3, v3, v59
	s_nop 1
	v_add_f32_dpp v3, v3, v3 quad_perm:[1,0,3,2] row_mask:0xf bank_mask:0xf
	s_nop 1
	v_add_f32_dpp v3, v3, v3 quad_perm:[2,3,0,1] row_mask:0xf bank_mask:0xf
	v_sub_f32_e32 v3, v8, v3
	v_cndmask_b32_e64 v5, v5, v3, s[44:45]
	ds_read2_b32 v[58:59], v10 offset0:192 offset1:196
	ds_read_b32 v61, v56 offset:20256
	v_cndmask_b32_e64 v8, 0, 1.0, s[56:57]
	v_add_u32_e32 v10, 0x5000, v56
	s_waitcnt lgkmcnt(1)
; #define LAS __attribute__((address_space(3)))
; template <int W> __device__ __forceinline__ void dn_solve(const LAS float* Mf, float (&t)[16], int lane) {
;     const int j = 16 * W + (lane >> 2), q = lane & 3;
; #pragma unroll
;     for (int s = 0; s < 16; ++s) t[s] = 0.f;
; #pragma unroll
;     for (int i = 16 * W; i < 64; ++i) {
;         float acc = 0.f;
; #pragma unroll
;         for (int s = 4 * W; s <= (i - 1) / 4 && i > 16 * W; ++s) acc += Mf[i * 64 + 4 * s + q] * t[s];
;         acc += __shfl_xor(acc, 1); acc += __shfl_xor(acc, 2);
;         const float val = (i == j ? 1.f : 0.f) - acc;
;         if (q == (i & 3)) t[i >> 2] = val;
;         asm volatile("" : "+v"(t[0]), "+v"(t[1]), "+v"(t[2]), "+v"(t[3]), "+v"(t[4]), "+v"(t[5]), "+v"(t[6]), "+v"(t[7]), "+v"(t[8]), "+v"(t[9]), "+v"(t[10]), "+v"(t[11]), "+v"(t[12]), "+v"(t[13]), "+v"(t[14]), "+v"(t[15]));
;     }
; }
	v_mov_b32_e32 v60, v59
	v_fma_f32 v3, v58, v2, 0
	s_waitcnt lgkmcnt(0)
	v_pk_mul_f32 v[58:59], v[4:5], v[60:61]
	s_nop 0
	v_add_f32_e32 v3, v3, v58
	v_add_f32_e32 v3, v3, v59
	s_nop 1
	v_add_f32_dpp v3, v3, v3 quad_perm:[1,0,3,2] row_mask:0xf bank_mask:0xf
	s_nop 1
	v_add_f32_dpp v3, v3, v3 quad_perm:[2,3,0,1] row_mask:0xf bank_mask:0xf
	v_sub_f32_e32 v3, v8, v3
	v_cndmask_b32_e32 v6, v5, v3, vcc
	ds_read2_b32 v[58:59], v10 offset1:4
	ds_read_b32 v61, v56 offset:20512
	v_mov_b32_e32 v5, v6
	v_cndmask_b32_e64 v8, 0, 1.0, s[54:55]
	s_waitcnt lgkmcnt(1)
	v_mov_b32_e32 v60, v59
	v_fma_f32 v3, v58, v2, 0
	s_waitcnt lgkmcnt(0)
	v_pk_mul_f32 v[58:59], v[4:5], v[60:61]
	s_nop 0
	v_add_f32_e32 v3, v3, v58
	v_add_f32_e32 v3, v3, v59
	s_nop 1
	v_add_f32_dpp v3, v3, v3 quad_perm:[1,0,3,2] row_mask:0xf bank_mask:0xf
	s_nop 1
	v_add_f32_dpp v3, v3, v3 quad_perm:[2,3,0,1] row_mask:0xf bank_mask:0xf
	v_sub_f32_e32 v3, v8, v3
	v_cndmask_b32_e64 v7, v7, v3, s[42:43]
	ds_read2_b32 v[58:59], v10 offset0:64 offset1:68
	ds_read2_b32 v[60:61], v10 offset0:72 offset1:76
	v_mov_b32_e32 v3, v4
	v_cndmask_b32_e64 v8, 0, 1.0, s[52:53]
	s_waitcnt lgkmcnt(1)
	v_pk_mul_f32 v[58:59], v[58:59], v[2:3]
	s_nop 0
	v_add_f32_e32 v3, 0, v58
	s_waitcnt lgkmcnt(0)
	v_pk_mul_f32 v[60:61], v[6:7], v[60:61]
	v_add_f32_e32 v3, v3, v59
	v_add_f32_e32 v3, v3, v60
	v_add_f32_e32 v3, v3, v61
	s_nop 1
	v_add_f32_dpp v3, v3, v3 quad_perm:[1,0,3,2] row_mask:0xf bank_mask:0xf
	s_nop 1
	v_add_f32_dpp v3, v3, v3 quad_perm:[2,3,0,1] row_mask:0xf bank_mask:0xf
	v_sub_f32_e32 v3, v8, v3
	v_cndmask_b32_e64 v7, v7, v3, s[46:47]
	ds_read2_b32 v[58:59], v10 offset0:128 offset1:132
	ds_read2_b32 v[60:61], v10 offset0:136 offset1:140
	v_mov_b32_e32 v3, v4
	v_cndmask_b32_e64 v8, 0, 1.0, s[0:1]
	s_waitcnt lgkmcnt(1)
	v_pk_mul_f32 v[58:59], v[58:59], v[2:3]
	s_nop 0
	v_add_f32_e32 v3, 0, v58
	s_waitcnt lgkmcnt(0)
	v_pk_mul_f32 v[60:61], v[6:7], v[60:61]
	v_add_f32_e32 v3, v3, v59
	v_add_f32_e32 v3, v3, v60
	v_add_f32_e32 v3, v3, v61
	s_nop 1
	v_add_f32_dpp v3, v3, v3 quad_perm:[1,0,3,2] row_mask:0xf bank_mask:0xf
	s_nop 1
	v_add_f32_dpp v3, v3, v3 quad_perm:[2,3,0,1] row_mask:0xf bank_mask:0xf
	v_sub_f32_e32 v3, v8, v3
	v_cndmask_b32_e64 v7, v7, v3, s[44:45]
	ds_read2_b32 v[58:59], v10 offset0:192 offset1:196
	ds_read2_b32 v[60:61], v10 offset0:200 offset1:204
	v_mov_b32_e32 v3, v4
	v_cndmask_b32_e64 v8, 0, 1.0, s[48:49]
	v_add_u32_e32 v10, 0x5400, v56
	s_waitcnt lgkmcnt(1)
	v_pk_mul_f32 v[58:59], v[58:59], v[2:3]
	s_waitcnt lgkmcnt(0)
	v_pk_mul_f32 v[60:61], v[6:7], v[60:61]
	v_add_f32_e32 v3, 0, v58
	v_add_f32_e32 v3, v3, v59
	v_add_f32_e32 v3, v3, v60
	v_add_f32_e32 v3, v3, v61
	s_nop 1
	v_add_f32_dpp v3, v3, v3 quad_perm:[1,0,3,2] row_mask:0xf bank_mask:0xf
	s_nop 1
	v_add_f32_dpp v3, v3, v3 quad_perm:[2,3,0,1] row_mask:0xf bank_mask:0xf
	v_sub_f32_e32 v3, v8, v3
	v_cndmask_b32_e32 v8, v7, v3, vcc
	ds_read2_b32 v[58:59], v10 offset1:4
	ds_read2_b32 v[60:61], v10 offset0:8 offset1:12
	v_mov_b32_e32 v3, v4
	v_mov_b32_e32 v7, v8
	s_waitcnt lgkmcnt(1)
	v_pk_mul_f32 v[58:59], v[58:59], v[2:3]
	s_nop 0
	v_add_f32_e32 v3, 0, v58
	s_waitcnt lgkmcnt(0)
	v_pk_mul_f32 v[60:61], v[6:7], v[60:61]
	v_add_f32_e32 v3, v3, v59
	v_add_f32_e32 v3, v3, v60
	v_add_f32_e32 v3, v3, v61
	s_nop 1
	v_add_f32_dpp v3, v3, v3 quad_perm:[1,0,3,2] row_mask:0xf bank_mask:0xf
	s_nop 1
	v_add_f32_dpp v3, v3, v3 quad_perm:[2,3,0,1] row_mask:0xf bank_mask:0xf
	v_sub_f32_e32 v3, 0, v3
	v_cndmask_b32_e64 v9, v9, v3, s[42:43]
	ds_read2_b32 v[58:59], v10 offset0:64 offset1:68
	ds_read2_b32 v[60:61], v10 offset0:72 offset1:76
	ds_read_b32 v63, v56 offset:21824
	v_mov_b32_e32 v5, v6
	s_waitcnt lgkmcnt(2)
	v_fma_f32 v3, v58, v2, 0
	v_mov_b32_e32 v58, v59
	s_waitcnt lgkmcnt(1)
	v_mov_b32_e32 v59, v60
	v_pk_mul_f32 v[58:59], v[4:5], v[58:59]
	v_mov_b32_e32 v62, v61
	v_add_f32_e32 v3, v3, v58
	s_waitcnt lgkmcnt(0)
	v_pk_mul_f32 v[60:61], v[8:9], v[62:63]
	v_add_f32_e32 v3, v3, v59
	v_add_f32_e32 v3, v3, v60
	v_add_f32_e32 v3, v3, v61
	s_nop 1
	v_add_f32_dpp v3, v3, v3 quad_perm:[1,0,3,2] row_mask:0xf bank_mask:0xf
	s_nop 1
	v_add_f32_dpp v3, v3, v3 quad_perm:[2,3,0,1] row_mask:0xf bank_mask:0xf
	v_sub_f32_e32 v3, 0, v3
	v_cndmask_b32_e64 v9, v9, v3, s[46:47]
	ds_read2_b32 v[58:59], v10 offset0:128 offset1:132
	ds_read2_b32 v[60:61], v10 offset0:136 offset1:140
	ds_read_b32 v63, v56 offset:22080
	v_mov_b32_e32 v5, v6
	s_waitcnt lgkmcnt(2)
	v_fma_f32 v3, v58, v2, 0
	v_mov_b32_e32 v58, v59
	s_waitcnt lgkmcnt(1)
	v_mov_b32_e32 v59, v60
	v_pk_mul_f32 v[58:59], v[4:5], v[58:59]
	v_mov_b32_e32 v62, v61
	v_add_f32_e32 v3, v3, v58
	s_waitcnt lgkmcnt(0)
	v_pk_mul_f32 v[60:61], v[8:9], v[62:63]
	v_add_f32_e32 v3, v3, v59
	v_add_f32_e32 v3, v3, v60
	v_add_f32_e32 v3, v3, v61
	s_nop 1
	v_add_f32_dpp v3, v3, v3 quad_perm:[1,0,3,2] row_mask:0xf bank_mask:0xf
	s_nop 1
	v_add_f32_dpp v3, v3, v3 quad_perm:[2,3,0,1] row_mask:0xf bank_mask:0xf
	v_sub_f32_e32 v3, 0, v3
	v_cndmask_b32_e64 v9, v9, v3, s[44:45]
	ds_read2_b32 v[58:59], v10 offset0:192 offset1:196
	ds_read2_b32 v[60:61], v10 offset0:200 offset1:204
	ds_read_b32 v63, v56 offset:22336
	v_mov_b32_e32 v5, v6
	s_waitcnt lgkmcnt(2)
	v_fma_f32 v3, v58, v2, 0
	v_mov_b32_e32 v58, v59
	s_waitcnt lgkmcnt(1)
	v_mov_b32_e32 v59, v60
	v_pk_mul_f32 v[58:59], v[4:5], v[58:59]
	v_mov_b32_e32 v62, v61
	v_add_f32_e32 v3, v3, v58
	s_waitcnt lgkmcnt(0)
	v_pk_mul_f32 v[60:61], v[8:9], v[62:63]
	v_add_f32_e32 v3, v3, v59
	v_add_f32_e32 v3, v3, v60
	v_add_f32_e32 v3, v3, v61
	s_nop 1
	v_add_f32_dpp v3, v3, v3 quad_perm:[1,0,3,2] row_mask:0xf bank_mask:0xf
	s_nop 1
	v_add_f32_dpp v3, v3, v3 quad_perm:[2,3,0,1] row_mask:0xf bank_mask:0xf
	v_sub_f32_e32 v3, 0, v3
	v_cndmask_b32_e32 v10, v9, v3, vcc
	ds_read2_b32 v[58:59], v12 offset1:4
	ds_read2_b32 v[60:61], v12 offset0:8 offset1:12
	ds_read_b32 v63, v56 offset:22592
	v_mov_b32_e32 v5, v6
	v_mov_b32_e32 v9, v10
	s_waitcnt lgkmcnt(2)
; #define LAS __attribute__((address_space(3)))
; template <int W> __device__ __forceinline__ void dn_solve(const LAS float* Mf, float (&t)[16], int lane) {
;     const int j = 16 * W + (lane >> 2), q = lane & 3;
; #pragma unroll
;     for (int s = 0; s < 16; ++s) t[s] = 0.f;
; #pragma unroll
;     for (int i = 16 * W; i < 64; ++i) {
;         float acc = 0.f;
; #pragma unroll
;         for (int s = 4 * W; s <= (i - 1) / 4 && i > 16 * W; ++s) acc += Mf[i * 64 + 4 * s + q] * t[s];
;         acc += __shfl_xor(acc, 1); acc += __shfl_xor(acc, 2);
;         const float val = (i == j ? 1.f : 0.f) - acc;
;         if (q == (i & 3)) t[i >> 2] = val;
;         asm volatile("" : "+v"(t[0]), "+v"(t[1]), "+v"(t[2]), "+v"(t[3]), "+v"(t[4]), "+v"(t[5]), "+v"(t[6]), "+v"(t[7]), "+v"(t[8]), "+v"(t[9]), "+v"(t[10]), "+v"(t[11]), "+v"(t[12]), "+v"(t[13]), "+v"(t[14]), "+v"(t[15]));
;     }
; }
	v_fma_f32 v3, v58, v2, 0
	v_mov_b32_e32 v58, v59
	s_waitcnt lgkmcnt(1)
	v_mov_b32_e32 v59, v60
	v_pk_mul_f32 v[58:59], v[4:5], v[58:59]
	v_mov_b32_e32 v62, v61
	v_add_f32_e32 v3, v3, v58
	s_waitcnt lgkmcnt(0)
	v_pk_mul_f32 v[60:61], v[8:9], v[62:63]
	v_add_f32_e32 v3, v3, v59
	v_add_f32_e32 v3, v3, v60
	v_add_f32_e32 v3, v3, v61
	s_nop 1
	v_add_f32_dpp v3, v3, v3 quad_perm:[1,0,3,2] row_mask:0xf bank_mask:0xf
	s_nop 1
	v_add_f32_dpp v3, v3, v3 quad_perm:[2,3,0,1] row_mask:0xf bank_mask:0xf
	v_sub_f32_e32 v3, 0, v3
	v_cndmask_b32_e64 v11, v11, v3, s[42:43]
	ds_read2_b32 v[58:59], v12 offset0:64 offset1:68
	ds_read2_b32 v[60:61], v12 offset0:72 offset1:76
	ds_read2_b32 v[62:63], v12 offset0:80 offset1:84
	v_mov_b32_e32 v7, v8
	s_waitcnt lgkmcnt(2)
	v_fma_f32 v3, v58, v2, 0
	s_waitcnt lgkmcnt(1)
	v_pk_mul_f32 v[60:61], v[6:7], v[60:61]
	v_fmac_f32_e32 v3, v4, v59
	v_add_f32_e32 v3, v3, v60
	s_waitcnt lgkmcnt(0)
	v_pk_mul_f32 v[62:63], v[10:11], v[62:63]
	v_add_f32_e32 v3, v3, v61
	v_add_f32_e32 v3, v3, v62
	v_add_f32_e32 v3, v3, v63
	s_nop 1
	v_add_f32_dpp v3, v3, v3 quad_perm:[1,0,3,2] row_mask:0xf bank_mask:0xf
	s_nop 1
	v_add_f32_dpp v3, v3, v3 quad_perm:[2,3,0,1] row_mask:0xf bank_mask:0xf
	v_sub_f32_e32 v3, 0, v3
	v_cndmask_b32_e64 v11, v11, v3, s[46:47]
	ds_read2_b32 v[58:59], v12 offset0:128 offset1:132
	ds_read2_b32 v[60:61], v12 offset0:136 offset1:140
	ds_read2_b32 v[62:63], v12 offset0:144 offset1:148
	v_mov_b32_e32 v7, v8
	s_waitcnt lgkmcnt(2)
	v_fma_f32 v3, v58, v2, 0
	s_waitcnt lgkmcnt(1)
	v_pk_mul_f32 v[60:61], v[6:7], v[60:61]
	v_fmac_f32_e32 v3, v4, v59
	v_add_f32_e32 v3, v3, v60
	s_waitcnt lgkmcnt(0)
	v_pk_mul_f32 v[62:63], v[10:11], v[62:63]
	v_add_f32_e32 v3, v3, v61
	v_add_f32_e32 v3, v3, v62
	v_add_f32_e32 v3, v3, v63
	s_nop 1
	v_add_f32_dpp v3, v3, v3 quad_perm:[1,0,3,2] row_mask:0xf bank_mask:0xf
	s_nop 1
	v_add_f32_dpp v3, v3, v3 quad_perm:[2,3,0,1] row_mask:0xf bank_mask:0xf
	v_sub_f32_e32 v3, 0, v3
	v_cndmask_b32_e64 v11, v11, v3, s[44:45]
	ds_read2_b32 v[58:59], v12 offset0:192 offset1:196
	ds_read2_b32 v[60:61], v12 offset0:200 offset1:204
	ds_read2_b32 v[62:63], v12 offset0:208 offset1:212
	v_mov_b32_e32 v7, v8
	s_waitcnt lgkmcnt(2)
	v_fma_f32 v3, v58, v2, 0
	s_waitcnt lgkmcnt(1)
	v_pk_mul_f32 v[60:61], v[6:7], v[60:61]
	v_fmac_f32_e32 v3, v4, v59
	v_add_f32_e32 v3, v3, v60
	s_waitcnt lgkmcnt(0)
	v_pk_mul_f32 v[62:63], v[10:11], v[62:63]
	v_add_f32_e32 v3, v3, v61
	v_add_f32_e32 v3, v3, v62
	v_add_f32_e32 v3, v3, v63
	s_nop 1
	v_add_f32_dpp v3, v3, v3 quad_perm:[1,0,3,2] row_mask:0xf bank_mask:0xf
	s_nop 1
	v_add_f32_dpp v3, v3, v3 quad_perm:[2,3,0,1] row_mask:0xf bank_mask:0xf
	v_sub_f32_e32 v3, 0, v3
	v_cndmask_b32_e32 v12, v11, v3, vcc
	ds_read2_b32 v[58:59], v14 offset1:4
	ds_read2_b32 v[60:61], v14 offset0:8 offset1:12
	ds_read2_b32 v[62:63], v14 offset0:16 offset1:20
	v_mov_b32_e32 v7, v8
	v_mov_b32_e32 v11, v12
	s_waitcnt lgkmcnt(2)
	v_fma_f32 v3, v58, v2, 0
	s_waitcnt lgkmcnt(1)
	v_pk_mul_f32 v[60:61], v[6:7], v[60:61]
	v_fmac_f32_e32 v3, v4, v59
	v_add_f32_e32 v3, v3, v60
	s_waitcnt lgkmcnt(0)
	v_pk_mul_f32 v[62:63], v[10:11], v[62:63]
	v_add_f32_e32 v3, v3, v61
	v_add_f32_e32 v3, v3, v62
	v_add_f32_e32 v3, v3, v63
	v_add_u32_e32 v7, 0x6000, v56
	s_waitcnt lgkmcnt(0)
	s_nop 1
	v_add_f32_dpp v3, v3, v3 quad_perm:[1,0,3,2] row_mask:0xf bank_mask:0xf
	s_nop 1
	v_add_f32_dpp v3, v3, v3 quad_perm:[2,3,0,1] row_mask:0xf bank_mask:0xf
	v_sub_f32_e32 v3, 0, v3
	v_cndmask_b32_e64 v13, v13, v3, s[42:43]
	ds_read2_b32 v[58:59], v14 offset0:64 offset1:68
	ds_read2_b32 v[60:61], v14 offset0:72 offset1:76
	ds_read2_b32 v[62:63], v14 offset0:80 offset1:84
	ds_read_b32 v65, v56 offset:23904
	v_mov_b32_e32 v9, v10
	s_waitcnt lgkmcnt(3)
	v_fma_f32 v3, v58, v2, 0
	s_waitcnt lgkmcnt(2)
	v_mov_b32_e32 v66, v61
	s_waitcnt lgkmcnt(1)
	v_mov_b32_e32 v67, v62
	v_fmac_f32_e32 v3, v4, v59
	v_pk_mul_f32 v[58:59], v[8:9], v[66:67]
	v_fmac_f32_e32 v3, v6, v60
	v_mov_b32_e32 v64, v63
	v_add_f32_e32 v3, v3, v58
	s_waitcnt lgkmcnt(0)
	v_pk_mul_f32 v[62:63], v[12:13], v[64:65]
	v_add_f32_e32 v3, v3, v59
	v_add_f32_e32 v3, v3, v62
	v_add_f32_e32 v3, v3, v63
	s_nop 1
	v_add_f32_dpp v3, v3, v3 quad_perm:[1,0,3,2] row_mask:0xf bank_mask:0xf
	s_nop 1
	v_add_f32_dpp v3, v3, v3 quad_perm:[2,3,0,1] row_mask:0xf bank_mask:0xf
	v_sub_f32_e32 v3, 0, v3
	v_cndmask_b32_e64 v13, v13, v3, s[46:47]
	ds_read2_b32 v[58:59], v14 offset0:128 offset1:132
	ds_read2_b32 v[60:61], v14 offset0:136 offset1:140
	ds_read2_b32 v[62:63], v14 offset0:144 offset1:148
	ds_read_b32 v65, v56 offset:24160
	v_mov_b32_e32 v9, v10
	s_waitcnt lgkmcnt(3)
	v_fma_f32 v3, v58, v2, 0
	s_waitcnt lgkmcnt(2)
	v_mov_b32_e32 v66, v61
	s_waitcnt lgkmcnt(1)
	v_mov_b32_e32 v67, v62
	v_fmac_f32_e32 v3, v4, v59
	v_pk_mul_f32 v[58:59], v[8:9], v[66:67]
	v_fmac_f32_e32 v3, v6, v60
	v_mov_b32_e32 v64, v63
	v_add_f32_e32 v3, v3, v58
	s_waitcnt lgkmcnt(0)
	v_pk_mul_f32 v[62:63], v[12:13], v[64:65]
	v_add_f32_e32 v3, v3, v59
	v_add_f32_e32 v3, v3, v62
	v_add_f32_e32 v3, v3, v63
	s_nop 1
	v_add_f32_dpp v3, v3, v3 quad_perm:[1,0,3,2] row_mask:0xf bank_mask:0xf
	s_nop 1
	v_add_f32_dpp v3, v3, v3 quad_perm:[2,3,0,1] row_mask:0xf bank_mask:0xf
	v_sub_f32_e32 v3, 0, v3
	v_cndmask_b32_e64 v13, v13, v3, s[44:45]
	ds_read2_b32 v[58:59], v14 offset0:192 offset1:196
	ds_read2_b32 v[60:61], v14 offset0:200 offset1:204
	ds_read2_b32 v[62:63], v14 offset0:208 offset1:212
	ds_read_b32 v65, v56 offset:24416
	v_mov_b32_e32 v9, v10
	s_waitcnt lgkmcnt(3)
	v_fma_f32 v3, v58, v2, 0
	s_waitcnt lgkmcnt(2)
	v_mov_b32_e32 v66, v61
	s_waitcnt lgkmcnt(1)
; #define LAS __attribute__((address_space(3)))
; template <int W> __device__ __forceinline__ void dn_solve(const LAS float* Mf, float (&t)[16], int lane) {
;     const int j = 16 * W + (lane >> 2), q = lane & 3;
; #pragma unroll
;     for (int s = 0; s < 16; ++s) t[s] = 0.f;
; #pragma unroll
;     for (int i = 16 * W; i < 64; ++i) {
;         float acc = 0.f;
; #pragma unroll
;         for (int s = 4 * W; s <= (i - 1) / 4 && i > 16 * W; ++s) acc += Mf[i * 64 + 4 * s + q] * t[s];
;         acc += __shfl_xor(acc, 1); acc += __shfl_xor(acc, 2);
;         const float val = (i == j ? 1.f : 0.f) - acc;
;         if (q == (i & 3)) t[i >> 2] = val;
;         asm volatile("" : "+v"(t[0]), "+v"(t[1]), "+v"(t[2]), "+v"(t[3]), "+v"(t[4]), "+v"(t[5]), "+v"(t[6]), "+v"(t[7]), "+v"(t[8]), "+v"(t[9]), "+v"(t[10]), "+v"(t[11]), "+v"(t[12]), "+v"(t[13]), "+v"(t[14]), "+v"(t[15]));
;     }
; }
	v_mov_b32_e32 v67, v62
	v_fmac_f32_e32 v3, v4, v59
	v_pk_mul_f32 v[58:59], v[8:9], v[66:67]
	v_fmac_f32_e32 v3, v6, v60
	v_mov_b32_e32 v64, v63
	v_add_f32_e32 v3, v3, v58
	s_waitcnt lgkmcnt(0)
	v_pk_mul_f32 v[62:63], v[12:13], v[64:65]
	v_add_f32_e32 v3, v3, v59
	v_add_f32_e32 v3, v3, v62
	v_add_f32_e32 v3, v3, v63
	s_nop 1
	v_add_f32_dpp v3, v3, v3 quad_perm:[1,0,3,2] row_mask:0xf bank_mask:0xf
	s_nop 1
	v_add_f32_dpp v3, v3, v3 quad_perm:[2,3,0,1] row_mask:0xf bank_mask:0xf
	v_sub_f32_e32 v3, 0, v3
	v_cndmask_b32_e32 v14, v13, v3, vcc
	ds_read2_b32 v[58:59], v7 offset1:4
	ds_read2_b32 v[60:61], v7 offset0:8 offset1:12
	ds_read2_b32 v[62:63], v7 offset0:16 offset1:20
	ds_read_b32 v65, v56 offset:24672
	v_mov_b32_e32 v9, v10
	s_waitcnt lgkmcnt(3)
	v_fma_f32 v3, v58, v2, 0
	s_waitcnt lgkmcnt(2)
	v_mov_b32_e32 v66, v61
	s_waitcnt lgkmcnt(1)
	v_mov_b32_e32 v67, v62
	v_fmac_f32_e32 v3, v4, v59
	v_pk_mul_f32 v[58:59], v[8:9], v[66:67]
	v_fmac_f32_e32 v3, v6, v60
	v_mov_b32_e32 v13, v14
	v_mov_b32_e32 v64, v63
	v_add_f32_e32 v3, v3, v58
	s_waitcnt lgkmcnt(0)
	v_pk_mul_f32 v[62:63], v[12:13], v[64:65]
	v_add_f32_e32 v3, v3, v59
	v_add_f32_e32 v3, v3, v62
	v_add_f32_e32 v3, v3, v63
	s_nop 1
	v_add_f32_dpp v3, v3, v3 quad_perm:[1,0,3,2] row_mask:0xf bank_mask:0xf
	s_nop 1
	v_add_f32_dpp v3, v3, v3 quad_perm:[2,3,0,1] row_mask:0xf bank_mask:0xf
	v_sub_f32_e32 v3, 0, v3
	v_cndmask_b32_e64 v15, v15, v3, s[42:43]
	ds_read2_b32 v[58:59], v7 offset0:64 offset1:68
	ds_read2_b32 v[60:61], v7 offset0:80 offset1:84
	ds_read2_b32 v[62:63], v7 offset0:88 offset1:92
	ds_read2_b32 v[64:65], v7 offset0:72 offset1:76
	v_mov_b32_e32 v11, v12
	s_waitcnt lgkmcnt(3)
	v_fma_f32 v3, v58, v2, 0
	v_fmac_f32_e32 v3, v4, v59
	s_waitcnt lgkmcnt(2)
	v_pk_mul_f32 v[60:61], v[10:11], v[60:61]
	s_waitcnt lgkmcnt(0)
	v_fmac_f32_e32 v3, v6, v64
	v_fmac_f32_e32 v3, v8, v65
	v_add_f32_e32 v3, v3, v60
	v_pk_mul_f32 v[62:63], v[14:15], v[62:63]
	v_add_f32_e32 v3, v3, v61
	v_add_f32_e32 v3, v3, v62
	v_add_f32_e32 v3, v3, v63
	s_nop 1
	v_add_f32_dpp v3, v3, v3 quad_perm:[1,0,3,2] row_mask:0xf bank_mask:0xf
	s_nop 1
	v_add_f32_dpp v3, v3, v3 quad_perm:[2,3,0,1] row_mask:0xf bank_mask:0xf
	v_sub_f32_e32 v3, 0, v3
	v_cndmask_b32_e64 v15, v15, v3, s[46:47]
	ds_read2_b32 v[58:59], v7 offset0:128 offset1:132
	ds_read2_b32 v[60:61], v7 offset0:144 offset1:148
	ds_read2_b32 v[62:63], v7 offset0:152 offset1:156
	ds_read2_b32 v[64:65], v7 offset0:136 offset1:140
	v_mov_b32_e32 v11, v12
	s_waitcnt lgkmcnt(3)
	v_fma_f32 v3, v58, v2, 0
	v_fmac_f32_e32 v3, v4, v59
	s_waitcnt lgkmcnt(2)
	v_pk_mul_f32 v[60:61], v[10:11], v[60:61]
	s_waitcnt lgkmcnt(0)
	v_fmac_f32_e32 v3, v6, v64
	v_fmac_f32_e32 v3, v8, v65
	v_add_f32_e32 v3, v3, v60
	v_pk_mul_f32 v[62:63], v[14:15], v[62:63]
	v_add_f32_e32 v3, v3, v61
	v_add_f32_e32 v3, v3, v62
	v_add_f32_e32 v3, v3, v63
	s_nop 1
	v_add_f32_dpp v3, v3, v3 quad_perm:[1,0,3,2] row_mask:0xf bank_mask:0xf
	s_nop 1
	v_add_f32_dpp v3, v3, v3 quad_perm:[2,3,0,1] row_mask:0xf bank_mask:0xf
	v_sub_f32_e32 v3, 0, v3
	v_cndmask_b32_e64 v15, v15, v3, s[44:45]
	ds_read2_b32 v[58:59], v7 offset0:192 offset1:196
	ds_read2_b32 v[60:61], v7 offset0:208 offset1:212
	ds_read2_b32 v[62:63], v7 offset0:216 offset1:220
	ds_read2_b32 v[64:65], v7 offset0:200 offset1:204
	v_mov_b32_e32 v11, v12
	s_waitcnt lgkmcnt(3)
	v_fma_f32 v3, v58, v2, 0
	v_fmac_f32_e32 v3, v4, v59
	s_waitcnt lgkmcnt(2)
	v_pk_mul_f32 v[60:61], v[10:11], v[60:61]
	s_waitcnt lgkmcnt(0)
	v_fmac_f32_e32 v3, v6, v64
	v_fmac_f32_e32 v3, v8, v65
	v_add_f32_e32 v3, v3, v60
	v_pk_mul_f32 v[62:63], v[14:15], v[62:63]
	v_add_f32_e32 v3, v3, v61
	v_add_f32_e32 v3, v3, v62
	v_add_f32_e32 v3, v3, v63
	v_add_u32_e32 v7, 0x6400, v56
	s_waitcnt lgkmcnt(0)
	s_nop 1
	v_add_f32_dpp v3, v3, v3 quad_perm:[1,0,3,2] row_mask:0xf bank_mask:0xf
	s_nop 1
	v_add_f32_dpp v3, v3, v3 quad_perm:[2,3,0,1] row_mask:0xf bank_mask:0xf
	v_sub_f32_e32 v3, 0, v3
	v_cndmask_b32_e32 v16, v15, v3, vcc
	ds_read2_b32 v[58:59], v7 offset1:4
	ds_read2_b32 v[60:61], v7 offset0:8 offset1:12
	ds_read2_b32 v[62:63], v7 offset0:16 offset1:20
	ds_read2_b32 v[64:65], v7 offset0:24 offset1:28
	v_mov_b32_e32 v11, v12
	s_waitcnt lgkmcnt(3)
	v_fma_f32 v3, v58, v2, 0
	v_fmac_f32_e32 v3, v4, v59
	s_waitcnt lgkmcnt(2)
	v_fmac_f32_e32 v3, v6, v60
	s_waitcnt lgkmcnt(1)
	v_pk_mul_f32 v[62:63], v[10:11], v[62:63]
	v_fmac_f32_e32 v3, v8, v61
	v_mov_b32_e32 v15, v16
	v_add_f32_e32 v3, v3, v62
	s_waitcnt lgkmcnt(0)
	v_pk_mul_f32 v[64:65], v[14:15], v[64:65]
	v_add_f32_e32 v3, v3, v63
	v_add_f32_e32 v3, v3, v64
	v_add_f32_e32 v3, v3, v65
	s_nop 1
	v_add_f32_dpp v3, v3, v3 quad_perm:[1,0,3,2] row_mask:0xf bank_mask:0xf
	s_nop 1
	v_add_f32_dpp v3, v3, v3 quad_perm:[2,3,0,1] row_mask:0xf bank_mask:0xf
	v_sub_f32_e32 v3, 0, v3
	v_cndmask_b32_e64 v17, v17, v3, s[42:43]
	ds_read2_b32 v[58:59], v7 offset0:64 offset1:68
	ds_read2_b32 v[60:61], v7 offset0:72 offset1:76
	ds_read2_b32 v[62:63], v7 offset0:80 offset1:84
	ds_read2_b32 v[64:65], v7 offset0:88 offset1:92
	ds_read_b32 v67, v56 offset:25984
	s_waitcnt lgkmcnt(4)
	v_fma_f32 v3, v58, v2, 0
	v_fmac_f32_e32 v3, v4, v59
	s_waitcnt lgkmcnt(3)
	v_fmac_f32_e32 v3, v6, v60
	v_mov_b32_e32 v13, v14
	s_waitcnt lgkmcnt(2)
	v_mov_b32_e32 v68, v63
	s_waitcnt lgkmcnt(1)
	v_mov_b32_e32 v69, v64
	v_fmac_f32_e32 v3, v8, v61
	v_pk_mul_f32 v[58:59], v[12:13], v[68:69]
	v_fmac_f32_e32 v3, v10, v62
	v_mov_b32_e32 v66, v65
	v_add_f32_e32 v3, v3, v58
	s_waitcnt lgkmcnt(0)
; #define LAS __attribute__((address_space(3)))
; template <int W> __device__ __forceinline__ void dn_solve(const LAS float* Mf, float (&t)[16], int lane) {
;     const int j = 16 * W + (lane >> 2), q = lane & 3;
; #pragma unroll
;     for (int s = 0; s < 16; ++s) t[s] = 0.f;
; #pragma unroll
;     for (int i = 16 * W; i < 64; ++i) {
;         float acc = 0.f;
; #pragma unroll
;         for (int s = 4 * W; s <= (i - 1) / 4 && i > 16 * W; ++s) acc += Mf[i * 64 + 4 * s + q] * t[s];
;         acc += __shfl_xor(acc, 1); acc += __shfl_xor(acc, 2);
;         const float val = (i == j ? 1.f : 0.f) - acc;
;         if (q == (i & 3)) t[i >> 2] = val;
;         asm volatile("" : "+v"(t[0]), "+v"(t[1]), "+v"(t[2]), "+v"(t[3]), "+v"(t[4]), "+v"(t[5]), "+v"(t[6]), "+v"(t[7]), "+v"(t[8]), "+v"(t[9]), "+v"(t[10]), "+v"(t[11]), "+v"(t[12]), "+v"(t[13]), "+v"(t[14]), "+v"(t[15]));
;     }
; }
	v_pk_mul_f32 v[64:65], v[16:17], v[66:67]
	v_add_f32_e32 v3, v3, v59
	v_add_f32_e32 v3, v3, v64
	v_add_f32_e32 v3, v3, v65
	s_nop 1
	v_add_f32_dpp v3, v3, v3 quad_perm:[1,0,3,2] row_mask:0xf bank_mask:0xf
	s_nop 1
	v_add_f32_dpp v3, v3, v3 quad_perm:[2,3,0,1] row_mask:0xf bank_mask:0xf
	v_sub_f32_e32 v3, 0, v3
	v_cndmask_b32_e64 v17, v17, v3, s[46:47]
	ds_read2_b32 v[58:59], v7 offset0:128 offset1:132
	ds_read2_b32 v[60:61], v7 offset0:136 offset1:140
	ds_read2_b32 v[62:63], v7 offset0:144 offset1:148
	ds_read2_b32 v[64:65], v7 offset0:152 offset1:156
	ds_read_b32 v67, v56 offset:26240
	s_waitcnt lgkmcnt(4)
	v_fma_f32 v3, v58, v2, 0
	v_fmac_f32_e32 v3, v4, v59
	s_waitcnt lgkmcnt(3)
	v_fmac_f32_e32 v3, v6, v60
	v_mov_b32_e32 v13, v14
	s_waitcnt lgkmcnt(2)
	v_mov_b32_e32 v68, v63
	s_waitcnt lgkmcnt(1)
	v_mov_b32_e32 v69, v64
	v_fmac_f32_e32 v3, v8, v61
	v_pk_mul_f32 v[58:59], v[12:13], v[68:69]
	v_fmac_f32_e32 v3, v10, v62
	v_mov_b32_e32 v66, v65
	v_add_f32_e32 v3, v3, v58
	s_waitcnt lgkmcnt(0)
	v_pk_mul_f32 v[64:65], v[16:17], v[66:67]
	v_add_f32_e32 v3, v3, v59
	v_add_f32_e32 v3, v3, v64
	v_add_f32_e32 v3, v3, v65
	s_nop 1
	v_add_f32_dpp v3, v3, v3 quad_perm:[1,0,3,2] row_mask:0xf bank_mask:0xf
	s_nop 1
	v_add_f32_dpp v3, v3, v3 quad_perm:[2,3,0,1] row_mask:0xf bank_mask:0xf
	v_sub_f32_e32 v3, 0, v3
	v_cndmask_b32_e64 v17, v17, v3, s[44:45]
	ds_read2_b32 v[58:59], v7 offset0:192 offset1:196
	ds_read2_b32 v[60:61], v7 offset0:200 offset1:204
	ds_read2_b32 v[62:63], v7 offset0:208 offset1:212
	ds_read2_b32 v[64:65], v7 offset0:216 offset1:220
	ds_read_b32 v67, v56 offset:26496
	s_waitcnt lgkmcnt(4)
	v_fma_f32 v3, v58, v2, 0
	v_fmac_f32_e32 v3, v4, v59
	s_waitcnt lgkmcnt(3)
	v_fmac_f32_e32 v3, v6, v60
	v_mov_b32_e32 v13, v14
	s_waitcnt lgkmcnt(2)
	v_mov_b32_e32 v68, v63
	s_waitcnt lgkmcnt(1)
	v_mov_b32_e32 v69, v64
	v_fmac_f32_e32 v3, v8, v61
	v_pk_mul_f32 v[58:59], v[12:13], v[68:69]
	v_fmac_f32_e32 v3, v10, v62
	v_mov_b32_e32 v66, v65
	v_add_f32_e32 v3, v3, v58
	s_waitcnt lgkmcnt(0)
	v_pk_mul_f32 v[64:65], v[16:17], v[66:67]
	v_add_f32_e32 v3, v3, v59
	v_add_f32_e32 v3, v3, v64
	v_add_f32_e32 v3, v3, v65
	v_add_u32_e32 v7, 0x6800, v56
	s_waitcnt lgkmcnt(0)
	s_nop 1
	v_add_f32_dpp v3, v3, v3 quad_perm:[1,0,3,2] row_mask:0xf bank_mask:0xf
	s_nop 1
	v_add_f32_dpp v3, v3, v3 quad_perm:[2,3,0,1] row_mask:0xf bank_mask:0xf
	v_sub_f32_e32 v3, 0, v3
	v_cndmask_b32_e32 v34, v17, v3, vcc
	ds_read2_b32 v[58:59], v7 offset1:4
	ds_read2_b32 v[60:61], v7 offset0:8 offset1:12
	ds_read2_b32 v[62:63], v7 offset0:16 offset1:20
	ds_read2_b32 v[64:65], v7 offset0:24 offset1:28
	ds_read_b32 v67, v56 offset:26752
	s_waitcnt lgkmcnt(4)
	v_fma_f32 v3, v58, v2, 0
	v_fmac_f32_e32 v3, v4, v59
	s_waitcnt lgkmcnt(3)
	v_fmac_f32_e32 v3, v6, v60
	v_mov_b32_e32 v13, v14
	s_waitcnt lgkmcnt(2)
	v_mov_b32_e32 v68, v63
	s_waitcnt lgkmcnt(1)
	v_mov_b32_e32 v69, v64
	v_fmac_f32_e32 v3, v8, v61
	v_pk_mul_f32 v[58:59], v[12:13], v[68:69]
	v_fmac_f32_e32 v3, v10, v62
	v_mov_b32_e32 v17, v34
	v_mov_b32_e32 v66, v65
	v_add_f32_e32 v3, v3, v58
	s_waitcnt lgkmcnt(0)
	v_pk_mul_f32 v[64:65], v[16:17], v[66:67]
	v_add_f32_e32 v3, v3, v59
	v_add_f32_e32 v3, v3, v64
	v_add_f32_e32 v3, v3, v65
	s_nop 1
	v_add_f32_dpp v3, v3, v3 quad_perm:[1,0,3,2] row_mask:0xf bank_mask:0xf
	s_nop 1
	v_add_f32_dpp v3, v3, v3 quad_perm:[2,3,0,1] row_mask:0xf bank_mask:0xf
	v_sub_f32_e32 v3, 0, v3
	v_cndmask_b32_e64 v35, v35, v3, s[42:43]
	ds_read2_b32 v[58:59], v7 offset0:64 offset1:68
	ds_read2_b32 v[60:61], v7 offset0:72 offset1:76
	ds_read2_b32 v[62:63], v7 offset0:88 offset1:92
	ds_read2_b32 v[64:65], v7 offset0:96 offset1:100
	ds_read2_b32 v[66:67], v7 offset0:80 offset1:84
	s_waitcnt lgkmcnt(4)
	v_fma_f32 v3, v58, v2, 0
	v_fmac_f32_e32 v3, v4, v59
	s_waitcnt lgkmcnt(3)
	v_fmac_f32_e32 v3, v6, v60
	v_fmac_f32_e32 v3, v8, v61
	v_mov_b32_e32 v15, v16
	s_waitcnt lgkmcnt(0)
	v_fmac_f32_e32 v3, v10, v66
	v_pk_mul_f32 v[62:63], v[14:15], v[62:63]
	v_fmac_f32_e32 v3, v12, v67
	v_add_f32_e32 v3, v3, v62
	v_pk_mul_f32 v[64:65], v[34:35], v[64:65]
	v_add_f32_e32 v3, v3, v63
	v_add_f32_e32 v3, v3, v64
	v_add_f32_e32 v3, v3, v65
	s_nop 1
	v_add_f32_dpp v3, v3, v3 quad_perm:[1,0,3,2] row_mask:0xf bank_mask:0xf
	s_nop 1
	v_add_f32_dpp v3, v3, v3 quad_perm:[2,3,0,1] row_mask:0xf bank_mask:0xf
	v_sub_f32_e32 v3, 0, v3
	v_cndmask_b32_e64 v35, v35, v3, s[46:47]
	ds_read2_b32 v[58:59], v7 offset0:128 offset1:132
	ds_read2_b32 v[60:61], v7 offset0:136 offset1:140
	ds_read2_b32 v[62:63], v7 offset0:152 offset1:156
	ds_read2_b32 v[64:65], v7 offset0:160 offset1:164
	ds_read2_b32 v[66:67], v7 offset0:144 offset1:148
	s_waitcnt lgkmcnt(4)
	v_fma_f32 v3, v58, v2, 0
	v_fmac_f32_e32 v3, v4, v59
	s_waitcnt lgkmcnt(3)
	v_fmac_f32_e32 v3, v6, v60
	v_fmac_f32_e32 v3, v8, v61
	v_mov_b32_e32 v15, v16
	s_waitcnt lgkmcnt(0)
	v_fmac_f32_e32 v3, v10, v66
	v_pk_mul_f32 v[62:63], v[14:15], v[62:63]
	v_fmac_f32_e32 v3, v12, v67
	v_add_f32_e32 v3, v3, v62
	v_pk_mul_f32 v[64:65], v[34:35], v[64:65]
	v_add_f32_e32 v3, v3, v63
	v_add_f32_e32 v3, v3, v64
	v_add_f32_e32 v3, v3, v65
	s_nop 1
	v_add_f32_dpp v3, v3, v3 quad_perm:[1,0,3,2] row_mask:0xf bank_mask:0xf
	s_nop 1
	v_add_f32_dpp v3, v3, v3 quad_perm:[2,3,0,1] row_mask:0xf bank_mask:0xf
	v_sub_f32_e32 v3, 0, v3
	v_cndmask_b32_e64 v35, v35, v3, s[44:45]
	ds_read2_b32 v[58:59], v7 offset0:192 offset1:196
	ds_read2_b32 v[60:61], v7 offset0:200 offset1:204
	ds_read2_b32 v[62:63], v7 offset0:216 offset1:220
	ds_read2_b32 v[64:65], v7 offset0:224 offset1:228
	ds_read2_b32 v[66:67], v7 offset0:208 offset1:212
	s_waitcnt lgkmcnt(4)
	v_fma_f32 v3, v58, v2, 0
	v_fmac_f32_e32 v3, v4, v59
	s_waitcnt lgkmcnt(3)
; #define LAS __attribute__((address_space(3)))
; template <int W> __device__ __forceinline__ void dn_solve(const LAS float* Mf, float (&t)[16], int lane) {
;     const int j = 16 * W + (lane >> 2), q = lane & 3;
; #pragma unroll
;     for (int s = 0; s < 16; ++s) t[s] = 0.f;
; #pragma unroll
;     for (int i = 16 * W; i < 64; ++i) {
;         float acc = 0.f;
; #pragma unroll
;         for (int s = 4 * W; s <= (i - 1) / 4 && i > 16 * W; ++s) acc += Mf[i * 64 + 4 * s + q] * t[s];
;         acc += __shfl_xor(acc, 1); acc += __shfl_xor(acc, 2);
;         const float val = (i == j ? 1.f : 0.f) - acc;
;         if (q == (i & 3)) t[i >> 2] = val;
;         asm volatile("" : "+v"(t[0]), "+v"(t[1]), "+v"(t[2]), "+v"(t[3]), "+v"(t[4]), "+v"(t[5]), "+v"(t[6]), "+v"(t[7]), "+v"(t[8]), "+v"(t[9]), "+v"(t[10]), "+v"(t[11]), "+v"(t[12]), "+v"(t[13]), "+v"(t[14]), "+v"(t[15]));
;     }
; }
	v_fmac_f32_e32 v3, v6, v60
	v_fmac_f32_e32 v3, v8, v61
	v_mov_b32_e32 v15, v16
	s_waitcnt lgkmcnt(0)
	v_fmac_f32_e32 v3, v10, v66
	v_pk_mul_f32 v[62:63], v[14:15], v[62:63]
	v_fmac_f32_e32 v3, v12, v67
	v_add_f32_e32 v3, v3, v62
	v_pk_mul_f32 v[64:65], v[34:35], v[64:65]
	v_add_f32_e32 v3, v3, v63
	v_add_f32_e32 v3, v3, v64
	v_add_f32_e32 v3, v3, v65
	v_add_u32_e32 v7, 0x6c00, v56
	s_waitcnt lgkmcnt(0)
	s_nop 1
	v_add_f32_dpp v3, v3, v3 quad_perm:[1,0,3,2] row_mask:0xf bank_mask:0xf
	s_nop 1
	v_add_f32_dpp v3, v3, v3 quad_perm:[2,3,0,1] row_mask:0xf bank_mask:0xf
	v_sub_f32_e32 v3, 0, v3
	v_cndmask_b32_e32 v36, v35, v3, vcc
	ds_read2_b32 v[58:59], v7 offset1:4
	ds_read2_b32 v[60:61], v7 offset0:8 offset1:12
	ds_read2_b32 v[62:63], v7 offset0:16 offset1:20
	ds_read2_b32 v[64:65], v7 offset0:24 offset1:28
	ds_read2_b32 v[66:67], v7 offset0:32 offset1:36
	s_waitcnt lgkmcnt(4)
	v_fma_f32 v3, v58, v2, 0
	v_fmac_f32_e32 v3, v4, v59
	s_waitcnt lgkmcnt(3)
	v_fmac_f32_e32 v3, v6, v60
	v_fmac_f32_e32 v3, v8, v61
	v_mov_b32_e32 v15, v16
	s_waitcnt lgkmcnt(2)
	v_fmac_f32_e32 v3, v10, v62
	s_waitcnt lgkmcnt(1)
	v_pk_mul_f32 v[64:65], v[14:15], v[64:65]
	v_fmac_f32_e32 v3, v12, v63
	v_mov_b32_e32 v35, v36
	v_add_f32_e32 v3, v3, v64
	s_waitcnt lgkmcnt(0)
	v_pk_mul_f32 v[66:67], v[34:35], v[66:67]
	v_add_f32_e32 v3, v3, v65
	v_add_f32_e32 v3, v3, v66
	v_add_f32_e32 v3, v3, v67
	s_nop 1
	v_add_f32_dpp v3, v3, v3 quad_perm:[1,0,3,2] row_mask:0xf bank_mask:0xf
	s_nop 1
	v_add_f32_dpp v3, v3, v3 quad_perm:[2,3,0,1] row_mask:0xf bank_mask:0xf
	v_sub_f32_e32 v3, 0, v3
	v_cndmask_b32_e64 v37, v37, v3, s[42:43]
	ds_read2_b32 v[58:59], v7 offset0:64 offset1:68
	ds_read2_b32 v[60:61], v7 offset0:72 offset1:76
	ds_read2_b32 v[62:63], v7 offset0:80 offset1:84
	ds_read2_b32 v[64:65], v7 offset0:88 offset1:92
	ds_read2_b32 v[66:67], v7 offset0:96 offset1:100
	ds_read_b32 v69, v56 offset:28064
	s_waitcnt lgkmcnt(5)
	v_fma_f32 v3, v58, v2, 0
	v_fmac_f32_e32 v3, v4, v59
	s_waitcnt lgkmcnt(4)
	v_fmac_f32_e32 v3, v6, v60
	v_fmac_f32_e32 v3, v8, v61
	s_waitcnt lgkmcnt(3)
	v_fmac_f32_e32 v3, v10, v62
	v_mov_b32_e32 v17, v34
	s_waitcnt lgkmcnt(2)
	v_mov_b32_e32 v70, v65
	s_waitcnt lgkmcnt(1)
	v_mov_b32_e32 v71, v66
	v_fmac_f32_e32 v3, v12, v63
	v_pk_mul_f32 v[58:59], v[16:17], v[70:71]
	v_fmac_f32_e32 v3, v14, v64
	v_mov_b32_e32 v68, v67
	v_add_f32_e32 v3, v3, v58
	s_waitcnt lgkmcnt(0)
	v_pk_mul_f32 v[66:67], v[36:37], v[68:69]
	v_add_f32_e32 v3, v3, v59
	v_add_f32_e32 v3, v3, v66
	v_add_f32_e32 v3, v3, v67
	s_nop 1
	v_add_f32_dpp v3, v3, v3 quad_perm:[1,0,3,2] row_mask:0xf bank_mask:0xf
	s_nop 1
	v_add_f32_dpp v3, v3, v3 quad_perm:[2,3,0,1] row_mask:0xf bank_mask:0xf
	v_sub_f32_e32 v3, 0, v3
	v_cndmask_b32_e64 v37, v37, v3, s[46:47]
	ds_read2_b32 v[58:59], v7 offset0:128 offset1:132
	ds_read2_b32 v[60:61], v7 offset0:136 offset1:140
	ds_read2_b32 v[62:63], v7 offset0:144 offset1:148
	ds_read2_b32 v[64:65], v7 offset0:152 offset1:156
	ds_read2_b32 v[66:67], v7 offset0:160 offset1:164
	ds_read_b32 v69, v56 offset:28320
	s_waitcnt lgkmcnt(5)
	v_fma_f32 v3, v58, v2, 0
	v_fmac_f32_e32 v3, v4, v59
	s_waitcnt lgkmcnt(4)
	v_fmac_f32_e32 v3, v6, v60
	v_fmac_f32_e32 v3, v8, v61
	s_waitcnt lgkmcnt(3)
	v_fmac_f32_e32 v3, v10, v62
	v_mov_b32_e32 v17, v34
	s_waitcnt lgkmcnt(2)
	v_mov_b32_e32 v70, v65
	s_waitcnt lgkmcnt(1)
	v_mov_b32_e32 v71, v66
	v_fmac_f32_e32 v3, v12, v63
	v_pk_mul_f32 v[58:59], v[16:17], v[70:71]
	v_fmac_f32_e32 v3, v14, v64
	v_mov_b32_e32 v68, v67
	v_add_f32_e32 v3, v3, v58
	s_waitcnt lgkmcnt(0)
	v_pk_mul_f32 v[66:67], v[36:37], v[68:69]
	v_add_f32_e32 v3, v3, v59
	v_add_f32_e32 v3, v3, v66
	v_add_f32_e32 v3, v3, v67
	s_nop 1
	v_add_f32_dpp v3, v3, v3 quad_perm:[1,0,3,2] row_mask:0xf bank_mask:0xf
	s_nop 1
	v_add_f32_dpp v3, v3, v3 quad_perm:[2,3,0,1] row_mask:0xf bank_mask:0xf
	v_sub_f32_e32 v3, 0, v3
	v_cndmask_b32_e64 v37, v37, v3, s[44:45]
	ds_read2_b32 v[58:59], v7 offset0:192 offset1:196
	ds_read2_b32 v[60:61], v7 offset0:200 offset1:204
	ds_read2_b32 v[62:63], v7 offset0:208 offset1:212
	ds_read2_b32 v[64:65], v7 offset0:216 offset1:220
	ds_read2_b32 v[66:67], v7 offset0:224 offset1:228
	ds_read_b32 v69, v56 offset:28576
	s_waitcnt lgkmcnt(5)
	v_fma_f32 v3, v58, v2, 0
	v_fmac_f32_e32 v3, v4, v59
	s_waitcnt lgkmcnt(4)
	v_fmac_f32_e32 v3, v6, v60
	v_fmac_f32_e32 v3, v8, v61
	s_waitcnt lgkmcnt(3)
	v_fmac_f32_e32 v3, v10, v62
	v_mov_b32_e32 v17, v34
	s_waitcnt lgkmcnt(2)
	v_mov_b32_e32 v70, v65
	s_waitcnt lgkmcnt(1)
	v_mov_b32_e32 v71, v66
	v_fmac_f32_e32 v3, v12, v63
	v_pk_mul_f32 v[58:59], v[16:17], v[70:71]
	v_fmac_f32_e32 v3, v14, v64
	v_mov_b32_e32 v68, v67
	v_add_f32_e32 v3, v3, v58
	s_waitcnt lgkmcnt(0)
	v_pk_mul_f32 v[66:67], v[36:37], v[68:69]
	v_add_f32_e32 v3, v3, v59
	v_add_f32_e32 v3, v3, v66
	v_add_f32_e32 v3, v3, v67
	v_add_u32_e32 v7, 0x7000, v56
	s_waitcnt lgkmcnt(0)
	s_nop 1
	v_add_f32_dpp v3, v3, v3 quad_perm:[1,0,3,2] row_mask:0xf bank_mask:0xf
	s_nop 1
	v_add_f32_dpp v3, v3, v3 quad_perm:[2,3,0,1] row_mask:0xf bank_mask:0xf
	v_sub_f32_e32 v3, 0, v3
	v_cndmask_b32_e32 v38, v37, v3, vcc
	ds_read2_b32 v[58:59], v7 offset1:4
	ds_read2_b32 v[60:61], v7 offset0:8 offset1:12
	ds_read2_b32 v[62:63], v7 offset0:16 offset1:20
	ds_read2_b32 v[64:65], v7 offset0:24 offset1:28
	ds_read2_b32 v[66:67], v7 offset0:32 offset1:36
	ds_read_b32 v69, v56 offset:28832
	s_waitcnt lgkmcnt(5)
	v_fma_f32 v3, v58, v2, 0
	v_fmac_f32_e32 v3, v4, v59
	s_waitcnt lgkmcnt(4)
	v_fmac_f32_e32 v3, v6, v60
	v_fmac_f32_e32 v3, v8, v61
	s_waitcnt lgkmcnt(3)
	v_fmac_f32_e32 v3, v10, v62
	v_mov_b32_e32 v17, v34
	s_waitcnt lgkmcnt(2)
	v_mov_b32_e32 v70, v65
	s_waitcnt lgkmcnt(1)
; #define LAS __attribute__((address_space(3)))
; template <int W> __device__ __forceinline__ void dn_solve(const LAS float* Mf, float (&t)[16], int lane) {
;     const int j = 16 * W + (lane >> 2), q = lane & 3;
; #pragma unroll
;     for (int s = 0; s < 16; ++s) t[s] = 0.f;
; #pragma unroll
;     for (int i = 16 * W; i < 64; ++i) {
;         float acc = 0.f;
; #pragma unroll
;         for (int s = 4 * W; s <= (i - 1) / 4 && i > 16 * W; ++s) acc += Mf[i * 64 + 4 * s + q] * t[s];
;         acc += __shfl_xor(acc, 1); acc += __shfl_xor(acc, 2);
;         const float val = (i == j ? 1.f : 0.f) - acc;
;         if (q == (i & 3)) t[i >> 2] = val;
;         asm volatile("" : "+v"(t[0]), "+v"(t[1]), "+v"(t[2]), "+v"(t[3]), "+v"(t[4]), "+v"(t[5]), "+v"(t[6]), "+v"(t[7]), "+v"(t[8]), "+v"(t[9]), "+v"(t[10]), "+v"(t[11]), "+v"(t[12]), "+v"(t[13]), "+v"(t[14]), "+v"(t[15]));
;     }
; }
	v_mov_b32_e32 v71, v66
	v_fmac_f32_e32 v3, v12, v63
	v_pk_mul_f32 v[58:59], v[16:17], v[70:71]
	v_fmac_f32_e32 v3, v14, v64
	v_mov_b32_e32 v37, v38
	v_mov_b32_e32 v68, v67
	v_add_f32_e32 v3, v3, v58
	s_waitcnt lgkmcnt(0)
	v_pk_mul_f32 v[66:67], v[36:37], v[68:69]
	v_add_f32_e32 v3, v3, v59
	v_add_f32_e32 v3, v3, v66
	v_add_f32_e32 v3, v3, v67
	s_nop 1
	v_add_f32_dpp v3, v3, v3 quad_perm:[1,0,3,2] row_mask:0xf bank_mask:0xf
	s_nop 1
	v_add_f32_dpp v3, v3, v3 quad_perm:[2,3,0,1] row_mask:0xf bank_mask:0xf
	v_sub_f32_e32 v3, 0, v3
	v_cndmask_b32_e64 v39, v39, v3, s[42:43]
	ds_read2_b32 v[58:59], v7 offset0:64 offset1:68
	ds_read2_b32 v[60:61], v7 offset0:72 offset1:76
	ds_read2_b32 v[62:63], v7 offset0:80 offset1:84
	ds_read2_b32 v[64:65], v7 offset0:96 offset1:100
	ds_read2_b32 v[66:67], v7 offset0:104 offset1:108
	ds_read2_b32 v[68:69], v7 offset0:88 offset1:92
	s_waitcnt lgkmcnt(5)
	v_fma_f32 v3, v58, v2, 0
	v_fmac_f32_e32 v3, v4, v59
	s_waitcnt lgkmcnt(4)
	v_fmac_f32_e32 v3, v6, v60
	v_fmac_f32_e32 v3, v8, v61
	s_waitcnt lgkmcnt(3)
	v_fmac_f32_e32 v3, v10, v62
	v_fmac_f32_e32 v3, v12, v63
	v_mov_b32_e32 v35, v36
	s_waitcnt lgkmcnt(0)
	v_fmac_f32_e32 v3, v14, v68
	v_pk_mul_f32 v[64:65], v[34:35], v[64:65]
	v_fmac_f32_e32 v3, v16, v69
	v_add_f32_e32 v3, v3, v64
	v_pk_mul_f32 v[66:67], v[38:39], v[66:67]
	v_add_f32_e32 v3, v3, v65
	v_add_f32_e32 v3, v3, v66
	v_add_f32_e32 v3, v3, v67
	s_nop 1
	v_add_f32_dpp v3, v3, v3 quad_perm:[1,0,3,2] row_mask:0xf bank_mask:0xf
	s_nop 1
	v_add_f32_dpp v3, v3, v3 quad_perm:[2,3,0,1] row_mask:0xf bank_mask:0xf
	v_sub_f32_e32 v3, 0, v3
	v_cndmask_b32_e64 v39, v39, v3, s[46:47]
	ds_read2_b32 v[58:59], v7 offset0:128 offset1:132
	ds_read2_b32 v[60:61], v7 offset0:136 offset1:140
	ds_read2_b32 v[62:63], v7 offset0:144 offset1:148
	ds_read2_b32 v[64:65], v7 offset0:160 offset1:164
	ds_read2_b32 v[66:67], v7 offset0:168 offset1:172
	ds_read2_b32 v[68:69], v7 offset0:152 offset1:156
	s_waitcnt lgkmcnt(5)
	v_fma_f32 v3, v58, v2, 0
	v_fmac_f32_e32 v3, v4, v59
	s_waitcnt lgkmcnt(4)
	v_fmac_f32_e32 v3, v6, v60
	v_fmac_f32_e32 v3, v8, v61
	s_waitcnt lgkmcnt(3)
	v_fmac_f32_e32 v3, v10, v62
	v_fmac_f32_e32 v3, v12, v63
	v_mov_b32_e32 v35, v36
	s_waitcnt lgkmcnt(0)
	v_fmac_f32_e32 v3, v14, v68
	v_pk_mul_f32 v[64:65], v[34:35], v[64:65]
	v_fmac_f32_e32 v3, v16, v69
	v_add_f32_e32 v3, v3, v64
	v_pk_mul_f32 v[66:67], v[38:39], v[66:67]
	v_add_f32_e32 v3, v3, v65
	v_add_f32_e32 v3, v3, v66
	v_add_f32_e32 v3, v3, v67
	s_nop 1
	v_add_f32_dpp v3, v3, v3 quad_perm:[1,0,3,2] row_mask:0xf bank_mask:0xf
	s_nop 1
	v_add_f32_dpp v3, v3, v3 quad_perm:[2,3,0,1] row_mask:0xf bank_mask:0xf
	v_sub_f32_e32 v3, 0, v3
	v_cndmask_b32_e64 v39, v39, v3, s[44:45]
	ds_read2_b32 v[58:59], v7 offset0:192 offset1:196
	ds_read2_b32 v[60:61], v7 offset0:200 offset1:204
	ds_read2_b32 v[62:63], v7 offset0:208 offset1:212
	ds_read2_b32 v[64:65], v7 offset0:224 offset1:228
	ds_read2_b32 v[66:67], v7 offset0:232 offset1:236
	ds_read2_b32 v[68:69], v7 offset0:216 offset1:220
	s_waitcnt lgkmcnt(5)
	v_fma_f32 v3, v58, v2, 0
	v_fmac_f32_e32 v3, v4, v59
	s_waitcnt lgkmcnt(4)
	v_fmac_f32_e32 v3, v6, v60
	v_fmac_f32_e32 v3, v8, v61
	s_waitcnt lgkmcnt(3)
	v_fmac_f32_e32 v3, v10, v62
	v_fmac_f32_e32 v3, v12, v63
	v_mov_b32_e32 v35, v36
	s_waitcnt lgkmcnt(0)
	v_fmac_f32_e32 v3, v14, v68
	v_pk_mul_f32 v[64:65], v[34:35], v[64:65]
	v_fmac_f32_e32 v3, v16, v69
	v_add_f32_e32 v3, v3, v64
	v_pk_mul_f32 v[66:67], v[38:39], v[66:67]
	v_add_f32_e32 v3, v3, v65
	v_add_f32_e32 v3, v3, v66
	v_add_f32_e32 v3, v3, v67
	v_add_u32_e32 v7, 0x7400, v56
	s_waitcnt lgkmcnt(0)
	s_nop 1
	v_add_f32_dpp v3, v3, v3 quad_perm:[1,0,3,2] row_mask:0xf bank_mask:0xf
	s_nop 1
	v_add_f32_dpp v3, v3, v3 quad_perm:[2,3,0,1] row_mask:0xf bank_mask:0xf
	v_sub_f32_e32 v3, 0, v3
	v_cndmask_b32_e32 v40, v39, v3, vcc
	ds_read2_b32 v[58:59], v7 offset1:4
	ds_read2_b32 v[60:61], v7 offset0:8 offset1:12
	ds_read2_b32 v[62:63], v7 offset0:16 offset1:20
	ds_read2_b32 v[64:65], v7 offset0:24 offset1:28
	ds_read2_b32 v[66:67], v7 offset0:32 offset1:36
	ds_read2_b32 v[68:69], v7 offset0:40 offset1:44
	s_waitcnt lgkmcnt(5)
	v_fma_f32 v3, v58, v2, 0
	v_fmac_f32_e32 v3, v4, v59
	s_waitcnt lgkmcnt(4)
	v_fmac_f32_e32 v3, v6, v60
	v_fmac_f32_e32 v3, v8, v61
	s_waitcnt lgkmcnt(3)
	v_fmac_f32_e32 v3, v10, v62
	v_fmac_f32_e32 v3, v12, v63
	v_mov_b32_e32 v35, v36
	s_waitcnt lgkmcnt(2)
	v_fmac_f32_e32 v3, v14, v64
	s_waitcnt lgkmcnt(1)
	v_pk_mul_f32 v[66:67], v[34:35], v[66:67]
	v_fmac_f32_e32 v3, v16, v65
	v_mov_b32_e32 v39, v40
	v_add_f32_e32 v3, v3, v66
	s_waitcnt lgkmcnt(0)
	v_pk_mul_f32 v[68:69], v[38:39], v[68:69]
	v_add_f32_e32 v3, v3, v67
	v_add_f32_e32 v3, v3, v68
	v_add_f32_e32 v3, v3, v69
	s_nop 1
	v_add_f32_dpp v3, v3, v3 quad_perm:[1,0,3,2] row_mask:0xf bank_mask:0xf
	s_nop 1
	v_add_f32_dpp v3, v3, v3 quad_perm:[2,3,0,1] row_mask:0xf bank_mask:0xf
	v_sub_f32_e32 v3, 0, v3
	v_cndmask_b32_e64 v41, v41, v3, s[42:43]
	ds_read2_b32 v[58:59], v7 offset0:64 offset1:68
	ds_read2_b32 v[60:61], v7 offset0:72 offset1:76
	ds_read2_b32 v[62:63], v7 offset0:80 offset1:84
	ds_read2_b32 v[64:65], v7 offset0:88 offset1:92
	ds_read2_b32 v[66:67], v7 offset0:96 offset1:100
	ds_read2_b32 v[68:69], v7 offset0:104 offset1:108
	ds_read_b32 v71, v56 offset:30144
	s_waitcnt lgkmcnt(6)
	v_fma_f32 v3, v58, v2, 0
	v_fmac_f32_e32 v3, v4, v59
	s_waitcnt lgkmcnt(5)
	v_fmac_f32_e32 v3, v6, v60
	v_fmac_f32_e32 v3, v8, v61
	s_waitcnt lgkmcnt(4)
	v_fmac_f32_e32 v3, v10, v62
	v_fmac_f32_e32 v3, v12, v63
	s_waitcnt lgkmcnt(3)
	v_fmac_f32_e32 v3, v14, v64
	v_mov_b32_e32 v37, v38
	s_waitcnt lgkmcnt(2)
	v_mov_b32_e32 v72, v67
	s_waitcnt lgkmcnt(1)
; #define LAS __attribute__((address_space(3)))
; template <int W> __device__ __forceinline__ void dn_solve(const LAS float* Mf, float (&t)[16], int lane) {
;     const int j = 16 * W + (lane >> 2), q = lane & 3;
; #pragma unroll
;     for (int s = 0; s < 16; ++s) t[s] = 0.f;
; #pragma unroll
;     for (int i = 16 * W; i < 64; ++i) {
;         float acc = 0.f;
; #pragma unroll
;         for (int s = 4 * W; s <= (i - 1) / 4 && i > 16 * W; ++s) acc += Mf[i * 64 + 4 * s + q] * t[s];
;         acc += __shfl_xor(acc, 1); acc += __shfl_xor(acc, 2);
;         const float val = (i == j ? 1.f : 0.f) - acc;
;         if (q == (i & 3)) t[i >> 2] = val;
;         asm volatile("" : "+v"(t[0]), "+v"(t[1]), "+v"(t[2]), "+v"(t[3]), "+v"(t[4]), "+v"(t[5]), "+v"(t[6]), "+v"(t[7]), "+v"(t[8]), "+v"(t[9]), "+v"(t[10]), "+v"(t[11]), "+v"(t[12]), "+v"(t[13]), "+v"(t[14]), "+v"(t[15]));
;     }
; }
	v_mov_b32_e32 v73, v68
	v_fmac_f32_e32 v3, v16, v65
	v_pk_mul_f32 v[58:59], v[36:37], v[72:73]
	v_fmac_f32_e32 v3, v34, v66
	v_mov_b32_e32 v70, v69
	v_add_f32_e32 v3, v3, v58
	s_waitcnt lgkmcnt(0)
	v_pk_mul_f32 v[68:69], v[40:41], v[70:71]
	v_add_f32_e32 v3, v3, v59
	v_add_f32_e32 v3, v3, v68
	v_add_f32_e32 v3, v3, v69
	s_nop 1
	v_add_f32_dpp v3, v3, v3 quad_perm:[1,0,3,2] row_mask:0xf bank_mask:0xf
	s_nop 1
	v_add_f32_dpp v3, v3, v3 quad_perm:[2,3,0,1] row_mask:0xf bank_mask:0xf
	v_sub_f32_e32 v3, 0, v3
	v_cndmask_b32_e64 v41, v41, v3, s[46:47]
	ds_read2_b32 v[58:59], v7 offset0:128 offset1:132
	ds_read2_b32 v[60:61], v7 offset0:136 offset1:140
	ds_read2_b32 v[62:63], v7 offset0:144 offset1:148
	ds_read2_b32 v[64:65], v7 offset0:152 offset1:156
	ds_read2_b32 v[66:67], v7 offset0:160 offset1:164
	ds_read2_b32 v[68:69], v7 offset0:168 offset1:172
	ds_read_b32 v71, v56 offset:30400
	s_waitcnt lgkmcnt(6)
	v_fma_f32 v3, v58, v2, 0
	v_fmac_f32_e32 v3, v4, v59
	s_waitcnt lgkmcnt(5)
	v_fmac_f32_e32 v3, v6, v60
	v_fmac_f32_e32 v3, v8, v61
	s_waitcnt lgkmcnt(4)
	v_fmac_f32_e32 v3, v10, v62
	v_fmac_f32_e32 v3, v12, v63
	s_waitcnt lgkmcnt(3)
	v_fmac_f32_e32 v3, v14, v64
	v_mov_b32_e32 v37, v38
	s_waitcnt lgkmcnt(2)
	v_mov_b32_e32 v72, v67
	s_waitcnt lgkmcnt(1)
	v_mov_b32_e32 v73, v68
	v_fmac_f32_e32 v3, v16, v65
	v_pk_mul_f32 v[58:59], v[36:37], v[72:73]
	v_fmac_f32_e32 v3, v34, v66
	v_mov_b32_e32 v70, v69
	v_add_f32_e32 v3, v3, v58
	s_waitcnt lgkmcnt(0)
	v_pk_mul_f32 v[68:69], v[40:41], v[70:71]
	v_add_f32_e32 v3, v3, v59
	v_add_f32_e32 v3, v3, v68
	v_add_f32_e32 v3, v3, v69
	s_nop 1
	v_add_f32_dpp v3, v3, v3 quad_perm:[1,0,3,2] row_mask:0xf bank_mask:0xf
	s_nop 1
	v_add_f32_dpp v3, v3, v3 quad_perm:[2,3,0,1] row_mask:0xf bank_mask:0xf
	v_sub_f32_e32 v3, 0, v3
	v_cndmask_b32_e64 v41, v41, v3, s[44:45]
	ds_read2_b32 v[58:59], v7 offset0:192 offset1:196
	ds_read2_b32 v[60:61], v7 offset0:200 offset1:204
	ds_read2_b32 v[62:63], v7 offset0:208 offset1:212
	ds_read2_b32 v[64:65], v7 offset0:216 offset1:220
	ds_read2_b32 v[66:67], v7 offset0:224 offset1:228
	ds_read2_b32 v[68:69], v7 offset0:232 offset1:236
	ds_read_b32 v71, v56 offset:30656
	s_waitcnt lgkmcnt(6)
	v_fma_f32 v3, v58, v2, 0
	v_fmac_f32_e32 v3, v4, v59
	s_waitcnt lgkmcnt(5)
	v_fmac_f32_e32 v3, v6, v60
	v_fmac_f32_e32 v3, v8, v61
	s_waitcnt lgkmcnt(4)
	v_fmac_f32_e32 v3, v10, v62
	v_fmac_f32_e32 v3, v12, v63
	s_waitcnt lgkmcnt(3)
	v_fmac_f32_e32 v3, v14, v64
	v_mov_b32_e32 v37, v38
	s_waitcnt lgkmcnt(2)
	v_mov_b32_e32 v72, v67
	s_waitcnt lgkmcnt(1)
	v_mov_b32_e32 v73, v68
	v_fmac_f32_e32 v3, v16, v65
	v_pk_mul_f32 v[58:59], v[36:37], v[72:73]
	v_fmac_f32_e32 v3, v34, v66
	v_mov_b32_e32 v70, v69
	v_add_f32_e32 v3, v3, v58
	s_waitcnt lgkmcnt(0)
	v_pk_mul_f32 v[68:69], v[40:41], v[70:71]
	v_add_f32_e32 v3, v3, v59
	v_add_f32_e32 v3, v3, v68
	v_add_f32_e32 v3, v3, v69
	v_add_u32_e32 v7, 0x7800, v56
	s_waitcnt lgkmcnt(0)
	s_nop 1
	v_add_f32_dpp v3, v3, v3 quad_perm:[1,0,3,2] row_mask:0xf bank_mask:0xf
	s_nop 1
	v_add_f32_dpp v3, v3, v3 quad_perm:[2,3,0,1] row_mask:0xf bank_mask:0xf
	v_sub_f32_e32 v3, 0, v3
	v_cndmask_b32_e32 v42, v41, v3, vcc
	ds_read2_b32 v[58:59], v7 offset1:4
	ds_read2_b32 v[60:61], v7 offset0:8 offset1:12
	ds_read2_b32 v[62:63], v7 offset0:16 offset1:20
	ds_read2_b32 v[64:65], v7 offset0:24 offset1:28
	ds_read2_b32 v[66:67], v7 offset0:32 offset1:36
	ds_read2_b32 v[68:69], v7 offset0:40 offset1:44
	ds_read_b32 v71, v56 offset:30912
	s_waitcnt lgkmcnt(6)
	v_fma_f32 v3, v58, v2, 0
	v_fmac_f32_e32 v3, v4, v59
	s_waitcnt lgkmcnt(5)
	v_fmac_f32_e32 v3, v6, v60
	v_fmac_f32_e32 v3, v8, v61
	s_waitcnt lgkmcnt(4)
	v_fmac_f32_e32 v3, v10, v62
	v_fmac_f32_e32 v3, v12, v63
	s_waitcnt lgkmcnt(3)
	v_fmac_f32_e32 v3, v14, v64
	v_mov_b32_e32 v37, v38
	s_waitcnt lgkmcnt(2)
	v_mov_b32_e32 v72, v67
	s_waitcnt lgkmcnt(1)
	v_mov_b32_e32 v73, v68
	v_fmac_f32_e32 v3, v16, v65
	v_pk_mul_f32 v[58:59], v[36:37], v[72:73]
	v_fmac_f32_e32 v3, v34, v66
	v_mov_b32_e32 v41, v42
	v_mov_b32_e32 v70, v69
	v_add_f32_e32 v3, v3, v58
	s_waitcnt lgkmcnt(0)
	v_pk_mul_f32 v[68:69], v[40:41], v[70:71]
	v_add_f32_e32 v3, v3, v59
	v_add_f32_e32 v3, v3, v68
	v_add_f32_e32 v3, v3, v69
	s_nop 1
	v_add_f32_dpp v3, v3, v3 quad_perm:[1,0,3,2] row_mask:0xf bank_mask:0xf
	s_nop 1
	v_add_f32_dpp v3, v3, v3 quad_perm:[2,3,0,1] row_mask:0xf bank_mask:0xf
	v_sub_f32_e32 v3, 0, v3
	v_cndmask_b32_e64 v43, v43, v3, s[42:43]
	ds_read2_b32 v[58:59], v7 offset0:64 offset1:68
	ds_read2_b32 v[60:61], v7 offset0:72 offset1:76
	ds_read2_b32 v[62:63], v7 offset0:80 offset1:84
	ds_read2_b32 v[64:65], v7 offset0:88 offset1:92
	ds_read2_b32 v[66:67], v7 offset0:104 offset1:108
	ds_read2_b32 v[68:69], v7 offset0:112 offset1:116
	ds_read2_b32 v[70:71], v7 offset0:96 offset1:100
	s_waitcnt lgkmcnt(6)
	v_fma_f32 v3, v58, v2, 0
	v_fmac_f32_e32 v3, v4, v59
	s_waitcnt lgkmcnt(5)
	v_fmac_f32_e32 v3, v6, v60
	v_fmac_f32_e32 v3, v8, v61
	s_waitcnt lgkmcnt(4)
	v_fmac_f32_e32 v3, v10, v62
	v_fmac_f32_e32 v3, v12, v63
	s_waitcnt lgkmcnt(3)
	v_fmac_f32_e32 v3, v14, v64
	v_fmac_f32_e32 v3, v16, v65
	v_mov_b32_e32 v39, v40
	s_waitcnt lgkmcnt(0)
	v_fmac_f32_e32 v3, v34, v70
	v_pk_mul_f32 v[66:67], v[38:39], v[66:67]
	v_fmac_f32_e32 v3, v36, v71
	v_add_f32_e32 v3, v3, v66
	v_pk_mul_f32 v[68:69], v[42:43], v[68:69]
	v_add_f32_e32 v3, v3, v67
	v_add_f32_e32 v3, v3, v68
	v_add_f32_e32 v3, v3, v69
	s_nop 1
	v_add_f32_dpp v3, v3, v3 quad_perm:[1,0,3,2] row_mask:0xf bank_mask:0xf
	s_nop 1
	v_add_f32_dpp v3, v3, v3 quad_perm:[2,3,0,1] row_mask:0xf bank_mask:0xf
	v_sub_f32_e32 v3, 0, v3
	v_cndmask_b32_e64 v43, v43, v3, s[46:47]
	ds_read2_b32 v[58:59], v7 offset0:128 offset1:132
	ds_read2_b32 v[60:61], v7 offset0:136 offset1:140
	ds_read2_b32 v[62:63], v7 offset0:144 offset1:148
	ds_read2_b32 v[64:65], v7 offset0:152 offset1:156
	ds_read2_b32 v[66:67], v7 offset0:168 offset1:172
	ds_read2_b32 v[68:69], v7 offset0:176 offset1:180
	ds_read2_b32 v[70:71], v7 offset0:160 offset1:164
	s_waitcnt lgkmcnt(6)
; #define LAS __attribute__((address_space(3)))
; template <int W> __device__ __forceinline__ void dn_solve(const LAS float* Mf, float (&t)[16], int lane) {
;     const int j = 16 * W + (lane >> 2), q = lane & 3;
; #pragma unroll
;     for (int s = 0; s < 16; ++s) t[s] = 0.f;
; #pragma unroll
;     for (int i = 16 * W; i < 64; ++i) {
;         float acc = 0.f;
; #pragma unroll
;         for (int s = 4 * W; s <= (i - 1) / 4 && i > 16 * W; ++s) acc += Mf[i * 64 + 4 * s + q] * t[s];
;         acc += __shfl_xor(acc, 1); acc += __shfl_xor(acc, 2);
;         const float val = (i == j ? 1.f : 0.f) - acc;
;         if (q == (i & 3)) t[i >> 2] = val;
;         asm volatile("" : "+v"(t[0]), "+v"(t[1]), "+v"(t[2]), "+v"(t[3]), "+v"(t[4]), "+v"(t[5]), "+v"(t[6]), "+v"(t[7]), "+v"(t[8]), "+v"(t[9]), "+v"(t[10]), "+v"(t[11]), "+v"(t[12]), "+v"(t[13]), "+v"(t[14]), "+v"(t[15]));
;     }
; }
	v_fma_f32 v3, v58, v2, 0
	v_fmac_f32_e32 v3, v4, v59
	s_waitcnt lgkmcnt(5)
	v_fmac_f32_e32 v3, v6, v60
	v_fmac_f32_e32 v3, v8, v61
	s_waitcnt lgkmcnt(4)
	v_fmac_f32_e32 v3, v10, v62
	v_fmac_f32_e32 v3, v12, v63
	s_waitcnt lgkmcnt(3)
	v_fmac_f32_e32 v3, v14, v64
	v_fmac_f32_e32 v3, v16, v65
	v_mov_b32_e32 v39, v40
	s_waitcnt lgkmcnt(0)
	v_fmac_f32_e32 v3, v34, v70
	v_pk_mul_f32 v[66:67], v[38:39], v[66:67]
	v_fmac_f32_e32 v3, v36, v71
	v_add_f32_e32 v3, v3, v66
	v_pk_mul_f32 v[68:69], v[42:43], v[68:69]
	v_add_f32_e32 v3, v3, v67
	v_add_f32_e32 v3, v3, v68
	v_add_f32_e32 v3, v3, v69
	s_nop 1
	v_add_f32_dpp v3, v3, v3 quad_perm:[1,0,3,2] row_mask:0xf bank_mask:0xf
	s_nop 1
	v_add_f32_dpp v3, v3, v3 quad_perm:[2,3,0,1] row_mask:0xf bank_mask:0xf
	v_sub_f32_e32 v3, 0, v3
	v_cndmask_b32_e64 v43, v43, v3, s[44:45]
	ds_read2_b32 v[58:59], v7 offset0:192 offset1:196
	ds_read2_b32 v[60:61], v7 offset0:200 offset1:204
	ds_read2_b32 v[62:63], v7 offset0:208 offset1:212
	ds_read2_b32 v[64:65], v7 offset0:216 offset1:220
	ds_read2_b32 v[66:67], v7 offset0:232 offset1:236
	ds_read2_b32 v[68:69], v7 offset0:240 offset1:244
	ds_read2_b32 v[70:71], v7 offset0:224 offset1:228
	s_waitcnt lgkmcnt(6)
	v_fma_f32 v3, v58, v2, 0
	v_fmac_f32_e32 v3, v4, v59
	s_waitcnt lgkmcnt(5)
	v_fmac_f32_e32 v3, v6, v60
	v_fmac_f32_e32 v3, v8, v61
	s_waitcnt lgkmcnt(4)
	v_fmac_f32_e32 v3, v10, v62
	v_fmac_f32_e32 v3, v12, v63
	s_waitcnt lgkmcnt(3)
	v_fmac_f32_e32 v3, v14, v64
	v_fmac_f32_e32 v3, v16, v65
	v_mov_b32_e32 v39, v40
	s_waitcnt lgkmcnt(0)
	v_fmac_f32_e32 v3, v34, v70
	v_pk_mul_f32 v[66:67], v[38:39], v[66:67]
	v_fmac_f32_e32 v3, v36, v71
	v_add_f32_e32 v3, v3, v66
	v_pk_mul_f32 v[68:69], v[42:43], v[68:69]
	v_add_f32_e32 v3, v3, v67
	v_add_f32_e32 v3, v3, v68
	v_add_f32_e32 v3, v3, v69
	v_add_u32_e32 v7, 0x7c00, v56
	s_waitcnt lgkmcnt(0)
	s_nop 1
	v_add_f32_dpp v3, v3, v3 quad_perm:[1,0,3,2] row_mask:0xf bank_mask:0xf
	s_nop 1
	v_add_f32_dpp v3, v3, v3 quad_perm:[2,3,0,1] row_mask:0xf bank_mask:0xf
	v_sub_f32_e32 v3, 0, v3
	v_cndmask_b32_e32 v44, v43, v3, vcc
	ds_read2_b32 v[58:59], v7 offset1:4
	ds_read2_b32 v[60:61], v7 offset0:8 offset1:12
	ds_read2_b32 v[62:63], v7 offset0:16 offset1:20
	ds_read2_b32 v[64:65], v7 offset0:24 offset1:28
	ds_read2_b32 v[66:67], v7 offset0:32 offset1:36
	ds_read2_b32 v[68:69], v7 offset0:40 offset1:44
	ds_read2_b32 v[70:71], v7 offset0:48 offset1:52
	s_waitcnt lgkmcnt(6)
	v_fma_f32 v3, v58, v2, 0
	v_fmac_f32_e32 v3, v4, v59
	s_waitcnt lgkmcnt(5)
	v_fmac_f32_e32 v3, v6, v60
	v_fmac_f32_e32 v3, v8, v61
	s_waitcnt lgkmcnt(4)
	v_fmac_f32_e32 v3, v10, v62
	v_fmac_f32_e32 v3, v12, v63
	s_waitcnt lgkmcnt(3)
	v_fmac_f32_e32 v3, v14, v64
	v_fmac_f32_e32 v3, v16, v65
	v_mov_b32_e32 v39, v40
	s_waitcnt lgkmcnt(2)
	v_fmac_f32_e32 v3, v34, v66
	s_waitcnt lgkmcnt(1)
	v_pk_mul_f32 v[68:69], v[38:39], v[68:69]
	v_fmac_f32_e32 v3, v36, v67
	v_mov_b32_e32 v43, v44
	v_add_f32_e32 v3, v3, v68
	s_waitcnt lgkmcnt(0)
	v_pk_mul_f32 v[70:71], v[42:43], v[70:71]
	v_add_f32_e32 v3, v3, v69
	v_add_f32_e32 v3, v3, v70
	v_add_f32_e32 v3, v3, v71
	s_nop 1
	v_add_f32_dpp v3, v3, v3 quad_perm:[1,0,3,2] row_mask:0xf bank_mask:0xf
	s_nop 1
	v_add_f32_dpp v3, v3, v3 quad_perm:[2,3,0,1] row_mask:0xf bank_mask:0xf
	v_sub_f32_e32 v3, 0, v3
	v_cndmask_b32_e64 v45, v45, v3, s[42:43]
	ds_read2_b32 v[58:59], v7 offset0:64 offset1:68
	ds_read2_b32 v[60:61], v7 offset0:72 offset1:76
	ds_read2_b32 v[62:63], v7 offset0:80 offset1:84
	ds_read2_b32 v[64:65], v7 offset0:88 offset1:92
	ds_read2_b32 v[66:67], v7 offset0:96 offset1:100
	ds_read2_b32 v[68:69], v7 offset0:104 offset1:108
	ds_read2_b32 v[70:71], v7 offset0:112 offset1:116
	ds_read_b32 v73, v56 offset:32224
	s_waitcnt lgkmcnt(7)
	v_fma_f32 v3, v58, v2, 0
	v_fmac_f32_e32 v3, v4, v59
	s_waitcnt lgkmcnt(6)
	v_fmac_f32_e32 v3, v6, v60
	v_fmac_f32_e32 v3, v8, v61
	s_waitcnt lgkmcnt(5)
	v_fmac_f32_e32 v3, v10, v62
	v_fmac_f32_e32 v3, v12, v63
	s_waitcnt lgkmcnt(4)
	v_fmac_f32_e32 v3, v14, v64
	v_fmac_f32_e32 v3, v16, v65
	s_waitcnt lgkmcnt(3)
	v_fmac_f32_e32 v3, v34, v66
	v_mov_b32_e32 v41, v42
	s_waitcnt lgkmcnt(2)
	v_mov_b32_e32 v74, v69
	s_waitcnt lgkmcnt(1)
	v_mov_b32_e32 v75, v70
	v_fmac_f32_e32 v3, v36, v67
	v_pk_mul_f32 v[58:59], v[40:41], v[74:75]
	v_fmac_f32_e32 v3, v38, v68
	v_mov_b32_e32 v72, v71
	v_add_f32_e32 v3, v3, v58
	s_waitcnt lgkmcnt(0)
	v_pk_mul_f32 v[70:71], v[44:45], v[72:73]
	v_add_f32_e32 v3, v3, v59
	v_add_f32_e32 v3, v3, v70
	v_add_f32_e32 v3, v3, v71
	s_nop 1
	v_add_f32_dpp v3, v3, v3 quad_perm:[1,0,3,2] row_mask:0xf bank_mask:0xf
	s_nop 1
	v_add_f32_dpp v3, v3, v3 quad_perm:[2,3,0,1] row_mask:0xf bank_mask:0xf
	v_sub_f32_e32 v3, 0, v3
	v_cndmask_b32_e64 v45, v45, v3, s[46:47]
	ds_read2_b32 v[58:59], v7 offset0:128 offset1:132
	ds_read2_b32 v[60:61], v7 offset0:136 offset1:140
	ds_read2_b32 v[62:63], v7 offset0:144 offset1:148
	ds_read2_b32 v[64:65], v7 offset0:152 offset1:156
	ds_read2_b32 v[66:67], v7 offset0:160 offset1:164
	ds_read2_b32 v[68:69], v7 offset0:168 offset1:172
	ds_read2_b32 v[70:71], v7 offset0:176 offset1:180
	ds_read_b32 v73, v56 offset:32480
	s_waitcnt lgkmcnt(7)
	v_fma_f32 v3, v58, v2, 0
	v_fmac_f32_e32 v3, v4, v59
	s_waitcnt lgkmcnt(6)
	v_fmac_f32_e32 v3, v6, v60
	v_fmac_f32_e32 v3, v8, v61
	s_waitcnt lgkmcnt(5)
	v_fmac_f32_e32 v3, v10, v62
	v_fmac_f32_e32 v3, v12, v63
	s_waitcnt lgkmcnt(4)
	v_fmac_f32_e32 v3, v14, v64
	v_fmac_f32_e32 v3, v16, v65
	s_waitcnt lgkmcnt(3)
	v_fmac_f32_e32 v3, v34, v66
	v_mov_b32_e32 v41, v42
	s_waitcnt lgkmcnt(2)
	v_mov_b32_e32 v74, v69
	s_waitcnt lgkmcnt(1)
; #define LAS __attribute__((address_space(3)))
; template <int W> __device__ __forceinline__ void dn_solve(const LAS float* Mf, float (&t)[16], int lane) {
;     const int j = 16 * W + (lane >> 2), q = lane & 3;
; #pragma unroll
;     for (int s = 0; s < 16; ++s) t[s] = 0.f;
; #pragma unroll
;     for (int i = 16 * W; i < 64; ++i) {
;         float acc = 0.f;
; #pragma unroll
;         for (int s = 4 * W; s <= (i - 1) / 4 && i > 16 * W; ++s) acc += Mf[i * 64 + 4 * s + q] * t[s];
;         acc += __shfl_xor(acc, 1); acc += __shfl_xor(acc, 2);
;         const float val = (i == j ? 1.f : 0.f) - acc;
;         if (q == (i & 3)) t[i >> 2] = val;
;         asm volatile("" : "+v"(t[0]), "+v"(t[1]), "+v"(t[2]), "+v"(t[3]), "+v"(t[4]), "+v"(t[5]), "+v"(t[6]), "+v"(t[7]), "+v"(t[8]), "+v"(t[9]), "+v"(t[10]), "+v"(t[11]), "+v"(t[12]), "+v"(t[13]), "+v"(t[14]), "+v"(t[15]));
;     }
; }
	v_mov_b32_e32 v75, v70
	v_fmac_f32_e32 v3, v36, v67
	v_pk_mul_f32 v[58:59], v[40:41], v[74:75]
	v_fmac_f32_e32 v3, v38, v68
	v_mov_b32_e32 v72, v71
	v_add_f32_e32 v3, v3, v58
	s_waitcnt lgkmcnt(0)
	v_pk_mul_f32 v[70:71], v[44:45], v[72:73]
	v_add_f32_e32 v3, v3, v59
	v_add_f32_e32 v3, v3, v70
	v_add_f32_e32 v3, v3, v71
	s_nop 1
	v_add_f32_dpp v3, v3, v3 quad_perm:[1,0,3,2] row_mask:0xf bank_mask:0xf
	s_nop 1
	v_add_f32_dpp v3, v3, v3 quad_perm:[2,3,0,1] row_mask:0xf bank_mask:0xf
	v_sub_f32_e32 v3, 0, v3
	v_cndmask_b32_e64 v45, v45, v3, s[44:45]
	ds_read2_b32 v[58:59], v7 offset0:192 offset1:196
	ds_read2_b32 v[60:61], v7 offset0:200 offset1:204
	ds_read2_b32 v[62:63], v7 offset0:208 offset1:212
	ds_read2_b32 v[64:65], v7 offset0:216 offset1:220
	ds_read2_b32 v[66:67], v7 offset0:224 offset1:228
	ds_read2_b32 v[68:69], v7 offset0:232 offset1:236
	ds_read2_b32 v[70:71], v7 offset0:240 offset1:244
	ds_read_b32 v73, v56 offset:32736
	s_waitcnt lgkmcnt(7)
	v_fma_f32 v3, v58, v2, 0
	v_fmac_f32_e32 v3, v4, v59
	s_waitcnt lgkmcnt(6)
	v_fmac_f32_e32 v3, v6, v60
	v_fmac_f32_e32 v3, v8, v61
	s_waitcnt lgkmcnt(5)
	v_fmac_f32_e32 v3, v10, v62
	v_fmac_f32_e32 v3, v12, v63
	s_waitcnt lgkmcnt(4)
	v_fmac_f32_e32 v3, v14, v64
	v_fmac_f32_e32 v3, v16, v65
	s_waitcnt lgkmcnt(3)
	v_fmac_f32_e32 v3, v34, v66
	v_mov_b32_e32 v41, v42
	s_waitcnt lgkmcnt(2)
	v_mov_b32_e32 v74, v69
	s_waitcnt lgkmcnt(1)
	v_mov_b32_e32 v75, v70
	v_fmac_f32_e32 v3, v36, v67
	v_pk_mul_f32 v[58:59], v[40:41], v[74:75]
	v_fmac_f32_e32 v3, v38, v68
	v_mov_b32_e32 v72, v71
	v_add_f32_e32 v3, v3, v58
	s_waitcnt lgkmcnt(0)
	v_pk_mul_f32 v[70:71], v[44:45], v[72:73]
	v_add_f32_e32 v3, v3, v59
	v_add_f32_e32 v3, v3, v70
	v_add_f32_e32 v3, v3, v71
	v_add_u32_e32 v7, 0x8000, v56
	s_waitcnt lgkmcnt(0)
	s_nop 1
	v_add_f32_dpp v3, v3, v3 quad_perm:[1,0,3,2] row_mask:0xf bank_mask:0xf
	s_nop 1
	v_add_f32_dpp v3, v3, v3 quad_perm:[2,3,0,1] row_mask:0xf bank_mask:0xf
	v_sub_f32_e32 v3, 0, v3
	v_cndmask_b32_e32 v46, v45, v3, vcc
	ds_read2_b32 v[58:59], v7 offset1:4
	ds_read2_b32 v[60:61], v7 offset0:8 offset1:12
	ds_read2_b32 v[62:63], v7 offset0:16 offset1:20
	ds_read2_b32 v[64:65], v7 offset0:24 offset1:28
	ds_read2_b32 v[66:67], v7 offset0:32 offset1:36
	ds_read2_b32 v[68:69], v7 offset0:40 offset1:44
	ds_read2_b32 v[70:71], v7 offset0:48 offset1:52
	ds_read_b32 v73, v56 offset:32992
	s_waitcnt lgkmcnt(7)
	v_fma_f32 v3, v58, v2, 0
	v_fmac_f32_e32 v3, v4, v59
	s_waitcnt lgkmcnt(6)
	v_fmac_f32_e32 v3, v6, v60
	v_fmac_f32_e32 v3, v8, v61
	s_waitcnt lgkmcnt(5)
	v_fmac_f32_e32 v3, v10, v62
	v_fmac_f32_e32 v3, v12, v63
	s_waitcnt lgkmcnt(4)
	v_fmac_f32_e32 v3, v14, v64
	v_fmac_f32_e32 v3, v16, v65
	s_waitcnt lgkmcnt(3)
	v_fmac_f32_e32 v3, v34, v66
	v_mov_b32_e32 v41, v42
	s_waitcnt lgkmcnt(2)
	v_mov_b32_e32 v74, v69
	s_waitcnt lgkmcnt(1)
	v_mov_b32_e32 v75, v70
	v_fmac_f32_e32 v3, v36, v67
	v_pk_mul_f32 v[58:59], v[40:41], v[74:75]
	v_fmac_f32_e32 v3, v38, v68
	v_mov_b32_e32 v45, v46
	v_mov_b32_e32 v72, v71
	v_add_f32_e32 v3, v3, v58
	s_waitcnt lgkmcnt(0)
	v_pk_mul_f32 v[70:71], v[44:45], v[72:73]
	v_add_f32_e32 v3, v3, v59
	v_add_f32_e32 v3, v3, v70
	v_add_f32_e32 v3, v3, v71
	s_nop 1
	v_add_f32_dpp v3, v3, v3 quad_perm:[1,0,3,2] row_mask:0xf bank_mask:0xf
	s_nop 1
	v_add_f32_dpp v3, v3, v3 quad_perm:[2,3,0,1] row_mask:0xf bank_mask:0xf
	v_sub_f32_e32 v3, 0, v3
	v_cndmask_b32_e64 v47, v47, v3, s[42:43]
	ds_read2_b32 v[58:59], v7 offset0:64 offset1:68
	ds_read2_b32 v[60:61], v7 offset0:72 offset1:76
	ds_read2_b32 v[62:63], v7 offset0:80 offset1:84
	ds_read2_b32 v[64:65], v7 offset0:88 offset1:92
	ds_read2_b32 v[66:67], v7 offset0:96 offset1:100
	ds_read2_b32 v[68:69], v7 offset0:112 offset1:116
	ds_read2_b32 v[70:71], v7 offset0:120 offset1:124
	ds_read2_b32 v[72:73], v7 offset0:104 offset1:108
	s_waitcnt lgkmcnt(7)
	v_fma_f32 v3, v58, v2, 0
	v_fmac_f32_e32 v3, v4, v59
	s_waitcnt lgkmcnt(6)
	v_fmac_f32_e32 v3, v6, v60
	v_fmac_f32_e32 v3, v8, v61
	s_waitcnt lgkmcnt(5)
	v_fmac_f32_e32 v3, v10, v62
	v_fmac_f32_e32 v3, v12, v63
	s_waitcnt lgkmcnt(4)
	v_fmac_f32_e32 v3, v14, v64
	v_fmac_f32_e32 v3, v16, v65
	s_waitcnt lgkmcnt(3)
	v_fmac_f32_e32 v3, v34, v66
	v_fmac_f32_e32 v3, v36, v67
	v_mov_b32_e32 v43, v44
	s_waitcnt lgkmcnt(0)
	v_fmac_f32_e32 v3, v38, v72
	v_pk_mul_f32 v[68:69], v[42:43], v[68:69]
	v_fmac_f32_e32 v3, v40, v73
	v_add_f32_e32 v3, v3, v68
	v_pk_mul_f32 v[70:71], v[46:47], v[70:71]
	v_add_f32_e32 v3, v3, v69
	v_add_f32_e32 v3, v3, v70
	v_add_f32_e32 v3, v3, v71
	s_nop 1
	v_add_f32_dpp v3, v3, v3 quad_perm:[1,0,3,2] row_mask:0xf bank_mask:0xf
	s_nop 1
	v_add_f32_dpp v3, v3, v3 quad_perm:[2,3,0,1] row_mask:0xf bank_mask:0xf
	v_sub_f32_e32 v3, 0, v3
	v_cndmask_b32_e64 v47, v47, v3, s[46:47]
	ds_read2_b32 v[58:59], v7 offset0:128 offset1:132
	ds_read2_b32 v[60:61], v7 offset0:136 offset1:140
	ds_read2_b32 v[62:63], v7 offset0:144 offset1:148
	ds_read2_b32 v[64:65], v7 offset0:152 offset1:156
	ds_read2_b32 v[66:67], v7 offset0:160 offset1:164
	ds_read2_b32 v[68:69], v7 offset0:176 offset1:180
	ds_read2_b32 v[70:71], v7 offset0:184 offset1:188
	ds_read2_b32 v[72:73], v7 offset0:168 offset1:172
	s_waitcnt lgkmcnt(7)
	v_fma_f32 v3, v58, v2, 0
	v_fmac_f32_e32 v3, v4, v59
	s_waitcnt lgkmcnt(6)
	v_fmac_f32_e32 v3, v6, v60
	v_fmac_f32_e32 v3, v8, v61
	s_waitcnt lgkmcnt(5)
	v_fmac_f32_e32 v3, v10, v62
	v_fmac_f32_e32 v3, v12, v63
	s_waitcnt lgkmcnt(4)
	v_fmac_f32_e32 v3, v14, v64
	v_fmac_f32_e32 v3, v16, v65
	s_waitcnt lgkmcnt(3)
	v_fmac_f32_e32 v3, v34, v66
	v_fmac_f32_e32 v3, v36, v67
	v_mov_b32_e32 v43, v44
	s_waitcnt lgkmcnt(0)
; #define LAS __attribute__((address_space(3)))
; template <int W> __device__ __forceinline__ void dn_solve(const LAS float* Mf, float (&t)[16], int lane) {
;     const int j = 16 * W + (lane >> 2), q = lane & 3;
; #pragma unroll
;     for (int s = 0; s < 16; ++s) t[s] = 0.f;
; #pragma unroll
;     for (int i = 16 * W; i < 64; ++i) {
;         float acc = 0.f;
; #pragma unroll
;         for (int s = 4 * W; s <= (i - 1) / 4 && i > 16 * W; ++s) acc += Mf[i * 64 + 4 * s + q] * t[s];
;         acc += __shfl_xor(acc, 1); acc += __shfl_xor(acc, 2);
;         const float val = (i == j ? 1.f : 0.f) - acc;
;         if (q == (i & 3)) t[i >> 2] = val;
;         asm volatile("" : "+v"(t[0]), "+v"(t[1]), "+v"(t[2]), "+v"(t[3]), "+v"(t[4]), "+v"(t[5]), "+v"(t[6]), "+v"(t[7]), "+v"(t[8]), "+v"(t[9]), "+v"(t[10]), "+v"(t[11]), "+v"(t[12]), "+v"(t[13]), "+v"(t[14]), "+v"(t[15]));
;     }
; }
	v_fmac_f32_e32 v3, v38, v72
	v_pk_mul_f32 v[68:69], v[42:43], v[68:69]
	v_fmac_f32_e32 v3, v40, v73
	v_add_f32_e32 v3, v3, v68
	v_pk_mul_f32 v[70:71], v[46:47], v[70:71]
	v_add_f32_e32 v3, v3, v69
	v_add_f32_e32 v3, v3, v70
	v_add_f32_e32 v3, v3, v71
	s_nop 1
	v_add_f32_dpp v3, v3, v3 quad_perm:[1,0,3,2] row_mask:0xf bank_mask:0xf
	s_nop 1
	v_add_f32_dpp v3, v3, v3 quad_perm:[2,3,0,1] row_mask:0xf bank_mask:0xf
	v_sub_f32_e32 v3, 0, v3
	v_cndmask_b32_e64 v47, v47, v3, s[44:45]
	ds_read2_b32 v[58:59], v7 offset0:192 offset1:196
	ds_read2_b32 v[60:61], v7 offset0:200 offset1:204
	ds_read2_b32 v[62:63], v7 offset0:208 offset1:212
	ds_read2_b32 v[64:65], v7 offset0:216 offset1:220
	ds_read2_b32 v[66:67], v7 offset0:224 offset1:228
	ds_read2_b32 v[68:69], v7 offset0:232 offset1:236
	ds_read2_b32 v[70:71], v7 offset0:240 offset1:244
	ds_read2_b32 v[72:73], v7 offset0:248 offset1:252
	s_waitcnt lgkmcnt(7)
	v_fma_f32 v3, v58, v2, 0
	v_fmac_f32_e32 v3, v4, v59
	s_waitcnt lgkmcnt(6)
	v_fmac_f32_e32 v3, v6, v60
	v_fmac_f32_e32 v3, v8, v61
	s_waitcnt lgkmcnt(5)
	v_fmac_f32_e32 v3, v10, v62
	v_fmac_f32_e32 v3, v12, v63
	v_mov_b32_e32 v35, v36
	s_waitcnt lgkmcnt(4)
	v_fmac_f32_e32 v3, v14, v64
	s_waitcnt lgkmcnt(3)
	v_pk_mul_f32 v[66:67], v[34:35], v[66:67]
	v_fmac_f32_e32 v3, v16, v65
	v_mov_b32_e32 v39, v40
	v_add_f32_e32 v3, v3, v66
	s_waitcnt lgkmcnt(2)
	v_pk_mul_f32 v[68:69], v[38:39], v[68:69]
	v_add_f32_e32 v3, v3, v67
	v_mov_b32_e32 v43, v44
	v_add_f32_e32 v3, v3, v68
	s_waitcnt lgkmcnt(1)
	v_pk_mul_f32 v[70:71], v[42:43], v[70:71]
	v_add_f32_e32 v3, v3, v69
	v_add_f32_e32 v3, v3, v70
	s_waitcnt lgkmcnt(0)
	v_pk_mul_f32 v[72:73], v[46:47], v[72:73]
	v_add_f32_e32 v3, v3, v71
	v_add_f32_e32 v3, v3, v72
	v_add_f32_e32 v3, v3, v73
	s_nop 1
	v_add_f32_dpp v3, v3, v3 quad_perm:[1,0,3,2] row_mask:0xf bank_mask:0xf
	s_nop 1
	v_add_f32_dpp v3, v3, v3 quad_perm:[2,3,0,1] row_mask:0xf bank_mask:0xf
	v_sub_f32_e32 v3, 0, v3
	v_cndmask_b32_e32 v3, v47, v3, vcc
.LBB0_117:
	s_andn2_b64 vcc, exec, s[86:87]
	s_cbranch_vccnz .LBB0_119
	v_mov_b32_e32 v2, v1
	v_mov_b32_e32 v4, v1
	v_mov_b32_e32 v6, v1
	v_mov_b32_e32 v8, v1
	v_mov_b32_e32 v11, v1
	v_mov_b32_e32 v14, v1
	v_mov_b32_e32 v15, v1
	v_mov_b32_e32 v17, v1
	v_mov_b32_e32 v35, v1
	s_waitcnt lgkmcnt(14)
	v_mov_b32_e32 v37, v1
	v_mov_b32_e32 v39, v1
	v_mov_b32_e32 v9, v1
	v_mov_b32_e32 v7, v1
	v_mov_b32_e32 v5, v1
	v_mov_b32_e32 v3, v1
	ds_read_b32 v10, v56 offset:21824
	v_cmp_eq_u32_e32 vcc, 1, v53
	v_cmp_eq_u32_e64 s[46:47], 1, v52
	v_cmp_eq_u32_e64 s[44:45], 2, v52
	v_cndmask_b32_e64 v13, 0, 1.0, vcc
	s_waitcnt lgkmcnt(0)
	v_fma_f32 v10, v10, v57, 0
	v_cmp_eq_u32_e32 vcc, 2, v53
	v_cmp_eq_u32_e64 s[0:1], 4, v53
	v_add_u32_e32 v34, 0x5800, v56
	v_cndmask_b32_e64 v16, 0, 1.0, vcc
	s_waitcnt lgkmcnt(0)
	s_nop 1
	v_add_f32_dpp v10, v10, v10 quad_perm:[1,0,3,2] row_mask:0xf bank_mask:0xf
	v_cmp_eq_u32_e32 vcc, 3, v53
	v_add_u32_e32 v36, 0x6800, v56
	v_add_u32_e32 v38, 0x6c00, v56
	s_waitcnt lgkmcnt(0)
	s_nop 1
	v_add_f32_dpp v10, v10, v10 quad_perm:[2,3,0,1] row_mask:0xf bank_mask:0xf
	v_sub_f32_e32 v10, v13, v10
	v_cndmask_b32_e64 v10, v57, v10, s[46:47]
	ds_read_b32 v12, v56 offset:22080
	s_waitcnt lgkmcnt(0)
	v_fma_f32 v12, v12, v10, 0
	s_nop 1
	v_add_f32_dpp v12, v12, v12 quad_perm:[1,0,3,2] row_mask:0xf bank_mask:0xf
	s_nop 1
	v_add_f32_dpp v12, v12, v12 quad_perm:[2,3,0,1] row_mask:0xf bank_mask:0xf
	v_sub_f32_e32 v12, v16, v12
	v_cndmask_b32_e64 v10, v10, v12, s[44:45]
	ds_read_b32 v12, v56 offset:22336
	v_cndmask_b32_e64 v16, 0, 1.0, vcc
	v_cmp_eq_u32_e32 vcc, 3, v52
	s_waitcnt lgkmcnt(0)
	v_fma_f32 v12, v12, v10, 0
	s_nop 1
	v_add_f32_dpp v12, v12, v12 quad_perm:[1,0,3,2] row_mask:0xf bank_mask:0xf
	s_nop 1
	v_add_f32_dpp v12, v12, v12 quad_perm:[2,3,0,1] row_mask:0xf bank_mask:0xf
	v_sub_f32_e32 v12, v16, v12
	v_cndmask_b32_e32 v10, v10, v12, vcc
	ds_read_b32 v12, v56 offset:22592
	v_cndmask_b32_e64 v16, 0, 1.0, s[0:1]
	v_cmp_eq_u32_e64 s[0:1], 5, v53
	s_waitcnt lgkmcnt(0)
	v_fma_f32 v12, v12, v10, 0
	s_nop 1
	v_add_f32_dpp v12, v12, v12 quad_perm:[1,0,3,2] row_mask:0xf bank_mask:0xf
	s_waitcnt lgkmcnt(0)
	s_nop 1
	v_add_f32_dpp v12, v12, v12 quad_perm:[2,3,0,1] row_mask:0xf bank_mask:0xf
	v_sub_f32_e32 v12, v16, v12
	v_cndmask_b32_e64 v11, v11, v12, s[42:43]
	ds_read2_b32 v[12:13], v34 offset0:80 offset1:84
	v_cndmask_b32_e64 v16, 0, 1.0, s[0:1]
	v_cmp_eq_u32_e64 s[0:1], 6, v53
	s_waitcnt lgkmcnt(0)
	v_pk_mul_f32 v[12:13], v[12:13], v[10:11]
	s_nop 0
	v_add_f32_e32 v12, 0, v12
	v_add_f32_e32 v12, v12, v13
	s_nop 1
	v_add_f32_dpp v12, v12, v12 quad_perm:[1,0,3,2] row_mask:0xf bank_mask:0xf
	s_waitcnt lgkmcnt(0)
	s_nop 1
	v_add_f32_dpp v12, v12, v12 quad_perm:[2,3,0,1] row_mask:0xf bank_mask:0xf
	v_sub_f32_e32 v12, v16, v12
	v_cndmask_b32_e64 v11, v11, v12, s[46:47]
	ds_read2_b32 v[12:13], v34 offset0:144 offset1:148
	v_cndmask_b32_e64 v16, 0, 1.0, s[0:1]
	v_cmp_eq_u32_e64 s[0:1], 7, v53
	s_waitcnt lgkmcnt(0)
	v_pk_mul_f32 v[12:13], v[12:13], v[10:11]
	s_nop 0
	v_add_f32_e32 v12, 0, v12
	v_add_f32_e32 v12, v12, v13
	s_nop 1
	v_add_f32_dpp v12, v12, v12 quad_perm:[1,0,3,2] row_mask:0xf bank_mask:0xf
	s_waitcnt lgkmcnt(0)
	s_nop 1
	v_add_f32_dpp v12, v12, v12 quad_perm:[2,3,0,1] row_mask:0xf bank_mask:0xf
	v_sub_f32_e32 v12, v16, v12
	v_cndmask_b32_e64 v11, v11, v12, s[44:45]
	ds_read2_b32 v[12:13], v34 offset0:208 offset1:212
	v_cndmask_b32_e64 v16, 0, 1.0, s[0:1]
	v_add_u32_e32 v34, 0x5c00, v56
	v_cmp_eq_u32_e64 s[0:1], 8, v53
	s_waitcnt lgkmcnt(0)
; #define LAS __attribute__((address_space(3)))
; template <int W> __device__ __forceinline__ void dn_solve(const LAS float* Mf, float (&t)[16], int lane) {
;     const int j = 16 * W + (lane >> 2), q = lane & 3;
; #pragma unroll
;     for (int s = 0; s < 16; ++s) t[s] = 0.f;
; #pragma unroll
;     for (int i = 16 * W; i < 64; ++i) {
;         float acc = 0.f;
; #pragma unroll
;         for (int s = 4 * W; s <= (i - 1) / 4 && i > 16 * W; ++s) acc += Mf[i * 64 + 4 * s + q] * t[s];
;         acc += __shfl_xor(acc, 1); acc += __shfl_xor(acc, 2);
;         const float val = (i == j ? 1.f : 0.f) - acc;
;         if (q == (i & 3)) t[i >> 2] = val;
;         asm volatile("" : "+v"(t[0]), "+v"(t[1]), "+v"(t[2]), "+v"(t[3]), "+v"(t[4]), "+v"(t[5]), "+v"(t[6]), "+v"(t[7]), "+v"(t[8]), "+v"(t[9]), "+v"(t[10]), "+v"(t[11]), "+v"(t[12]), "+v"(t[13]), "+v"(t[14]), "+v"(t[15]));
;     }
; }
	v_pk_mul_f32 v[12:13], v[12:13], v[10:11]
	s_nop 0
	v_add_f32_e32 v12, 0, v12
	v_add_f32_e32 v12, v12, v13
	s_nop 1
	v_add_f32_dpp v12, v12, v12 quad_perm:[1,0,3,2] row_mask:0xf bank_mask:0xf
	s_nop 1
	v_add_f32_dpp v12, v12, v12 quad_perm:[2,3,0,1] row_mask:0xf bank_mask:0xf
	v_sub_f32_e32 v12, v16, v12
	v_cndmask_b32_e32 v12, v11, v12, vcc
	ds_read2_b32 v[40:41], v34 offset0:16 offset1:20
	v_mov_b32_e32 v11, v12
	v_cndmask_b32_e64 v16, 0, 1.0, s[0:1]
	v_cmp_eq_u32_e64 s[0:1], 9, v53
	s_waitcnt lgkmcnt(0)
	v_pk_mul_f32 v[40:41], v[40:41], v[10:11]
	s_nop 0
	v_add_f32_e32 v11, 0, v40
	v_add_f32_e32 v11, v11, v41
	s_nop 1
	v_add_f32_dpp v11, v11, v11 quad_perm:[1,0,3,2] row_mask:0xf bank_mask:0xf
	s_nop 1
	v_add_f32_dpp v11, v11, v11 quad_perm:[2,3,0,1] row_mask:0xf bank_mask:0xf
	v_sub_f32_e32 v11, v16, v11
	v_cndmask_b32_e64 v13, v14, v11, s[42:43]
	ds_read2_b32 v[40:41], v34 offset0:80 offset1:84
	ds_read_b32 v43, v56 offset:23904
	v_cndmask_b32_e64 v16, 0, 1.0, s[0:1]
	v_cmp_eq_u32_e64 s[0:1], 10, v53
	s_waitcnt lgkmcnt(1)
	v_mov_b32_e32 v42, v41
	v_fma_f32 v11, v40, v10, 0
	s_waitcnt lgkmcnt(0)
	v_pk_mul_f32 v[40:41], v[12:13], v[42:43]
	s_nop 0
	v_add_f32_e32 v11, v11, v40
	v_add_f32_e32 v11, v11, v41
	s_nop 1
	v_add_f32_dpp v11, v11, v11 quad_perm:[1,0,3,2] row_mask:0xf bank_mask:0xf
	s_nop 1
	v_add_f32_dpp v11, v11, v11 quad_perm:[2,3,0,1] row_mask:0xf bank_mask:0xf
	v_sub_f32_e32 v11, v16, v11
	v_cndmask_b32_e64 v13, v13, v11, s[46:47]
	ds_read2_b32 v[40:41], v34 offset0:144 offset1:148
	ds_read_b32 v43, v56 offset:24160
	v_cndmask_b32_e64 v16, 0, 1.0, s[0:1]
	v_cmp_eq_u32_e64 s[0:1], 11, v53
	s_waitcnt lgkmcnt(1)
	v_mov_b32_e32 v42, v41
	v_fma_f32 v11, v40, v10, 0
	s_waitcnt lgkmcnt(0)
	v_pk_mul_f32 v[40:41], v[12:13], v[42:43]
	s_nop 0
	v_add_f32_e32 v11, v11, v40
	v_add_f32_e32 v11, v11, v41
	s_nop 1
	v_add_f32_dpp v11, v11, v11 quad_perm:[1,0,3,2] row_mask:0xf bank_mask:0xf
	s_nop 1
	v_add_f32_dpp v11, v11, v11 quad_perm:[2,3,0,1] row_mask:0xf bank_mask:0xf
	v_sub_f32_e32 v11, v16, v11
	v_cndmask_b32_e64 v13, v13, v11, s[44:45]
	ds_read2_b32 v[40:41], v34 offset0:208 offset1:212
	ds_read_b32 v43, v56 offset:24416
	v_cndmask_b32_e64 v16, 0, 1.0, s[0:1]
	v_add_u32_e32 v34, 0x6000, v56
	v_cmp_eq_u32_e64 s[0:1], 12, v53
	s_waitcnt lgkmcnt(1)
	v_mov_b32_e32 v42, v41
	v_fma_f32 v11, v40, v10, 0
	s_waitcnt lgkmcnt(0)
	v_pk_mul_f32 v[40:41], v[12:13], v[42:43]
	s_nop 0
	v_add_f32_e32 v11, v11, v40
	v_add_f32_e32 v11, v11, v41
	s_nop 1
	v_add_f32_dpp v11, v11, v11 quad_perm:[1,0,3,2] row_mask:0xf bank_mask:0xf
	s_nop 1
	v_add_f32_dpp v11, v11, v11 quad_perm:[2,3,0,1] row_mask:0xf bank_mask:0xf
	v_sub_f32_e32 v11, v16, v11
	v_cndmask_b32_e32 v14, v13, v11, vcc
	ds_read2_b32 v[40:41], v34 offset0:16 offset1:20
	ds_read_b32 v43, v56 offset:24672
	v_mov_b32_e32 v13, v14
	v_cndmask_b32_e64 v16, 0, 1.0, s[0:1]
	v_cmp_eq_u32_e64 s[0:1], 13, v53
	s_waitcnt lgkmcnt(1)
	v_mov_b32_e32 v42, v41
	v_fma_f32 v11, v40, v10, 0
	s_waitcnt lgkmcnt(0)
	v_pk_mul_f32 v[40:41], v[12:13], v[42:43]
	s_nop 0
	v_add_f32_e32 v11, v11, v40
	v_add_f32_e32 v11, v11, v41
	s_nop 1
	v_add_f32_dpp v11, v11, v11 quad_perm:[1,0,3,2] row_mask:0xf bank_mask:0xf
	s_nop 1
	v_add_f32_dpp v11, v11, v11 quad_perm:[2,3,0,1] row_mask:0xf bank_mask:0xf
	v_sub_f32_e32 v11, v16, v11
	v_cndmask_b32_e64 v15, v15, v11, s[42:43]
	ds_read2_b32 v[40:41], v34 offset0:80 offset1:84
	ds_read2_b32 v[42:43], v34 offset0:88 offset1:92
	v_mov_b32_e32 v11, v12
	v_cndmask_b32_e64 v16, 0, 1.0, s[0:1]
	v_cmp_eq_u32_e64 s[0:1], 14, v53
	s_waitcnt lgkmcnt(1)
	v_pk_mul_f32 v[40:41], v[40:41], v[10:11]
	s_waitcnt lgkmcnt(0)
	v_pk_mul_f32 v[42:43], v[14:15], v[42:43]
	v_add_f32_e32 v11, 0, v40
	v_add_f32_e32 v11, v11, v41
	v_add_f32_e32 v11, v11, v42
	v_add_f32_e32 v11, v11, v43
	s_nop 1
	v_add_f32_dpp v11, v11, v11 quad_perm:[1,0,3,2] row_mask:0xf bank_mask:0xf
	s_nop 1
	v_add_f32_dpp v11, v11, v11 quad_perm:[2,3,0,1] row_mask:0xf bank_mask:0xf
	v_sub_f32_e32 v11, v16, v11
	v_cndmask_b32_e64 v15, v15, v11, s[46:47]
	ds_read2_b32 v[40:41], v34 offset0:144 offset1:148
	ds_read2_b32 v[42:43], v34 offset0:152 offset1:156
	v_mov_b32_e32 v11, v12
	v_cndmask_b32_e64 v16, 0, 1.0, s[0:1]
	v_cmp_eq_u32_e64 s[0:1], 15, v53
	s_waitcnt lgkmcnt(1)
	v_pk_mul_f32 v[40:41], v[40:41], v[10:11]
	s_waitcnt lgkmcnt(0)
	v_pk_mul_f32 v[42:43], v[14:15], v[42:43]
	v_add_f32_e32 v11, 0, v40
	v_add_f32_e32 v11, v11, v41
	v_add_f32_e32 v11, v11, v42
	v_add_f32_e32 v11, v11, v43
	s_nop 1
	v_add_f32_dpp v11, v11, v11 quad_perm:[1,0,3,2] row_mask:0xf bank_mask:0xf
	s_nop 1
	v_add_f32_dpp v11, v11, v11 quad_perm:[2,3,0,1] row_mask:0xf bank_mask:0xf
	v_sub_f32_e32 v11, v16, v11
	v_cndmask_b32_e64 v15, v15, v11, s[44:45]
	ds_read2_b32 v[40:41], v34 offset0:208 offset1:212
	ds_read2_b32 v[42:43], v34 offset0:216 offset1:220
	v_mov_b32_e32 v11, v12
	v_cndmask_b32_e64 v16, 0, 1.0, s[0:1]
	v_add_u32_e32 v34, 0x6400, v56
	s_waitcnt lgkmcnt(1)
	v_pk_mul_f32 v[40:41], v[40:41], v[10:11]
	s_waitcnt lgkmcnt(0)
	v_pk_mul_f32 v[42:43], v[14:15], v[42:43]
	v_add_f32_e32 v11, 0, v40
	v_add_f32_e32 v11, v11, v41
	v_add_f32_e32 v11, v11, v42
	v_add_f32_e32 v11, v11, v43
	s_nop 1
	v_add_f32_dpp v11, v11, v11 quad_perm:[1,0,3,2] row_mask:0xf bank_mask:0xf
	s_nop 1
	v_add_f32_dpp v11, v11, v11 quad_perm:[2,3,0,1] row_mask:0xf bank_mask:0xf
	v_sub_f32_e32 v11, v16, v11
	v_cndmask_b32_e32 v16, v15, v11, vcc
	ds_read2_b32 v[40:41], v34 offset0:16 offset1:20
	ds_read2_b32 v[42:43], v34 offset0:24 offset1:28
	v_mov_b32_e32 v11, v12
	v_mov_b32_e32 v15, v16
	s_waitcnt lgkmcnt(1)
	v_pk_mul_f32 v[40:41], v[40:41], v[10:11]
	s_nop 0
	v_add_f32_e32 v11, 0, v40
	s_waitcnt lgkmcnt(0)
; #define LAS __attribute__((address_space(3)))
; template <int W> __device__ __forceinline__ void dn_solve(const LAS float* Mf, float (&t)[16], int lane) {
;     const int j = 16 * W + (lane >> 2), q = lane & 3;
; #pragma unroll
;     for (int s = 0; s < 16; ++s) t[s] = 0.f;
; #pragma unroll
;     for (int i = 16 * W; i < 64; ++i) {
;         float acc = 0.f;
; #pragma unroll
;         for (int s = 4 * W; s <= (i - 1) / 4 && i > 16 * W; ++s) acc += Mf[i * 64 + 4 * s + q] * t[s];
;         acc += __shfl_xor(acc, 1); acc += __shfl_xor(acc, 2);
;         const float val = (i == j ? 1.f : 0.f) - acc;
;         if (q == (i & 3)) t[i >> 2] = val;
;         asm volatile("" : "+v"(t[0]), "+v"(t[1]), "+v"(t[2]), "+v"(t[3]), "+v"(t[4]), "+v"(t[5]), "+v"(t[6]), "+v"(t[7]), "+v"(t[8]), "+v"(t[9]), "+v"(t[10]), "+v"(t[11]), "+v"(t[12]), "+v"(t[13]), "+v"(t[14]), "+v"(t[15]));
;     }
; }
	v_pk_mul_f32 v[42:43], v[14:15], v[42:43]
	v_add_f32_e32 v11, v11, v41
	v_add_f32_e32 v11, v11, v42
	v_add_f32_e32 v11, v11, v43
	s_nop 1
	v_add_f32_dpp v11, v11, v11 quad_perm:[1,0,3,2] row_mask:0xf bank_mask:0xf
	s_nop 1
	v_add_f32_dpp v11, v11, v11 quad_perm:[2,3,0,1] row_mask:0xf bank_mask:0xf
	v_sub_f32_e32 v11, 0, v11
	v_cndmask_b32_e64 v17, v17, v11, s[42:43]
	ds_read2_b32 v[40:41], v34 offset0:80 offset1:84
	ds_read2_b32 v[42:43], v34 offset0:88 offset1:92
	ds_read_b32 v45, v56 offset:25984
	v_mov_b32_e32 v13, v14
	s_waitcnt lgkmcnt(2)
	v_fma_f32 v11, v40, v10, 0
	v_mov_b32_e32 v40, v41
	s_waitcnt lgkmcnt(1)
	v_mov_b32_e32 v41, v42
	v_pk_mul_f32 v[40:41], v[12:13], v[40:41]
	v_mov_b32_e32 v44, v43
	v_add_f32_e32 v11, v11, v40
	s_waitcnt lgkmcnt(0)
	v_pk_mul_f32 v[42:43], v[16:17], v[44:45]
	v_add_f32_e32 v11, v11, v41
	v_add_f32_e32 v11, v11, v42
	v_add_f32_e32 v11, v11, v43
	s_nop 1
	v_add_f32_dpp v11, v11, v11 quad_perm:[1,0,3,2] row_mask:0xf bank_mask:0xf
	s_nop 1
	v_add_f32_dpp v11, v11, v11 quad_perm:[2,3,0,1] row_mask:0xf bank_mask:0xf
	v_sub_f32_e32 v11, 0, v11
	v_cndmask_b32_e64 v17, v17, v11, s[46:47]
	ds_read2_b32 v[40:41], v34 offset0:144 offset1:148
	ds_read2_b32 v[42:43], v34 offset0:152 offset1:156
	ds_read_b32 v45, v56 offset:26240
	v_mov_b32_e32 v13, v14
	s_waitcnt lgkmcnt(2)
	v_fma_f32 v11, v40, v10, 0
	v_mov_b32_e32 v40, v41
	s_waitcnt lgkmcnt(1)
	v_mov_b32_e32 v41, v42
	v_pk_mul_f32 v[40:41], v[12:13], v[40:41]
	v_mov_b32_e32 v44, v43
	v_add_f32_e32 v11, v11, v40
	s_waitcnt lgkmcnt(0)
	v_pk_mul_f32 v[42:43], v[16:17], v[44:45]
	v_add_f32_e32 v11, v11, v41
	v_add_f32_e32 v11, v11, v42
	v_add_f32_e32 v11, v11, v43
	s_nop 1
	v_add_f32_dpp v11, v11, v11 quad_perm:[1,0,3,2] row_mask:0xf bank_mask:0xf
	s_nop 1
	v_add_f32_dpp v11, v11, v11 quad_perm:[2,3,0,1] row_mask:0xf bank_mask:0xf
	v_sub_f32_e32 v11, 0, v11
	v_cndmask_b32_e64 v17, v17, v11, s[44:45]
	ds_read2_b32 v[40:41], v34 offset0:208 offset1:212
	ds_read2_b32 v[42:43], v34 offset0:216 offset1:220
	ds_read_b32 v45, v56 offset:26496
	v_mov_b32_e32 v13, v14
	s_waitcnt lgkmcnt(2)
	v_fma_f32 v11, v40, v10, 0
	v_mov_b32_e32 v40, v41
	s_waitcnt lgkmcnt(1)
	v_mov_b32_e32 v41, v42
	v_pk_mul_f32 v[40:41], v[12:13], v[40:41]
	v_mov_b32_e32 v44, v43
	v_add_f32_e32 v11, v11, v40
	s_waitcnt lgkmcnt(0)
	v_pk_mul_f32 v[42:43], v[16:17], v[44:45]
	v_add_f32_e32 v11, v11, v41
	v_add_f32_e32 v11, v11, v42
	v_add_f32_e32 v11, v11, v43
	s_nop 1
	v_add_f32_dpp v11, v11, v11 quad_perm:[1,0,3,2] row_mask:0xf bank_mask:0xf
	s_nop 1
	v_add_f32_dpp v11, v11, v11 quad_perm:[2,3,0,1] row_mask:0xf bank_mask:0xf
	v_sub_f32_e32 v11, 0, v11
	v_cndmask_b32_e32 v34, v17, v11, vcc
	ds_read2_b32 v[40:41], v36 offset0:16 offset1:20
	ds_read2_b32 v[42:43], v36 offset0:24 offset1:28
	ds_read_b32 v45, v56 offset:26752
	v_mov_b32_e32 v13, v14
	v_mov_b32_e32 v17, v34
	s_waitcnt lgkmcnt(2)
	v_fma_f32 v11, v40, v10, 0
	v_mov_b32_e32 v40, v41
	s_waitcnt lgkmcnt(1)
	v_mov_b32_e32 v41, v42
	v_pk_mul_f32 v[40:41], v[12:13], v[40:41]
	v_mov_b32_e32 v44, v43
	v_add_f32_e32 v11, v11, v40
	s_waitcnt lgkmcnt(0)
	v_pk_mul_f32 v[42:43], v[16:17], v[44:45]
	v_add_f32_e32 v11, v11, v41
	v_add_f32_e32 v11, v11, v42
	v_add_f32_e32 v11, v11, v43
	s_nop 1
	v_add_f32_dpp v11, v11, v11 quad_perm:[1,0,3,2] row_mask:0xf bank_mask:0xf
	s_nop 1
	v_add_f32_dpp v11, v11, v11 quad_perm:[2,3,0,1] row_mask:0xf bank_mask:0xf
	v_sub_f32_e32 v11, 0, v11
	v_cndmask_b32_e64 v35, v35, v11, s[42:43]
	ds_read2_b32 v[40:41], v36 offset0:80 offset1:84
	ds_read2_b32 v[42:43], v36 offset0:88 offset1:92
	ds_read2_b32 v[44:45], v36 offset0:96 offset1:100
	v_mov_b32_e32 v15, v16
	s_waitcnt lgkmcnt(2)
	v_fma_f32 v11, v40, v10, 0
	s_waitcnt lgkmcnt(1)
	v_pk_mul_f32 v[42:43], v[14:15], v[42:43]
	v_fmac_f32_e32 v11, v12, v41
	v_add_f32_e32 v11, v11, v42
	s_waitcnt lgkmcnt(0)
	v_pk_mul_f32 v[44:45], v[34:35], v[44:45]
	v_add_f32_e32 v11, v11, v43
	v_add_f32_e32 v11, v11, v44
	v_add_f32_e32 v11, v11, v45
	s_nop 1
	v_add_f32_dpp v11, v11, v11 quad_perm:[1,0,3,2] row_mask:0xf bank_mask:0xf
	s_nop 1
	v_add_f32_dpp v11, v11, v11 quad_perm:[2,3,0,1] row_mask:0xf bank_mask:0xf
	v_sub_f32_e32 v11, 0, v11
	v_cndmask_b32_e64 v35, v35, v11, s[46:47]
	ds_read2_b32 v[40:41], v36 offset0:144 offset1:148
	ds_read2_b32 v[42:43], v36 offset0:152 offset1:156
	ds_read2_b32 v[44:45], v36 offset0:160 offset1:164
	v_mov_b32_e32 v15, v16
	s_waitcnt lgkmcnt(2)
	v_fma_f32 v11, v40, v10, 0
	s_waitcnt lgkmcnt(1)
	v_pk_mul_f32 v[42:43], v[14:15], v[42:43]
	v_fmac_f32_e32 v11, v12, v41
	v_add_f32_e32 v11, v11, v42
	s_waitcnt lgkmcnt(0)
	v_pk_mul_f32 v[44:45], v[34:35], v[44:45]
	v_add_f32_e32 v11, v11, v43
	v_add_f32_e32 v11, v11, v44
	v_add_f32_e32 v11, v11, v45
	s_nop 1
	v_add_f32_dpp v11, v11, v11 quad_perm:[1,0,3,2] row_mask:0xf bank_mask:0xf
	s_nop 1
	v_add_f32_dpp v11, v11, v11 quad_perm:[2,3,0,1] row_mask:0xf bank_mask:0xf
	v_sub_f32_e32 v11, 0, v11
	v_cndmask_b32_e64 v35, v35, v11, s[44:45]
	ds_read2_b32 v[40:41], v36 offset0:208 offset1:212
	ds_read2_b32 v[42:43], v36 offset0:216 offset1:220
	ds_read2_b32 v[44:45], v36 offset0:224 offset1:228
	v_mov_b32_e32 v15, v16
	s_waitcnt lgkmcnt(2)
	v_fma_f32 v11, v40, v10, 0
	s_waitcnt lgkmcnt(1)
	v_pk_mul_f32 v[42:43], v[14:15], v[42:43]
	v_fmac_f32_e32 v11, v12, v41
	v_add_f32_e32 v11, v11, v42
	s_waitcnt lgkmcnt(0)
	v_pk_mul_f32 v[44:45], v[34:35], v[44:45]
	v_add_f32_e32 v11, v11, v43
	v_add_f32_e32 v11, v11, v44
	v_add_f32_e32 v11, v11, v45
	s_nop 1
	v_add_f32_dpp v11, v11, v11 quad_perm:[1,0,3,2] row_mask:0xf bank_mask:0xf
	s_nop 1
	v_add_f32_dpp v11, v11, v11 quad_perm:[2,3,0,1] row_mask:0xf bank_mask:0xf
	v_sub_f32_e32 v11, 0, v11
	v_cndmask_b32_e32 v36, v35, v11, vcc
	ds_read2_b32 v[40:41], v38 offset0:16 offset1:20
	ds_read2_b32 v[42:43], v38 offset0:24 offset1:28
	ds_read2_b32 v[44:45], v38 offset0:32 offset1:36
	v_mov_b32_e32 v15, v16
	v_mov_b32_e32 v35, v36
	s_waitcnt lgkmcnt(2)
; #define LAS __attribute__((address_space(3)))
; template <int W> __device__ __forceinline__ void dn_solve(const LAS float* Mf, float (&t)[16], int lane) {
;     const int j = 16 * W + (lane >> 2), q = lane & 3;
; #pragma unroll
;     for (int s = 0; s < 16; ++s) t[s] = 0.f;
; #pragma unroll
;     for (int i = 16 * W; i < 64; ++i) {
;         float acc = 0.f;
; #pragma unroll
;         for (int s = 4 * W; s <= (i - 1) / 4 && i > 16 * W; ++s) acc += Mf[i * 64 + 4 * s + q] * t[s];
;         acc += __shfl_xor(acc, 1); acc += __shfl_xor(acc, 2);
;         const float val = (i == j ? 1.f : 0.f) - acc;
;         if (q == (i & 3)) t[i >> 2] = val;
;         asm volatile("" : "+v"(t[0]), "+v"(t[1]), "+v"(t[2]), "+v"(t[3]), "+v"(t[4]), "+v"(t[5]), "+v"(t[6]), "+v"(t[7]), "+v"(t[8]), "+v"(t[9]), "+v"(t[10]), "+v"(t[11]), "+v"(t[12]), "+v"(t[13]), "+v"(t[14]), "+v"(t[15]));
;     }
; }
	v_fma_f32 v11, v40, v10, 0
	s_waitcnt lgkmcnt(1)
	v_pk_mul_f32 v[42:43], v[14:15], v[42:43]
	v_fmac_f32_e32 v11, v12, v41
	v_add_f32_e32 v11, v11, v42
	s_waitcnt lgkmcnt(0)
	v_pk_mul_f32 v[44:45], v[34:35], v[44:45]
	v_add_f32_e32 v11, v11, v43
	v_add_f32_e32 v11, v11, v44
	v_add_f32_e32 v11, v11, v45
	v_add_u32_e32 v15, 0x7000, v56
	s_waitcnt lgkmcnt(0)
	s_nop 1
	v_add_f32_dpp v11, v11, v11 quad_perm:[1,0,3,2] row_mask:0xf bank_mask:0xf
	s_nop 1
	v_add_f32_dpp v11, v11, v11 quad_perm:[2,3,0,1] row_mask:0xf bank_mask:0xf
	v_sub_f32_e32 v11, 0, v11
	v_cndmask_b32_e64 v37, v37, v11, s[42:43]
	ds_read2_b32 v[40:41], v38 offset0:80 offset1:84
	ds_read2_b32 v[42:43], v38 offset0:88 offset1:92
	ds_read2_b32 v[44:45], v38 offset0:96 offset1:100
	ds_read_b32 v47, v56 offset:28064
	v_mov_b32_e32 v17, v34
	s_waitcnt lgkmcnt(3)
	v_fma_f32 v11, v40, v10, 0
	s_waitcnt lgkmcnt(2)
	v_mov_b32_e32 v58, v43
	s_waitcnt lgkmcnt(1)
	v_mov_b32_e32 v59, v44
	v_fmac_f32_e32 v11, v12, v41
	v_pk_mul_f32 v[40:41], v[16:17], v[58:59]
	v_fmac_f32_e32 v11, v14, v42
	v_mov_b32_e32 v46, v45
	v_add_f32_e32 v11, v11, v40
	s_waitcnt lgkmcnt(0)
	v_pk_mul_f32 v[44:45], v[36:37], v[46:47]
	v_add_f32_e32 v11, v11, v41
	v_add_f32_e32 v11, v11, v44
	v_add_f32_e32 v11, v11, v45
	s_nop 1
	v_add_f32_dpp v11, v11, v11 quad_perm:[1,0,3,2] row_mask:0xf bank_mask:0xf
	s_nop 1
	v_add_f32_dpp v11, v11, v11 quad_perm:[2,3,0,1] row_mask:0xf bank_mask:0xf
	v_sub_f32_e32 v11, 0, v11
	v_cndmask_b32_e64 v37, v37, v11, s[46:47]
	ds_read2_b32 v[40:41], v38 offset0:144 offset1:148
	ds_read2_b32 v[42:43], v38 offset0:152 offset1:156
	ds_read2_b32 v[44:45], v38 offset0:160 offset1:164
	ds_read_b32 v47, v56 offset:28320
	v_mov_b32_e32 v17, v34
	s_waitcnt lgkmcnt(3)
	v_fma_f32 v11, v40, v10, 0
	s_waitcnt lgkmcnt(2)
	v_mov_b32_e32 v58, v43
	s_waitcnt lgkmcnt(1)
	v_mov_b32_e32 v59, v44
	v_fmac_f32_e32 v11, v12, v41
	v_pk_mul_f32 v[40:41], v[16:17], v[58:59]
	v_fmac_f32_e32 v11, v14, v42
	v_mov_b32_e32 v46, v45
	v_add_f32_e32 v11, v11, v40
	s_waitcnt lgkmcnt(0)
	v_pk_mul_f32 v[44:45], v[36:37], v[46:47]
	v_add_f32_e32 v11, v11, v41
	v_add_f32_e32 v11, v11, v44
	v_add_f32_e32 v11, v11, v45
	s_nop 1
	v_add_f32_dpp v11, v11, v11 quad_perm:[1,0,3,2] row_mask:0xf bank_mask:0xf
	s_nop 1
	v_add_f32_dpp v11, v11, v11 quad_perm:[2,3,0,1] row_mask:0xf bank_mask:0xf
	v_sub_f32_e32 v11, 0, v11
	v_cndmask_b32_e64 v37, v37, v11, s[44:45]
	ds_read2_b32 v[40:41], v38 offset0:208 offset1:212
	ds_read2_b32 v[42:43], v38 offset0:216 offset1:220
	ds_read2_b32 v[44:45], v38 offset0:224 offset1:228
	ds_read_b32 v47, v56 offset:28576
	v_mov_b32_e32 v17, v34
	s_waitcnt lgkmcnt(3)
	v_fma_f32 v11, v40, v10, 0
	s_waitcnt lgkmcnt(2)
	v_mov_b32_e32 v58, v43
	s_waitcnt lgkmcnt(1)
	v_mov_b32_e32 v59, v44
	v_fmac_f32_e32 v11, v12, v41
	v_pk_mul_f32 v[40:41], v[16:17], v[58:59]
	v_fmac_f32_e32 v11, v14, v42
	v_mov_b32_e32 v46, v45
	v_add_f32_e32 v11, v11, v40
	s_waitcnt lgkmcnt(0)
	v_pk_mul_f32 v[44:45], v[36:37], v[46:47]
	v_add_f32_e32 v11, v11, v41
	v_add_f32_e32 v11, v11, v44
	v_add_f32_e32 v11, v11, v45
	s_nop 1
	v_add_f32_dpp v11, v11, v11 quad_perm:[1,0,3,2] row_mask:0xf bank_mask:0xf
	s_nop 1
	v_add_f32_dpp v11, v11, v11 quad_perm:[2,3,0,1] row_mask:0xf bank_mask:0xf
	v_sub_f32_e32 v11, 0, v11
	v_cndmask_b32_e32 v38, v37, v11, vcc
	ds_read2_b32 v[40:41], v15 offset0:16 offset1:20
	ds_read2_b32 v[42:43], v15 offset0:24 offset1:28
	ds_read2_b32 v[44:45], v15 offset0:32 offset1:36
	ds_read_b32 v47, v56 offset:28832
	v_mov_b32_e32 v17, v34
	s_waitcnt lgkmcnt(3)
	v_fma_f32 v11, v40, v10, 0
	s_waitcnt lgkmcnt(2)
	v_mov_b32_e32 v58, v43
	s_waitcnt lgkmcnt(1)
	v_mov_b32_e32 v59, v44
	v_fmac_f32_e32 v11, v12, v41
	v_pk_mul_f32 v[40:41], v[16:17], v[58:59]
	v_fmac_f32_e32 v11, v14, v42
	v_mov_b32_e32 v37, v38
	v_mov_b32_e32 v46, v45
	v_add_f32_e32 v11, v11, v40
	s_waitcnt lgkmcnt(0)
	v_pk_mul_f32 v[44:45], v[36:37], v[46:47]
	v_add_f32_e32 v11, v11, v41
	v_add_f32_e32 v11, v11, v44
	v_add_f32_e32 v11, v11, v45
	s_nop 1
	v_add_f32_dpp v11, v11, v11 quad_perm:[1,0,3,2] row_mask:0xf bank_mask:0xf
	s_nop 1
	v_add_f32_dpp v11, v11, v11 quad_perm:[2,3,0,1] row_mask:0xf bank_mask:0xf
	v_sub_f32_e32 v11, 0, v11
	v_cndmask_b32_e64 v39, v39, v11, s[42:43]
	ds_read2_b32 v[40:41], v15 offset0:80 offset1:84
	ds_read2_b32 v[42:43], v15 offset0:96 offset1:100
	ds_read2_b32 v[44:45], v15 offset0:104 offset1:108
	ds_read2_b32 v[46:47], v15 offset0:88 offset1:92
	v_mov_b32_e32 v35, v36
	s_waitcnt lgkmcnt(3)
	v_fma_f32 v11, v40, v10, 0
	v_fmac_f32_e32 v11, v12, v41
	s_waitcnt lgkmcnt(2)
	v_pk_mul_f32 v[42:43], v[34:35], v[42:43]
	s_waitcnt lgkmcnt(0)
	v_fmac_f32_e32 v11, v14, v46
	v_fmac_f32_e32 v11, v16, v47
	v_add_f32_e32 v11, v11, v42
	v_pk_mul_f32 v[44:45], v[38:39], v[44:45]
	v_add_f32_e32 v11, v11, v43
	v_add_f32_e32 v11, v11, v44
	v_add_f32_e32 v11, v11, v45
	s_nop 1
	v_add_f32_dpp v11, v11, v11 quad_perm:[1,0,3,2] row_mask:0xf bank_mask:0xf
	s_nop 1
	v_add_f32_dpp v11, v11, v11 quad_perm:[2,3,0,1] row_mask:0xf bank_mask:0xf
	v_sub_f32_e32 v11, 0, v11
	v_cndmask_b32_e64 v39, v39, v11, s[46:47]
	ds_read2_b32 v[40:41], v15 offset0:144 offset1:148
	ds_read2_b32 v[42:43], v15 offset0:160 offset1:164
	ds_read2_b32 v[44:45], v15 offset0:168 offset1:172
	ds_read2_b32 v[46:47], v15 offset0:152 offset1:156
	v_mov_b32_e32 v35, v36
	s_waitcnt lgkmcnt(3)
	v_fma_f32 v11, v40, v10, 0
	v_fmac_f32_e32 v11, v12, v41
	s_waitcnt lgkmcnt(2)
	v_pk_mul_f32 v[42:43], v[34:35], v[42:43]
	s_waitcnt lgkmcnt(0)
; #define LAS __attribute__((address_space(3)))
; template <int W> __device__ __forceinline__ void dn_solve(const LAS float* Mf, float (&t)[16], int lane) {
;     const int j = 16 * W + (lane >> 2), q = lane & 3;
; #pragma unroll
;     for (int s = 0; s < 16; ++s) t[s] = 0.f;
; #pragma unroll
;     for (int i = 16 * W; i < 64; ++i) {
;         float acc = 0.f;
; #pragma unroll
;         for (int s = 4 * W; s <= (i - 1) / 4 && i > 16 * W; ++s) acc += Mf[i * 64 + 4 * s + q] * t[s];
;         acc += __shfl_xor(acc, 1); acc += __shfl_xor(acc, 2);
;         const float val = (i == j ? 1.f : 0.f) - acc;
;         if (q == (i & 3)) t[i >> 2] = val;
;         asm volatile("" : "+v"(t[0]), "+v"(t[1]), "+v"(t[2]), "+v"(t[3]), "+v"(t[4]), "+v"(t[5]), "+v"(t[6]), "+v"(t[7]), "+v"(t[8]), "+v"(t[9]), "+v"(t[10]), "+v"(t[11]), "+v"(t[12]), "+v"(t[13]), "+v"(t[14]), "+v"(t[15]));
;     }
; }
	v_fmac_f32_e32 v11, v14, v46
	v_fmac_f32_e32 v11, v16, v47
	v_add_f32_e32 v11, v11, v42
	v_pk_mul_f32 v[44:45], v[38:39], v[44:45]
	v_add_f32_e32 v11, v11, v43
	v_add_f32_e32 v11, v11, v44
	v_add_f32_e32 v11, v11, v45
	s_nop 1
	v_add_f32_dpp v11, v11, v11 quad_perm:[1,0,3,2] row_mask:0xf bank_mask:0xf
	s_nop 1
	v_add_f32_dpp v11, v11, v11 quad_perm:[2,3,0,1] row_mask:0xf bank_mask:0xf
	v_sub_f32_e32 v11, 0, v11
	v_cndmask_b32_e64 v39, v39, v11, s[44:45]
	ds_read2_b32 v[40:41], v15 offset0:208 offset1:212
	ds_read2_b32 v[42:43], v15 offset0:224 offset1:228
	ds_read2_b32 v[44:45], v15 offset0:232 offset1:236
	ds_read2_b32 v[46:47], v15 offset0:216 offset1:220
	v_mov_b32_e32 v35, v36
	s_waitcnt lgkmcnt(3)
	v_fma_f32 v11, v40, v10, 0
	v_fmac_f32_e32 v11, v12, v41
	s_waitcnt lgkmcnt(2)
	v_pk_mul_f32 v[42:43], v[34:35], v[42:43]
	s_waitcnt lgkmcnt(0)
	v_fmac_f32_e32 v11, v14, v46
	v_fmac_f32_e32 v11, v16, v47
	v_add_f32_e32 v11, v11, v42
	v_pk_mul_f32 v[44:45], v[38:39], v[44:45]
	v_add_f32_e32 v11, v11, v43
	v_add_f32_e32 v11, v11, v44
	v_add_f32_e32 v11, v11, v45
	v_add_u32_e32 v15, 0x7400, v56
	s_waitcnt lgkmcnt(0)
	s_nop 1
	v_add_f32_dpp v11, v11, v11 quad_perm:[1,0,3,2] row_mask:0xf bank_mask:0xf
	s_nop 1
	v_add_f32_dpp v11, v11, v11 quad_perm:[2,3,0,1] row_mask:0xf bank_mask:0xf
	v_sub_f32_e32 v11, 0, v11
	v_cndmask_b32_e32 v40, v39, v11, vcc
	ds_read2_b32 v[42:43], v15 offset0:16 offset1:20
	ds_read2_b32 v[44:45], v15 offset0:24 offset1:28
	ds_read2_b32 v[46:47], v15 offset0:32 offset1:36
	ds_read2_b32 v[58:59], v15 offset0:40 offset1:44
	v_mov_b32_e32 v35, v36
	s_waitcnt lgkmcnt(3)
	v_fma_f32 v11, v42, v10, 0
	v_fmac_f32_e32 v11, v12, v43
	s_waitcnt lgkmcnt(2)
	v_fmac_f32_e32 v11, v14, v44
	s_waitcnt lgkmcnt(1)
	v_pk_mul_f32 v[46:47], v[34:35], v[46:47]
	v_fmac_f32_e32 v11, v16, v45
	v_mov_b32_e32 v39, v40
	v_add_f32_e32 v11, v11, v46
	s_waitcnt lgkmcnt(0)
	v_pk_mul_f32 v[58:59], v[38:39], v[58:59]
	v_add_f32_e32 v11, v11, v47
	v_add_f32_e32 v11, v11, v58
	v_add_f32_e32 v11, v11, v59
	s_nop 1
	v_add_f32_dpp v11, v11, v11 quad_perm:[1,0,3,2] row_mask:0xf bank_mask:0xf
	s_nop 1
	v_add_f32_dpp v11, v11, v11 quad_perm:[2,3,0,1] row_mask:0xf bank_mask:0xf
	v_sub_f32_e32 v11, 0, v11
	v_cndmask_b32_e64 v41, v9, v11, s[42:43]
	ds_read2_b32 v[42:43], v15 offset0:80 offset1:84
	ds_read2_b32 v[44:45], v15 offset0:88 offset1:92
	ds_read2_b32 v[46:47], v15 offset0:96 offset1:100
	ds_read2_b32 v[58:59], v15 offset0:104 offset1:108
	ds_read_b32 v61, v56 offset:30144
	s_waitcnt lgkmcnt(4)
	v_fma_f32 v9, v42, v10, 0
	v_fmac_f32_e32 v9, v12, v43
	s_waitcnt lgkmcnt(3)
	v_fmac_f32_e32 v9, v14, v44
	v_mov_b32_e32 v37, v38
	s_waitcnt lgkmcnt(2)
	v_mov_b32_e32 v62, v47
	s_waitcnt lgkmcnt(1)
	v_mov_b32_e32 v63, v58
	v_fmac_f32_e32 v9, v16, v45
	v_pk_mul_f32 v[42:43], v[36:37], v[62:63]
	v_fmac_f32_e32 v9, v34, v46
	v_mov_b32_e32 v60, v59
	v_add_f32_e32 v9, v9, v42
	s_waitcnt lgkmcnt(0)
	v_pk_mul_f32 v[58:59], v[40:41], v[60:61]
	v_add_f32_e32 v9, v9, v43
	v_add_f32_e32 v9, v9, v58
	v_add_f32_e32 v9, v9, v59
	v_add_u32_e32 v13, 0x7800, v56
	s_waitcnt lgkmcnt(0)
	s_nop 1
	v_add_f32_dpp v9, v9, v9 quad_perm:[1,0,3,2] row_mask:0xf bank_mask:0xf
	s_nop 1
	v_add_f32_dpp v9, v9, v9 quad_perm:[2,3,0,1] row_mask:0xf bank_mask:0xf
	v_sub_f32_e32 v9, 0, v9
	v_cndmask_b32_e64 v41, v41, v9, s[46:47]
	ds_read2_b32 v[42:43], v15 offset0:144 offset1:148
	ds_read2_b32 v[44:45], v15 offset0:152 offset1:156
	ds_read2_b32 v[46:47], v15 offset0:160 offset1:164
	ds_read2_b32 v[58:59], v15 offset0:168 offset1:172
	ds_read_b32 v61, v56 offset:30400
	s_waitcnt lgkmcnt(4)
	v_fma_f32 v9, v42, v10, 0
	v_fmac_f32_e32 v9, v12, v43
	s_waitcnt lgkmcnt(3)
	v_fmac_f32_e32 v9, v14, v44
	v_mov_b32_e32 v37, v38
	s_waitcnt lgkmcnt(2)
	v_mov_b32_e32 v62, v47
	s_waitcnt lgkmcnt(1)
	v_mov_b32_e32 v63, v58
	v_fmac_f32_e32 v9, v16, v45
	v_pk_mul_f32 v[42:43], v[36:37], v[62:63]
	v_fmac_f32_e32 v9, v34, v46
	v_mov_b32_e32 v60, v59
	v_add_f32_e32 v9, v9, v42
	s_waitcnt lgkmcnt(0)
	v_pk_mul_f32 v[58:59], v[40:41], v[60:61]
	v_add_f32_e32 v9, v9, v43
	v_add_f32_e32 v9, v9, v58
	v_add_f32_e32 v9, v9, v59
	s_nop 1
	v_add_f32_dpp v9, v9, v9 quad_perm:[1,0,3,2] row_mask:0xf bank_mask:0xf
	s_nop 1
	v_add_f32_dpp v9, v9, v9 quad_perm:[2,3,0,1] row_mask:0xf bank_mask:0xf
	v_sub_f32_e32 v9, 0, v9
	v_cndmask_b32_e64 v41, v41, v9, s[44:45]
	ds_read2_b32 v[42:43], v15 offset0:208 offset1:212
	ds_read2_b32 v[44:45], v15 offset0:216 offset1:220
	ds_read2_b32 v[46:47], v15 offset0:224 offset1:228
	ds_read2_b32 v[58:59], v15 offset0:232 offset1:236
	ds_read_b32 v61, v56 offset:30656
	s_waitcnt lgkmcnt(4)
	v_fma_f32 v9, v42, v10, 0
	v_fmac_f32_e32 v9, v12, v43
	s_waitcnt lgkmcnt(3)
	v_fmac_f32_e32 v9, v14, v44
	v_mov_b32_e32 v37, v38
	s_waitcnt lgkmcnt(2)
	v_mov_b32_e32 v62, v47
	s_waitcnt lgkmcnt(1)
	v_mov_b32_e32 v63, v58
	v_fmac_f32_e32 v9, v16, v45
	v_pk_mul_f32 v[42:43], v[36:37], v[62:63]
	v_fmac_f32_e32 v9, v34, v46
	v_mov_b32_e32 v60, v59
	v_add_f32_e32 v9, v9, v42
	s_waitcnt lgkmcnt(0)
	v_pk_mul_f32 v[58:59], v[40:41], v[60:61]
	v_add_f32_e32 v9, v9, v43
	v_add_f32_e32 v9, v9, v58
	v_add_f32_e32 v9, v9, v59
	s_nop 1
	v_add_f32_dpp v9, v9, v9 quad_perm:[1,0,3,2] row_mask:0xf bank_mask:0xf
	s_nop 1
	v_add_f32_dpp v9, v9, v9 quad_perm:[2,3,0,1] row_mask:0xf bank_mask:0xf
	v_sub_f32_e32 v9, 0, v9
	v_cndmask_b32_e32 v42, v41, v9, vcc
	ds_read2_b32 v[44:45], v13 offset0:16 offset1:20
	ds_read2_b32 v[46:47], v13 offset0:24 offset1:28
	ds_read2_b32 v[58:59], v13 offset0:32 offset1:36
	ds_read2_b32 v[60:61], v13 offset0:40 offset1:44
	ds_read_b32 v63, v56 offset:30912
	s_waitcnt lgkmcnt(4)
; #define LAS __attribute__((address_space(3)))
; template <int W> __device__ __forceinline__ void dn_solve(const LAS float* Mf, float (&t)[16], int lane) {
;     const int j = 16 * W + (lane >> 2), q = lane & 3;
; #pragma unroll
;     for (int s = 0; s < 16; ++s) t[s] = 0.f;
; #pragma unroll
;     for (int i = 16 * W; i < 64; ++i) {
;         float acc = 0.f;
; #pragma unroll
;         for (int s = 4 * W; s <= (i - 1) / 4 && i > 16 * W; ++s) acc += Mf[i * 64 + 4 * s + q] * t[s];
;         acc += __shfl_xor(acc, 1); acc += __shfl_xor(acc, 2);
;         const float val = (i == j ? 1.f : 0.f) - acc;
;         if (q == (i & 3)) t[i >> 2] = val;
;         asm volatile("" : "+v"(t[0]), "+v"(t[1]), "+v"(t[2]), "+v"(t[3]), "+v"(t[4]), "+v"(t[5]), "+v"(t[6]), "+v"(t[7]), "+v"(t[8]), "+v"(t[9]), "+v"(t[10]), "+v"(t[11]), "+v"(t[12]), "+v"(t[13]), "+v"(t[14]), "+v"(t[15]));
;     }
; }
	v_fma_f32 v9, v44, v10, 0
	v_fmac_f32_e32 v9, v12, v45
	s_waitcnt lgkmcnt(3)
	v_fmac_f32_e32 v9, v14, v46
	v_mov_b32_e32 v37, v38
	s_waitcnt lgkmcnt(2)
	v_mov_b32_e32 v64, v59
	s_waitcnt lgkmcnt(1)
	v_mov_b32_e32 v65, v60
	v_fmac_f32_e32 v9, v16, v47
	v_pk_mul_f32 v[44:45], v[36:37], v[64:65]
	v_fmac_f32_e32 v9, v34, v58
	v_mov_b32_e32 v41, v42
	v_mov_b32_e32 v62, v61
	v_add_f32_e32 v9, v9, v44
	s_waitcnt lgkmcnt(0)
	v_pk_mul_f32 v[60:61], v[40:41], v[62:63]
	v_add_f32_e32 v9, v9, v45
	v_add_f32_e32 v9, v9, v60
	v_add_f32_e32 v9, v9, v61
	s_nop 1
	v_add_f32_dpp v9, v9, v9 quad_perm:[1,0,3,2] row_mask:0xf bank_mask:0xf
	s_nop 1
	v_add_f32_dpp v9, v9, v9 quad_perm:[2,3,0,1] row_mask:0xf bank_mask:0xf
	v_sub_f32_e32 v9, 0, v9
	v_cndmask_b32_e64 v43, v7, v9, s[42:43]
	ds_read2_b32 v[44:45], v13 offset0:80 offset1:84
	ds_read2_b32 v[46:47], v13 offset0:88 offset1:92
	ds_read2_b32 v[58:59], v13 offset0:104 offset1:108
	ds_read2_b32 v[60:61], v13 offset0:112 offset1:116
	ds_read2_b32 v[62:63], v13 offset0:96 offset1:100
	s_waitcnt lgkmcnt(4)
	v_fma_f32 v7, v44, v10, 0
	v_fmac_f32_e32 v7, v12, v45
	s_waitcnt lgkmcnt(3)
	v_fmac_f32_e32 v7, v14, v46
	v_fmac_f32_e32 v7, v16, v47
	v_mov_b32_e32 v39, v40
	s_waitcnt lgkmcnt(0)
	v_fmac_f32_e32 v7, v34, v62
	v_pk_mul_f32 v[58:59], v[38:39], v[58:59]
	v_fmac_f32_e32 v7, v36, v63
	v_add_f32_e32 v7, v7, v58
	v_pk_mul_f32 v[60:61], v[42:43], v[60:61]
	v_add_f32_e32 v7, v7, v59
	v_add_f32_e32 v7, v7, v60
	v_add_f32_e32 v7, v7, v61
	v_add_u32_e32 v11, 0x7c00, v56
	s_waitcnt lgkmcnt(0)
	s_nop 1
	v_add_f32_dpp v7, v7, v7 quad_perm:[1,0,3,2] row_mask:0xf bank_mask:0xf
	s_nop 1
	v_add_f32_dpp v7, v7, v7 quad_perm:[2,3,0,1] row_mask:0xf bank_mask:0xf
	v_sub_f32_e32 v7, 0, v7
	v_cndmask_b32_e64 v43, v43, v7, s[46:47]
	ds_read2_b32 v[44:45], v13 offset0:144 offset1:148
	ds_read2_b32 v[46:47], v13 offset0:152 offset1:156
	ds_read2_b32 v[58:59], v13 offset0:168 offset1:172
	ds_read2_b32 v[60:61], v13 offset0:176 offset1:180
	ds_read2_b32 v[62:63], v13 offset0:160 offset1:164
	s_waitcnt lgkmcnt(4)
	v_fma_f32 v7, v44, v10, 0
	v_fmac_f32_e32 v7, v12, v45
	s_waitcnt lgkmcnt(3)
	v_fmac_f32_e32 v7, v14, v46
	v_fmac_f32_e32 v7, v16, v47
	v_mov_b32_e32 v39, v40
	s_waitcnt lgkmcnt(0)
	v_fmac_f32_e32 v7, v34, v62
	v_pk_mul_f32 v[58:59], v[38:39], v[58:59]
	v_fmac_f32_e32 v7, v36, v63
	v_add_f32_e32 v7, v7, v58
	v_pk_mul_f32 v[60:61], v[42:43], v[60:61]
	v_add_f32_e32 v7, v7, v59
	v_add_f32_e32 v7, v7, v60
	v_add_f32_e32 v7, v7, v61
	s_nop 1
	v_add_f32_dpp v7, v7, v7 quad_perm:[1,0,3,2] row_mask:0xf bank_mask:0xf
	s_nop 1
	v_add_f32_dpp v7, v7, v7 quad_perm:[2,3,0,1] row_mask:0xf bank_mask:0xf
	v_sub_f32_e32 v7, 0, v7
	v_cndmask_b32_e64 v43, v43, v7, s[44:45]
	ds_read2_b32 v[44:45], v13 offset0:208 offset1:212
	ds_read2_b32 v[46:47], v13 offset0:216 offset1:220
	ds_read2_b32 v[58:59], v13 offset0:232 offset1:236
	ds_read2_b32 v[60:61], v13 offset0:240 offset1:244
	ds_read2_b32 v[62:63], v13 offset0:224 offset1:228
	s_waitcnt lgkmcnt(4)
	v_fma_f32 v7, v44, v10, 0
	v_fmac_f32_e32 v7, v12, v45
	s_waitcnt lgkmcnt(3)
	v_fmac_f32_e32 v7, v14, v46
	v_fmac_f32_e32 v7, v16, v47
	v_mov_b32_e32 v39, v40
	s_waitcnt lgkmcnt(0)
	v_fmac_f32_e32 v7, v34, v62
	v_pk_mul_f32 v[58:59], v[38:39], v[58:59]
	v_fmac_f32_e32 v7, v36, v63
	v_add_f32_e32 v7, v7, v58
	v_pk_mul_f32 v[60:61], v[42:43], v[60:61]
	v_add_f32_e32 v7, v7, v59
	v_add_f32_e32 v7, v7, v60
	v_add_f32_e32 v7, v7, v61
	s_nop 1
	v_add_f32_dpp v7, v7, v7 quad_perm:[1,0,3,2] row_mask:0xf bank_mask:0xf
	s_nop 1
	v_add_f32_dpp v7, v7, v7 quad_perm:[2,3,0,1] row_mask:0xf bank_mask:0xf
	v_sub_f32_e32 v7, 0, v7
	v_cndmask_b32_e32 v44, v43, v7, vcc
	ds_read2_b32 v[46:47], v11 offset0:16 offset1:20
	ds_read2_b32 v[58:59], v11 offset0:24 offset1:28
	ds_read2_b32 v[60:61], v11 offset0:32 offset1:36
	ds_read2_b32 v[62:63], v11 offset0:40 offset1:44
	ds_read2_b32 v[64:65], v11 offset0:48 offset1:52
	s_waitcnt lgkmcnt(4)
	v_fma_f32 v7, v46, v10, 0
	v_fmac_f32_e32 v7, v12, v47
	s_waitcnt lgkmcnt(3)
	v_fmac_f32_e32 v7, v14, v58
	v_fmac_f32_e32 v7, v16, v59
	v_mov_b32_e32 v39, v40
	s_waitcnt lgkmcnt(2)
	v_fmac_f32_e32 v7, v34, v60
	s_waitcnt lgkmcnt(1)
	v_pk_mul_f32 v[62:63], v[38:39], v[62:63]
	v_fmac_f32_e32 v7, v36, v61
	v_mov_b32_e32 v43, v44
	v_add_f32_e32 v7, v7, v62
	s_waitcnt lgkmcnt(0)
	v_pk_mul_f32 v[64:65], v[42:43], v[64:65]
	v_add_f32_e32 v7, v7, v63
	v_add_f32_e32 v7, v7, v64
	v_add_f32_e32 v7, v7, v65
	s_nop 1
	v_add_f32_dpp v7, v7, v7 quad_perm:[1,0,3,2] row_mask:0xf bank_mask:0xf
	s_nop 1
	v_add_f32_dpp v7, v7, v7 quad_perm:[2,3,0,1] row_mask:0xf bank_mask:0xf
	v_sub_f32_e32 v7, 0, v7
	v_cndmask_b32_e64 v45, v5, v7, s[42:43]
	ds_read2_b32 v[46:47], v11 offset0:80 offset1:84
	ds_read2_b32 v[58:59], v11 offset0:88 offset1:92
	ds_read2_b32 v[60:61], v11 offset0:96 offset1:100
	ds_read2_b32 v[62:63], v11 offset0:104 offset1:108
	ds_read2_b32 v[64:65], v11 offset0:112 offset1:116
	ds_read_b32 v67, v56 offset:32224
	s_waitcnt lgkmcnt(5)
	v_fma_f32 v5, v46, v10, 0
	v_fmac_f32_e32 v5, v12, v47
	s_waitcnt lgkmcnt(4)
	v_fmac_f32_e32 v5, v14, v58
	v_fmac_f32_e32 v5, v16, v59
	s_waitcnt lgkmcnt(3)
	v_fmac_f32_e32 v5, v34, v60
	v_mov_b32_e32 v41, v42
	s_waitcnt lgkmcnt(2)
	v_mov_b32_e32 v68, v63
	s_waitcnt lgkmcnt(1)
	v_mov_b32_e32 v69, v64
	v_fmac_f32_e32 v5, v36, v61
	v_pk_mul_f32 v[46:47], v[40:41], v[68:69]
	v_fmac_f32_e32 v5, v38, v62
	v_mov_b32_e32 v66, v65
	v_add_f32_e32 v5, v5, v46
	s_waitcnt lgkmcnt(0)
	v_pk_mul_f32 v[64:65], v[44:45], v[66:67]
	v_add_f32_e32 v5, v5, v47
	v_add_f32_e32 v5, v5, v64
	v_add_f32_e32 v5, v5, v65
	v_add_u32_e32 v9, 0x8000, v56
	s_waitcnt lgkmcnt(0)
; #define LAS __attribute__((address_space(3)))
; template <int W> __device__ __forceinline__ void dn_solve(const LAS float* Mf, float (&t)[16], int lane) {
;     const int j = 16 * W + (lane >> 2), q = lane & 3;
; #pragma unroll
;     for (int s = 0; s < 16; ++s) t[s] = 0.f;
; #pragma unroll
;     for (int i = 16 * W; i < 64; ++i) {
;         float acc = 0.f;
; #pragma unroll
;         for (int s = 4 * W; s <= (i - 1) / 4 && i > 16 * W; ++s) acc += Mf[i * 64 + 4 * s + q] * t[s];
;         acc += __shfl_xor(acc, 1); acc += __shfl_xor(acc, 2);
;         const float val = (i == j ? 1.f : 0.f) - acc;
;         if (q == (i & 3)) t[i >> 2] = val;
;         asm volatile("" : "+v"(t[0]), "+v"(t[1]), "+v"(t[2]), "+v"(t[3]), "+v"(t[4]), "+v"(t[5]), "+v"(t[6]), "+v"(t[7]), "+v"(t[8]), "+v"(t[9]), "+v"(t[10]), "+v"(t[11]), "+v"(t[12]), "+v"(t[13]), "+v"(t[14]), "+v"(t[15]));
;     }
; }
	s_nop 1
	v_add_f32_dpp v5, v5, v5 quad_perm:[1,0,3,2] row_mask:0xf bank_mask:0xf
	s_nop 1
	v_add_f32_dpp v5, v5, v5 quad_perm:[2,3,0,1] row_mask:0xf bank_mask:0xf
	v_sub_f32_e32 v5, 0, v5
	v_cndmask_b32_e64 v45, v45, v5, s[46:47]
	ds_read2_b32 v[46:47], v11 offset0:144 offset1:148
	ds_read2_b32 v[58:59], v11 offset0:152 offset1:156
	ds_read2_b32 v[60:61], v11 offset0:160 offset1:164
	ds_read2_b32 v[62:63], v11 offset0:168 offset1:172
	ds_read2_b32 v[64:65], v11 offset0:176 offset1:180
	ds_read_b32 v67, v56 offset:32480
	s_waitcnt lgkmcnt(5)
	v_fma_f32 v5, v46, v10, 0
	v_fmac_f32_e32 v5, v12, v47
	s_waitcnt lgkmcnt(4)
	v_fmac_f32_e32 v5, v14, v58
	v_fmac_f32_e32 v5, v16, v59
	s_waitcnt lgkmcnt(3)
	v_fmac_f32_e32 v5, v34, v60
	v_mov_b32_e32 v41, v42
	s_waitcnt lgkmcnt(2)
	v_mov_b32_e32 v68, v63
	s_waitcnt lgkmcnt(1)
	v_mov_b32_e32 v69, v64
	v_fmac_f32_e32 v5, v36, v61
	v_pk_mul_f32 v[46:47], v[40:41], v[68:69]
	v_fmac_f32_e32 v5, v38, v62
	v_mov_b32_e32 v66, v65
	v_add_f32_e32 v5, v5, v46
	s_waitcnt lgkmcnt(0)
	v_pk_mul_f32 v[64:65], v[44:45], v[66:67]
	v_add_f32_e32 v5, v5, v47
	v_add_f32_e32 v5, v5, v64
	v_add_f32_e32 v5, v5, v65
	s_nop 1
	v_add_f32_dpp v5, v5, v5 quad_perm:[1,0,3,2] row_mask:0xf bank_mask:0xf
	s_nop 1
	v_add_f32_dpp v5, v5, v5 quad_perm:[2,3,0,1] row_mask:0xf bank_mask:0xf
	v_sub_f32_e32 v5, 0, v5
	v_cndmask_b32_e64 v45, v45, v5, s[44:45]
	ds_read2_b32 v[46:47], v11 offset0:208 offset1:212
	ds_read2_b32 v[58:59], v11 offset0:216 offset1:220
	ds_read2_b32 v[60:61], v11 offset0:224 offset1:228
	ds_read2_b32 v[62:63], v11 offset0:232 offset1:236
	ds_read2_b32 v[64:65], v11 offset0:240 offset1:244
	ds_read_b32 v67, v56 offset:32736
	s_waitcnt lgkmcnt(5)
	v_fma_f32 v5, v46, v10, 0
	v_fmac_f32_e32 v5, v12, v47
	s_waitcnt lgkmcnt(4)
	v_fmac_f32_e32 v5, v14, v58
	v_fmac_f32_e32 v5, v16, v59
	s_waitcnt lgkmcnt(3)
	v_fmac_f32_e32 v5, v34, v60
	v_mov_b32_e32 v41, v42
	s_waitcnt lgkmcnt(2)
	v_mov_b32_e32 v68, v63
	s_waitcnt lgkmcnt(1)
	v_mov_b32_e32 v69, v64
	v_fmac_f32_e32 v5, v36, v61
	v_pk_mul_f32 v[46:47], v[40:41], v[68:69]
	v_fmac_f32_e32 v5, v38, v62
	v_mov_b32_e32 v66, v65
	v_add_f32_e32 v5, v5, v46
	s_waitcnt lgkmcnt(0)
	v_pk_mul_f32 v[64:65], v[44:45], v[66:67]
	v_add_f32_e32 v5, v5, v47
	v_add_f32_e32 v5, v5, v64
	v_add_f32_e32 v5, v5, v65
	s_nop 1
	v_add_f32_dpp v5, v5, v5 quad_perm:[1,0,3,2] row_mask:0xf bank_mask:0xf
	s_nop 1
	v_add_f32_dpp v5, v5, v5 quad_perm:[2,3,0,1] row_mask:0xf bank_mask:0xf
	v_sub_f32_e32 v5, 0, v5
	v_cndmask_b32_e32 v46, v45, v5, vcc
	ds_read2_b32 v[58:59], v9 offset0:16 offset1:20
	ds_read2_b32 v[60:61], v9 offset0:24 offset1:28
	ds_read2_b32 v[62:63], v9 offset0:32 offset1:36
	ds_read2_b32 v[64:65], v9 offset0:40 offset1:44
	ds_read2_b32 v[66:67], v9 offset0:48 offset1:52
	ds_read_b32 v57, v56 offset:32992
	s_waitcnt lgkmcnt(5)
	v_fma_f32 v5, v58, v10, 0
	v_fmac_f32_e32 v5, v12, v59
	s_waitcnt lgkmcnt(4)
	v_fmac_f32_e32 v5, v14, v60
	v_fmac_f32_e32 v5, v16, v61
	s_waitcnt lgkmcnt(3)
	v_fmac_f32_e32 v5, v34, v62
	v_mov_b32_e32 v41, v42
	s_waitcnt lgkmcnt(2)
	v_mov_b32_e32 v68, v65
	s_waitcnt lgkmcnt(1)
	v_mov_b32_e32 v69, v66
	v_fmac_f32_e32 v5, v36, v63
	v_pk_mul_f32 v[58:59], v[40:41], v[68:69]
	v_fmac_f32_e32 v5, v38, v64
	v_mov_b32_e32 v45, v46
	v_mov_b32_e32 v56, v67
	v_add_f32_e32 v5, v5, v58
	s_waitcnt lgkmcnt(0)
; #define LAS __attribute__((address_space(3)))
; template <int W> __device__ __forceinline__ void dn_solve(const LAS float* Mf, float (&t)[16], int lane) {
;     const int j = 16 * W + (lane >> 2), q = lane & 3;
; #pragma unroll
;     for (int s = 0; s < 16; ++s) t[s] = 0.f;
; #pragma unroll
;     for (int i = 16 * W; i < 64; ++i) {
;         float acc = 0.f;
; #pragma unroll
;         for (int s = 4 * W; s <= (i - 1) / 4 && i > 16 * W; ++s) acc += Mf[i * 64 + 4 * s + q] * t[s];
;         acc += __shfl_xor(acc, 1); acc += __shfl_xor(acc, 2);
;         const float val = (i == j ? 1.f : 0.f) - acc;
;         if (q == (i & 3)) t[i >> 2] = val;
;         asm volatile("" : "+v"(t[0]), "+v"(t[1]), "+v"(t[2]), "+v"(t[3]), "+v"(t[4]), "+v"(t[5]), "+v"(t[6]), "+v"(t[7]), "+v"(t[8]), "+v"(t[9]), "+v"(t[10]), "+v"(t[11]), "+v"(t[12]), "+v"(t[13]), "+v"(t[14]), "+v"(t[15]));
;     }
; }
	v_pk_mul_f32 v[56:57], v[44:45], v[56:57]
	v_add_f32_e32 v5, v5, v59
	v_add_f32_e32 v5, v5, v56
	v_add_f32_e32 v5, v5, v57
	s_nop 1
	v_add_f32_dpp v5, v5, v5 quad_perm:[1,0,3,2] row_mask:0xf bank_mask:0xf
	s_nop 1
	v_add_f32_dpp v5, v5, v5 quad_perm:[2,3,0,1] row_mask:0xf bank_mask:0xf
	v_sub_f32_e32 v5, 0, v5
	v_cndmask_b32_e64 v47, v3, v5, s[42:43]
	ds_read2_b32 v[56:57], v9 offset0:80 offset1:84
	ds_read2_b32 v[58:59], v9 offset0:88 offset1:92
	ds_read2_b32 v[60:61], v9 offset0:96 offset1:100
	ds_read2_b32 v[62:63], v9 offset0:112 offset1:116
	ds_read2_b32 v[64:65], v9 offset0:120 offset1:124
	ds_read2_b32 v[66:67], v9 offset0:104 offset1:108
	s_waitcnt lgkmcnt(5)
	v_fma_f32 v3, v56, v10, 0
	v_fmac_f32_e32 v3, v12, v57
	s_waitcnt lgkmcnt(4)
	v_fmac_f32_e32 v3, v14, v58
	v_fmac_f32_e32 v3, v16, v59
	s_waitcnt lgkmcnt(3)
	v_fmac_f32_e32 v3, v34, v60
	v_fmac_f32_e32 v3, v36, v61
	v_mov_b32_e32 v43, v44
	s_waitcnt lgkmcnt(0)
	v_fmac_f32_e32 v3, v38, v66
	v_pk_mul_f32 v[62:63], v[42:43], v[62:63]
	v_fmac_f32_e32 v3, v40, v67
	v_add_f32_e32 v3, v3, v62
	v_pk_mul_f32 v[64:65], v[46:47], v[64:65]
	v_add_f32_e32 v3, v3, v63
	v_add_f32_e32 v3, v3, v64
	v_add_f32_e32 v3, v3, v65
	s_nop 1
	v_add_f32_dpp v3, v3, v3 quad_perm:[1,0,3,2] row_mask:0xf bank_mask:0xf
	s_nop 1
	v_add_f32_dpp v3, v3, v3 quad_perm:[2,3,0,1] row_mask:0xf bank_mask:0xf
	v_sub_f32_e32 v3, 0, v3
	v_cndmask_b32_e64 v47, v47, v3, s[46:47]
	ds_read2_b32 v[56:57], v9 offset0:144 offset1:148
	ds_read2_b32 v[58:59], v9 offset0:152 offset1:156
	ds_read2_b32 v[60:61], v9 offset0:160 offset1:164
	ds_read2_b32 v[62:63], v9 offset0:176 offset1:180
	ds_read2_b32 v[64:65], v9 offset0:184 offset1:188
	ds_read2_b32 v[66:67], v9 offset0:168 offset1:172
	s_waitcnt lgkmcnt(5)
	v_fma_f32 v3, v56, v10, 0
	v_fmac_f32_e32 v3, v12, v57
	s_waitcnt lgkmcnt(4)
	v_fmac_f32_e32 v3, v14, v58
	v_fmac_f32_e32 v3, v16, v59
	s_waitcnt lgkmcnt(3)
	v_fmac_f32_e32 v3, v34, v60
	v_fmac_f32_e32 v3, v36, v61
	v_mov_b32_e32 v43, v44
	s_waitcnt lgkmcnt(0)
	v_fmac_f32_e32 v3, v38, v66
	v_pk_mul_f32 v[62:63], v[42:43], v[62:63]
	v_fmac_f32_e32 v3, v40, v67
	v_add_f32_e32 v3, v3, v62
	v_pk_mul_f32 v[64:65], v[46:47], v[64:65]
	v_add_f32_e32 v3, v3, v63
	v_add_f32_e32 v3, v3, v64
	v_add_f32_e32 v3, v3, v65
	s_nop 1
	v_add_f32_dpp v3, v3, v3 quad_perm:[1,0,3,2] row_mask:0xf bank_mask:0xf
	s_nop 1
	v_add_f32_dpp v3, v3, v3 quad_perm:[2,3,0,1] row_mask:0xf bank_mask:0xf
	v_sub_f32_e32 v3, 0, v3
	v_cndmask_b32_e64 v47, v47, v3, s[44:45]
	ds_read2_b32 v[56:57], v9 offset0:208 offset1:212
	ds_read2_b32 v[58:59], v9 offset0:216 offset1:220
	ds_read2_b32 v[60:61], v9 offset0:224 offset1:228
	ds_read2_b32 v[62:63], v9 offset0:232 offset1:236
	ds_read2_b32 v[64:65], v9 offset0:240 offset1:244
	ds_read2_b32 v[66:67], v9 offset0:248 offset1:252
	s_waitcnt lgkmcnt(5)
	v_fma_f32 v3, v56, v10, 0
	v_fmac_f32_e32 v3, v12, v57
	v_mov_b32_e32 v35, v36
	s_waitcnt lgkmcnt(4)
	v_fmac_f32_e32 v3, v14, v58
	s_waitcnt lgkmcnt(3)
	v_pk_mul_f32 v[60:61], v[34:35], v[60:61]
	v_fmac_f32_e32 v3, v16, v59
	v_mov_b32_e32 v39, v40
	v_add_f32_e32 v3, v3, v60
	s_waitcnt lgkmcnt(2)
	v_pk_mul_f32 v[62:63], v[38:39], v[62:63]
	v_add_f32_e32 v3, v3, v61
	v_mov_b32_e32 v43, v44
	v_add_f32_e32 v3, v3, v62
	s_waitcnt lgkmcnt(1)
	v_pk_mul_f32 v[64:65], v[42:43], v[64:65]
	v_add_f32_e32 v3, v3, v63
	v_add_f32_e32 v3, v3, v64
	v_add_f32_e32 v3, v3, v65
	s_waitcnt lgkmcnt(0)
	v_pk_mul_f32 v[56:57], v[46:47], v[66:67]
	s_nop 0
	v_add_f32_e32 v3, v3, v56
	v_add_f32_e32 v3, v3, v57
	s_nop 1
	v_add_f32_dpp v3, v3, v3 quad_perm:[1,0,3,2] row_mask:0xf bank_mask:0xf
	s_nop 1
	v_add_f32_dpp v3, v3, v3 quad_perm:[2,3,0,1] row_mask:0xf bank_mask:0xf
	v_sub_f32_e32 v3, 0, v3
	v_cndmask_b32_e32 v3, v47, v3, vcc

; __device__ __forceinline__ float silu_f(float z) { return z / (1.f + __expf(-z)); }
; __device__ __forceinline__ void unpack8(const u32x4 v, float (&f)[8]) { f[0] = bf_lo(v.x); f[1] = bf_hi(v.x); f[2] = bf_lo(v.y); f[3] = bf_hi(v.y); f[4] = bf_lo(v.z); f[5] = bf_hi(v.z); f[6] = bf_lo(v.w); f[7] = bf_hi(v.w); }
; __device__ __forceinline__ void dn_conv_phase(bf16_t* P, const bf16_t* HALO, const float* conv_w, int G) {
;     ...
;         for (int rr = 0; rr < 64; ++rr) {
;             u32x4 w4;
;             if (rr + 2 < 64) w4 = *(const u32x4*)(base + (size_t)(rr + 2) * 4096);
;             else w4 = slast ? zero : *(const u32x4*)(HALO + ((size_t)(rb + 1) * 4 + (rr + 2 - 64)) * 4096 + col0);
;             float x0[8], x1[8], x2[8], x3[8], x4[8], y[8];
;             unpack8(w0, x0); unpack8(w1, x1); unpack8(w2, x2); unpack8(w3, x3); unpack8(w4, x4);
;             float ss = 0.f;
; #pragma unroll
;             for (int c = 0; c < 8; ++c) { const float a = x0[c] * cw[c][0] + x1[c] * cw[c][1] + x2[c] * cw[c][2] + x3[c] * cw[c][3] + x4[c] * cw[c][4]; y[c] = silu_f(a); ss += y[c] * y[c]; }
.LBB0_139:
	s_nop 0
	v_lshl_add_u64 v[74:75], v[50:51], 0, s[52:53]
	v_add_co_u32_e32 v2, vcc, 0x7604000, v74
	s_waitcnt vmcnt(2)
	v_lshlrev_b32_e32 v80, 16, v40
	v_addc_co_u32_e32 v3, vcc, 0, v75, vcc
	global_load_dwordx4 v[24:27], v[2:3], off
	v_and_b32_e32 v81, 0xffff0000, v40
	v_lshlrev_b32_e32 v2, 16, v28
	v_and_b32_e32 v3, 0xffff0000, v28
	v_pk_mul_f32 v[80:81], v[18:19], v[80:81]
	s_waitcnt vmcnt(2)
	v_lshlrev_b32_e32 v82, 16, v32
	v_and_b32_e32 v83, 0xffff0000, v32
	v_pk_fma_f32 v[80:81], v[70:71], v[2:3], v[80:81]
	s_waitcnt vmcnt(1)
	v_lshlrev_b32_e32 v76, 16, v36
	v_and_b32_e32 v77, 0xffff0000, v36
	v_pk_fma_f32 v[80:81], v[20:21], v[82:83], v[80:81]
	v_lshlrev_b32_e32 v96, 16, v29
	v_pk_fma_f32 v[80:81], v[16:17], v[76:77], v[80:81]
	v_and_b32_e32 v97, 0xffff0000, v29
	v_and_b32_e32 v87, 0xffff0000, v33
	v_and_b32_e32 v98, 0xffff0000, v30
	v_lshlrev_b32_e32 v99, 16, v30
	v_and_b32_e32 v102, 0xffff0000, v31
	v_lshlrev_b32_e32 v103, 16, v31
	v_lshlrev_b32_e32 v95, 16, v35
	s_waitcnt vmcnt(0)
	v_lshlrev_b32_e32 v78, 16, v24
	v_and_b32_e32 v79, 0xffff0000, v24
	v_pk_fma_f32 v[80:81], v[22:23], v[78:79], v[80:81]
	v_lshlrev_b32_e32 v89, 16, v26
	v_mul_f32_e32 v0, 0xbfb8aa3b, v80
	v_exp_f32_e32 v84, v0
	v_mul_f32_e32 v0, 0xbfb8aa3b, v81
	v_exp_f32_e32 v85, v0
	v_mov_b32_e32 v0, 1.0
	v_pk_add_f32 v[84:85], v[84:85], 1.0 op_sel_hi:[1,0]
	s_nop 0
	v_div_scale_f32 v28, s[0:1], v85, v85, v81
	v_rcp_f32_e32 v32, v28
	s_nop 0
	v_fma_f32 v36, -v28, v32, 1.0
	v_fmac_f32_e32 v32, v36, v32
	v_div_scale_f32 v36, vcc, v81, v85, v81
	v_mul_f32_e32 v40, v36, v32
	v_fma_f32 v86, -v28, v40, v36
	v_fmac_f32_e32 v40, v86, v32
	v_fma_f32 v28, -v28, v40, v36
	v_div_fmas_f32 v28, v28, v32, v40
	v_div_fixup_f32 v93, v28, v85, v81
	v_div_scale_f32 v28, s[0:1], v84, v84, v80
	v_rcp_f32_e32 v32, v28
	v_and_b32_e32 v85, 0xffff0000, v41
	v_lshlrev_b32_e32 v86, 16, v33
	v_fma_f32 v36, -v28, v32, 1.0
	v_fmac_f32_e32 v32, v36, v32
	v_div_scale_f32 v36, vcc, v80, v84, v80
	v_mul_f32_e32 v40, v36, v32
	v_fma_f32 v81, -v28, v40, v36
	v_fmac_f32_e32 v40, v81, v32
	v_fma_f32 v28, -v28, v40, v36
	v_div_fmas_f32 v28, v28, v32, v40
	v_div_fixup_f32 v92, v28, v84, v80
	v_lshlrev_b32_e32 v84, 16, v41
	v_pk_mul_f32 v[28:29], v[10:11], v[84:85]
	v_lshlrev_b32_e32 v40, 16, v37
	v_pk_fma_f32 v[28:29], v[68:69], v[96:97], v[28:29]
	v_and_b32_e32 v41, 0xffff0000, v37
	v_pk_fma_f32 v[28:29], v[12:13], v[86:87], v[28:29]
	v_lshlrev_b32_e32 v80, 16, v25
	v_and_b32_e32 v81, 0xffff0000, v25
	v_pk_fma_f32 v[28:29], v[66:67], v[40:41], v[28:29]
	s_nop 0
	v_pk_fma_f32 v[28:29], v[14:15], v[80:81], v[28:29]
	s_nop 0
	v_mul_f32_e32 v32, 0xbfb8aa3b, v28
	v_mul_f32_e32 v33, 0xbfb8aa3b, v29
	v_exp_f32_e32 v32, v32
	v_exp_f32_e32 v33, v33
	s_nop 0
	v_pk_add_f32 v[32:33], v[32:33], 1.0 op_sel_hi:[1,0]
	s_nop 0
	v_div_scale_f32 v36, s[0:1], v33, v33, v29
	v_rcp_f32_e32 v37, v36
	s_nop 0
	v_fma_f32 v84, -v36, v37, 1.0
	v_fmac_f32_e32 v37, v84, v37
	v_div_scale_f32 v84, vcc, v29, v33, v29
	v_mul_f32_e32 v85, v84, v37
	v_fma_f32 v88, -v36, v85, v84
	v_fmac_f32_e32 v85, v88, v37
	v_fma_f32 v36, -v36, v85, v84
	v_div_fmas_f32 v36, v36, v37, v85
	v_div_fixup_f32 v33, v36, v33, v29
	v_div_scale_f32 v29, s[0:1], v32, v32, v28
	v_rcp_f32_e32 v36, v29
	v_and_b32_e32 v88, 0xffff0000, v26
	v_fma_f32 v37, -v29, v36, 1.0
	v_fmac_f32_e32 v36, v37, v36
	v_div_scale_f32 v37, vcc, v28, v32, v28
	v_mul_f32_e32 v84, v37, v36
	v_fma_f32 v85, -v29, v84, v37
	v_fmac_f32_e32 v84, v85, v36
	v_fma_f32 v29, -v29, v84, v37
	v_div_fmas_f32 v29, v29, v36, v84
	v_div_fixup_f32 v32, v29, v32, v28
	v_and_b32_e32 v28, 0xffff0000, v42
	v_lshlrev_b32_e32 v29, 16, v42
	v_pk_mul_f32 v[28:29], v[64:65], v[28:29]
	v_and_b32_e32 v36, 0xffff0000, v34
	v_lshlrev_b32_e32 v37, 16, v34
	v_pk_fma_f32 v[28:29], v[8:9], v[98:99], v[28:29]
	v_and_b32_e32 v84, 0xffff0000, v38
	v_lshlrev_b32_e32 v85, 16, v38
	v_pk_fma_f32 v[28:29], v[62:63], v[36:37], v[28:29]
	s_nop 0
	v_pk_fma_f32 v[28:29], v[60:61], v[84:85], v[28:29]
	s_nop 0
	v_pk_fma_f32 v[28:29], v[6:7], v[88:89], v[28:29]
	s_nop 0
	v_mul_f32_e32 v30, 0xbfb8aa3b, v29
	v_exp_f32_e32 v91, v30
	v_mul_f32_e32 v30, 0xbfb8aa3b, v28
	v_exp_f32_e32 v90, v30
	s_nop 0
	v_pk_add_f32 v[90:91], v[90:91], 1.0 op_sel_hi:[1,0]
	s_nop 0
	v_div_scale_f32 v30, s[0:1], v91, v91, v29
	v_rcp_f32_e32 v34, v30
	s_nop 0
	v_fma_f32 v38, -v30, v34, 1.0
	v_fmac_f32_e32 v34, v38, v34
	v_div_scale_f32 v38, vcc, v29, v91, v29
	v_mul_f32_e32 v42, v38, v34
	v_fma_f32 v94, -v30, v42, v38
	v_fmac_f32_e32 v42, v94, v34
	v_fma_f32 v30, -v30, v42, v38
	v_div_fmas_f32 v30, v30, v34, v42
	v_div_fixup_f32 v101, v30, v91, v29
	v_div_scale_f32 v29, s[0:1], v90, v90, v28
	v_rcp_f32_e32 v30, v29
	v_and_b32_e32 v94, 0xffff0000, v35
	v_lshlrev_b32_e32 v91, 16, v27
	v_fma_f32 v34, -v29, v30, 1.0
	v_fmac_f32_e32 v30, v34, v30
	v_div_scale_f32 v34, vcc, v28, v90, v28
	v_mul_f32_e32 v38, v34, v30
	v_fma_f32 v42, -v29, v38, v34
	v_fmac_f32_e32 v38, v42, v30
	v_fma_f32 v29, -v29, v38, v34
	v_div_fmas_f32 v29, v29, v30, v38
	v_div_fixup_f32 v100, v29, v90, v28
	v_and_b32_e32 v28, 0xffff0000, v43
	v_lshlrev_b32_e32 v29, 16, v43
	v_pk_mul_f32 v[28:29], v[56:57], v[28:29]
	v_and_b32_e32 v42, 0xffff0000, v39
	v_pk_fma_f32 v[28:29], v[4:5], v[102:103], v[28:29]
	v_lshlrev_b32_e32 v43, 16, v39
	v_pk_fma_f32 v[28:29], v[54:55], v[94:95], v[28:29]
	v_and_b32_e32 v90, 0xffff0000, v27
	v_pk_fma_f32 v[28:29], v[52:53], v[42:43], v[28:29]
	s_nop 0
	v_pk_fma_f32 v[28:29], v[58:59], v[90:91], v[28:29]
	s_nop 0
	v_mul_f32_e32 v30, 0xbfb8aa3b, v29
	v_exp_f32_e32 v31, v30
	v_mul_f32_e32 v30, 0xbfb8aa3b, v28
	v_exp_f32_e32 v30, v30
	s_nop 0
	v_pk_add_f32 v[30:31], v[30:31], 1.0 op_sel_hi:[1,0]
	s_nop 0
	v_div_scale_f32 v34, s[0:1], v31, v31, v29
	v_rcp_f32_e32 v35, v34
	s_nop 0
	v_fma_f32 v38, -v34, v35, 1.0
	v_fmac_f32_e32 v35, v38, v35
	v_div_scale_f32 v38, vcc, v29, v31, v29
	v_mul_f32_e32 v39, v38, v35
	v_fma_f32 v104, -v34, v39, v38
	v_fmac_f32_e32 v39, v104, v35
	v_fma_f32 v34, -v34, v39, v38
	v_div_fmas_f32 v34, v34, v35, v39
	v_div_fixup_f32 v35, v34, v31, v29
	v_div_scale_f32 v29, s[0:1], v30, v30, v28
	v_rcp_f32_e32 v31, v29
	s_nop 0
	v_fma_f32 v34, -v29, v31, 1.0
	v_fmac_f32_e32 v31, v34, v31
	v_div_scale_f32 v34, vcc, v28, v30, v28
	v_mul_f32_e32 v38, v34, v31
	v_fma_f32 v39, -v29, v38, v34
	v_fmac_f32_e32 v38, v39, v31
	v_fma_f32 v29, -v29, v38, v34
	v_div_fmas_f32 v29, v29, v31, v38
	v_div_fixup_f32 v34, v29, v30, v28
	v_mov_b32_e32 v38, 1.0
	s_and_saveexec_b64 s[0:1], s[40:41]
	s_cbranch_execz .LBB0_141
; __device__ __forceinline__ unsigned cvtpk_s(float lo, float hi) { f32x2_t v = {lo, hi}; bf16x2_t b = __builtin_convertvector(v, bf16x2_t); return __builtin_bit_cast(unsigned, b); }
; __device__ __forceinline__ float silu_f(float z) { return z / (1.f + __expf(-z)); }
; __device__ __forceinline__ void dn_conv_phase(bf16_t* P, const bf16_t* HALO, const float* conv_w, int G) {
;     ...
;             for (int c = 0; c < 8; ++c) { const float a = x0[c] * cw[c][0] + x1[c] * cw[c][1] + x2[c] * cw[c][2] + x3[c] * cw[c][3] + x4[c] * cw[c][4]; y[c] = silu_f(a); ss += y[c] * y[c]; }
;             float sc = 1.f;
;             if (kind < 2) { ss += __shfl_xor(ss, 1); ss += __shfl_xor(ss, 2); ss += __shfl_xor(ss, 4); ss += __shfl_xor(ss, 8); sc = rsqrtf(ss + EPS) * (kind == 0 ? 0.08838834764831845f : 1.f); }
;             u32x4 o; o.x = cvtpk_s(y[0] * sc, y[1] * sc); o.y = cvtpk_s(y[2] * sc, y[3] * sc); o.z = cvtpk_s(y[4] * sc, y[5] * sc); o.w = cvtpk_s(y[6] * sc, y[7] * sc);
;             *(u32x4*)(base + (size_t)rr * 4096) = o;
	v_pk_mul_f32 v[28:29], v[92:93], v[92:93]
	v_pk_mul_f32 v[30:31], v[32:33], v[32:33]
	v_add_f32_e32 v28, v28, v29
	v_add_f32_e32 v28, v30, v28
	v_pk_mul_f32 v[38:39], v[100:101], v[100:101]
	v_add_f32_e32 v28, v31, v28
	v_and_b32_e32 v30, 64, v190
	v_add_f32_e32 v28, v39, v28
	v_xor_b32_e32 v29, 1, v190
	v_add_u32_e32 v30, 64, v30
	v_pk_mul_f32 v[104:105], v[34:35], v[34:35]
	v_add_f32_e32 v28, v38, v28
	v_cmp_lt_i32_e32 vcc, v29, v30
	v_add_f32_e32 v28, v105, v28
	v_add_f32_e32 v28, v104, v28
	s_nop 1
	v_add_f32_dpp v28, v28, v28 quad_perm:[1,0,3,2] row_mask:0xf bank_mask:0xf
	s_nop 1
	v_add_f32_dpp v28, v28, v28 quad_perm:[2,3,0,1] row_mask:0xf bank_mask:0xf
	s_nop 1
	v_add_f32_dpp v28, v28, v28 row_half_mirror row_mask:0xf bank_mask:0xf
	s_nop 1
	v_add_f32_dpp v28, v28, v28 row_mirror row_mask:0xf bank_mask:0xf
	v_add_f32_e32 v28, 0x358637bd, v28
	v_mul_f32_e32 v29, 0x4b800000, v28
	v_cmp_gt_f32_e32 vcc, s39, v28
	s_nop 1
	v_cndmask_b32_e32 v28, v28, v29, vcc
	v_rsq_f32_e32 v28, v28
	s_nop 0
	v_mul_f32_e32 v29, 0x45800000, v28
	v_cndmask_b32_e32 v28, v28, v29, vcc
	v_mul_f32_e32 v38, v106, v28
.LBB0_141:
	s_or_b64 exec, exec, s[0:1]
	v_add_co_u32_e32 v104, vcc, s26, v74
	s_mov_b32 s19, 0x7606000
	s_mov_b64 s[0:1], vcc
	v_add_co_u32_e32 v28, vcc, s19, v74
	v_pk_mul_f32 v[2:3], v[18:19], v[2:3]
	s_nop 0
	v_addc_co_u32_e32 v29, vcc, 0, v75, vcc
	global_load_dwordx4 v[28:31], v[28:29], off
	v_pk_mul_f32 v[34:35], v[34:35], v[38:39] op_sel_hi:[1,0]
	v_pk_fma_f32 v[2:3], v[70:71], v[82:83], v[2:3]
	v_pk_mul_f32 v[92:93], v[92:93], v[38:39] op_sel_hi:[1,0]
	v_pk_mul_f32 v[108:109], v[32:33], v[38:39] op_sel_hi:[1,0]
	v_pk_mul_f32 v[100:101], v[100:101], v[38:39] op_sel_hi:[1,0]
	v_pk_mul_f32 v[38:39], v[10:11], v[96:97]
	v_pk_mul_f32 v[96:97], v[64:65], v[98:99]
	v_pk_mov_b32 v[98:99], v[34:35], v[34:35] op_sel:[1,0]
	v_pk_fma_f32 v[2:3], v[20:21], v[76:77], v[2:3]
	v_cvt_pk_bf16_f32 v32, v92, v93
	v_pk_mov_b32 v[92:93], v[100:101], v[100:101] op_sel:[1,0]
	v_pk_fma_f32 v[38:39], v[68:69], v[86:87], v[38:39]
	v_cvt_pk_bf16_f32 v35, v98, v99
	v_pk_fma_f32 v[2:3], v[16:17], v[78:79], v[2:3]
	v_cvt_pk_bf16_f32 v33, v108, v109
	v_addc_co_u32_e64 v105, vcc, 0, v75, s[0:1]
	v_cvt_pk_bf16_f32 v34, v92, v93
	v_pk_fma_f32 v[38:39], v[12:13], v[40:41], v[38:39]
	v_pk_fma_f32 v[96:97], v[8:9], v[36:37], v[96:97]
	global_store_dwordx4 v[104:105], v[32:35], off
	v_pk_fma_f32 v[92:93], v[62:63], v[84:85], v[96:97]
	v_pk_mul_f32 v[102:103], v[56:57], v[102:103]
	v_pk_fma_f32 v[32:33], v[66:67], v[80:81], v[38:39]
	v_pk_fma_f32 v[34:35], v[60:61], v[88:89], v[92:93]
	v_pk_fma_f32 v[102:103], v[4:5], v[94:95], v[102:103]
	s_waitcnt vmcnt(1)
; __device__ __forceinline__ float silu_f(float z) { return z / (1.f + __expf(-z)); }
; __device__ __forceinline__ void unpack8(const u32x4 v, float (&f)[8]) { f[0] = bf_lo(v.x); f[1] = bf_hi(v.x); f[2] = bf_lo(v.y); f[3] = bf_hi(v.y); f[4] = bf_lo(v.z); f[5] = bf_hi(v.z); f[6] = bf_lo(v.w); f[7] = bf_hi(v.w); }
; __device__ __forceinline__ void dn_conv_phase(bf16_t* P, const bf16_t* HALO, const float* conv_w, int G) {
;     ...
;             if (rr + 2 < 64) w4 = *(const u32x4*)(base + (size_t)(rr + 2) * 4096);
;             else w4 = slast ? zero : *(const u32x4*)(HALO + ((size_t)(rb + 1) * 4 + (rr + 2 - 64)) * 4096 + col0);
;             float x0[8], x1[8], x2[8], x3[8], x4[8], y[8];
;             unpack8(w0, x0); unpack8(w1, x1); unpack8(w2, x2); unpack8(w3, x3); unpack8(w4, x4);
;             float ss = 0.f;
; #pragma unroll
;             for (int c = 0; c < 8; ++c) { const float a = x0[c] * cw[c][0] + x1[c] * cw[c][1] + x2[c] * cw[c][2] + x3[c] * cw[c][3] + x4[c] * cw[c][4]; y[c] = silu_f(a); ss += y[c] * y[c]; }
;             float sc = 1.f;
;             if (kind < 2) { ss += __shfl_xor(ss, 1); ss += __shfl_xor(ss, 2); ss += __shfl_xor(ss, 4); ss += __shfl_xor(ss, 8); sc = rsqrtf(ss + EPS) * (kind == 0 ? 0.08838834764831845f : 1.f); }
	v_lshlrev_b32_e32 v98, 16, v28
	v_and_b32_e32 v99, 0xffff0000, v28
	v_pk_fma_f32 v[2:3], v[22:23], v[98:99], v[2:3]
	v_lshlrev_b32_e32 v96, 16, v29
	v_mul_f32_e32 v38, 0xbfb8aa3b, v2
	v_mul_f32_e32 v39, 0xbfb8aa3b, v3
	v_and_b32_e32 v97, 0xffff0000, v29
	v_exp_f32_e32 v38, v38
	v_exp_f32_e32 v39, v39
	v_pk_fma_f32 v[32:33], v[14:15], v[96:97], v[32:33]
	v_and_b32_e32 v92, 0xffff0000, v30
	v_lshlrev_b32_e32 v93, 16, v30
	v_mul_f32_e32 v100, 0xbfb8aa3b, v32
	v_mul_f32_e32 v101, 0xbfb8aa3b, v33
	v_pk_fma_f32 v[34:35], v[6:7], v[92:93], v[34:35]
	v_exp_f32_e32 v100, v100
	v_exp_f32_e32 v101, v101
	v_mul_f32_e32 v104, 0xbfb8aa3b, v35
	v_pk_add_f32 v[38:39], v[38:39], 1.0 op_sel_hi:[1,0]
	v_exp_f32_e32 v105, v104
	v_div_scale_f32 v104, s[0:1], v39, v39, v3
	v_rcp_f32_e32 v115, v104
	v_pk_add_f32 v[100:101], v[100:101], 1.0 op_sel_hi:[1,0]
	v_div_scale_f32 v109, s[0:1], v38, v38, v2
	v_div_scale_f32 v111, s[0:1], v101, v101, v33
	v_rcp_f32_e32 v116, v109
	v_rcp_f32_e32 v117, v111
	v_fma_f32 v119, -v104, v115, 1.0
	v_div_scale_f32 v108, vcc, v3, v39, v3
	v_fmac_f32_e32 v115, v119, v115
	v_div_scale_f32 v113, s[0:1], v100, v100, v32
	v_fma_f32 v120, -v109, v116, 1.0
	v_mul_f32_e32 v119, v108, v115
	v_div_scale_f32 v110, s[42:43], v2, v38, v2
	v_rcp_f32_e32 v118, v113
	v_fma_f32 v121, -v111, v117, 1.0
	v_fmac_f32_e32 v116, v120, v116
	v_fma_f32 v123, -v104, v119, v108
	v_div_scale_f32 v112, s[44:45], v33, v101, v33
	v_fmac_f32_e32 v117, v121, v117
	v_mul_f32_e32 v120, v110, v116
	v_fmac_f32_e32 v119, v123, v115
	v_mul_f32_e32 v121, v112, v117
	v_fma_f32 v124, -v109, v120, v110
	v_fma_f32 v104, -v104, v119, v108
	v_mul_f32_e32 v107, 0xbfb8aa3b, v34
	v_fma_f32 v125, -v111, v121, v112
	v_fmac_f32_e32 v120, v124, v116
	v_div_fmas_f32 v104, v104, v115, v119
	v_fma_f32 v122, -v113, v118, 1.0
	v_fmac_f32_e32 v121, v125, v117
	v_fma_f32 v108, -v109, v120, v110
	v_div_fixup_f32 v3, v104, v39, v3
	s_mov_b64 vcc, s[42:43]
	v_exp_f32_e32 v104, v107
	v_div_scale_f32 v114, s[0:1], v32, v100, v32
	v_fmac_f32_e32 v118, v122, v118
	v_fma_f32 v109, -v111, v121, v112
	v_div_fmas_f32 v39, v108, v116, v120
	s_mov_b64 vcc, s[44:45]
	v_mul_f32_e32 v122, v114, v118
	v_div_fixup_f32 v2, v39, v38, v2
	v_div_fmas_f32 v38, v109, v117, v121
	v_div_fixup_f32 v33, v38, v101, v33
	v_fma_f32 v38, -v113, v122, v114
	v_fmac_f32_e32 v122, v38, v118
	v_pk_add_f32 v[38:39], v[104:105], 1.0 op_sel_hi:[1,0]
	v_fma_f32 v101, -v113, v122, v114
	v_div_scale_f32 v104, s[42:43], v39, v39, v35
	v_rcp_f32_e32 v105, v104
	s_mov_b64 vcc, s[0:1]
	v_div_fmas_f32 v101, v101, v118, v122
	v_div_fixup_f32 v32, v101, v100, v32
	v_fma_f32 v100, -v104, v105, 1.0
	v_fmac_f32_e32 v105, v100, v105
	v_div_scale_f32 v100, vcc, v35, v39, v35
	v_mul_f32_e32 v101, v100, v105
	v_fma_f32 v107, -v104, v101, v100
	v_fmac_f32_e32 v101, v107, v105
	v_fma_f32 v100, -v104, v101, v100
	v_div_scale_f32 v107, s[0:1], v38, v38, v34
	v_div_fmas_f32 v100, v100, v105, v101
	v_pk_fma_f32 v[102:103], v[54:55], v[42:43], v[102:103]
	v_rcp_f32_e32 v108, v107
	v_div_fixup_f32 v35, v100, v39, v35
	v_and_b32_e32 v100, 0xffff0000, v31
	v_lshlrev_b32_e32 v101, 16, v31
	v_pk_fma_f32 v[102:103], v[52:53], v[90:91], v[102:103]
	v_fma_f32 v39, -v107, v108, 1.0
	v_pk_fma_f32 v[102:103], v[58:59], v[100:101], v[102:103]
	v_fmac_f32_e32 v108, v39, v108
	v_mul_f32_e32 v104, 0xbfb8aa3b, v103
	v_exp_f32_e32 v105, v104
	v_mul_f32_e32 v104, 0xbfb8aa3b, v102
	v_exp_f32_e32 v104, v104
	v_div_scale_f32 v39, vcc, v34, v38, v34
	v_mul_f32_e32 v109, v39, v108
	v_fma_f32 v110, -v107, v109, v39
	v_fmac_f32_e32 v109, v110, v108
	v_pk_add_f32 v[104:105], v[104:105], 1.0 op_sel_hi:[1,0]
	v_fma_f32 v39, -v107, v109, v39
	v_div_scale_f32 v107, s[0:1], v105, v105, v103
	v_rcp_f32_e32 v110, v107
	v_div_fmas_f32 v39, v39, v108, v109
	v_div_fixup_f32 v34, v39, v38, v34
	v_fma_f32 v38, -v107, v110, 1.0
	v_fmac_f32_e32 v110, v38, v110
	v_div_scale_f32 v38, vcc, v103, v105, v103
	v_mul_f32_e32 v39, v38, v110
	v_fma_f32 v108, -v107, v39, v38
	v_fmac_f32_e32 v39, v108, v110
	v_fma_f32 v38, -v107, v39, v38
	v_div_scale_f32 v107, s[0:1], v104, v104, v102
	v_rcp_f32_e32 v108, v107
	v_div_fmas_f32 v38, v38, v110, v39
	v_div_fixup_f32 v39, v38, v105, v103
	v_fma_f32 v38, -v107, v108, 1.0
	v_fmac_f32_e32 v108, v38, v108
	v_div_scale_f32 v38, vcc, v102, v104, v102
	v_mul_f32_e32 v103, v38, v108
	v_fma_f32 v105, -v107, v103, v38
	v_fmac_f32_e32 v103, v105, v108
	v_fma_f32 v38, -v107, v103, v38
	v_div_fmas_f32 v38, v38, v108, v103
	v_div_fixup_f32 v38, v38, v104, v102
	s_and_saveexec_b64 s[0:1], s[40:41]
	s_cbranch_execz .LBB0_143
	v_pk_mul_f32 v[102:103], v[2:3], v[2:3]
	v_pk_mul_f32 v[104:105], v[32:33], v[32:33]
	v_add_f32_e32 v0, v102, v103
	v_add_f32_e32 v0, v104, v0
	v_pk_mul_f32 v[108:109], v[34:35], v[34:35]
	v_add_f32_e32 v0, v105, v0
	v_and_b32_e32 v103, 64, v190
	v_add_f32_e32 v0, v109, v0
	v_xor_b32_e32 v102, 1, v190
	v_add_u32_e32 v103, 64, v103
	v_pk_mul_f32 v[110:111], v[38:39], v[38:39]
	v_add_f32_e32 v0, v108, v0
	v_cmp_lt_i32_e32 vcc, v102, v103
	v_add_f32_e32 v0, v111, v0
	v_add_f32_e32 v0, v110, v0
	s_nop 1
	v_add_f32_dpp v0, v0, v0 quad_perm:[1,0,3,2] row_mask:0xf bank_mask:0xf
	s_nop 1
	v_add_f32_dpp v0, v0, v0 quad_perm:[2,3,0,1] row_mask:0xf bank_mask:0xf
	s_nop 1
	v_add_f32_dpp v0, v0, v0 row_half_mirror row_mask:0xf bank_mask:0xf
	s_nop 1
	v_add_f32_dpp v0, v0, v0 row_mirror row_mask:0xf bank_mask:0xf
	v_add_f32_e32 v0, 0x358637bd, v0
	v_mul_f32_e32 v102, 0x4b800000, v0
	v_cmp_gt_f32_e32 vcc, s39, v0
	s_nop 1
	v_cndmask_b32_e32 v0, v0, v102, vcc
	v_rsq_f32_e32 v0, v0
	s_nop 0
	v_mul_f32_e32 v102, 0x45800000, v0
	v_cndmask_b32_e32 v0, v0, v102, vcc
	v_mul_f32_e32 v0, v106, v0

; __device__ __forceinline__ unsigned cvtpk_s(float lo, float hi) { f32x2_t v = {lo, hi}; bf16x2_t b = __builtin_convertvector(v, bf16x2_t); return __builtin_bit_cast(unsigned, b); }
; __device__ __forceinline__ float silu_f(float z) { return z / (1.f + __expf(-z)); }
; __device__ __forceinline__ void unpack8(const u32x4 v, float (&f)[8]) { f[0] = bf_lo(v.x); f[1] = bf_hi(v.x); f[2] = bf_lo(v.y); f[3] = bf_hi(v.y); f[4] = bf_lo(v.z); f[5] = bf_hi(v.z); f[6] = bf_lo(v.w); f[7] = bf_hi(v.w); }
; __device__ __forceinline__ void dn_conv_phase(bf16_t* P, const bf16_t* HALO, const float* conv_w, int G) {
;     ...
;             float x0[8], x1[8], x2[8], x3[8], x4[8], y[8];
;             unpack8(w0, x0); unpack8(w1, x1); unpack8(w2, x2); unpack8(w3, x3); unpack8(w4, x4);
;             float ss = 0.f;
; #pragma unroll
;             for (int c = 0; c < 8; ++c) { const float a = x0[c] * cw[c][0] + x1[c] * cw[c][1] + x2[c] * cw[c][2] + x3[c] * cw[c][3] + x4[c] * cw[c][4]; y[c] = silu_f(a); ss += y[c] * y[c]; }
;             float sc = 1.f;
;             if (kind < 2) { ss += __shfl_xor(ss, 1); ss += __shfl_xor(ss, 2); ss += __shfl_xor(ss, 4); ss += __shfl_xor(ss, 8); sc = rsqrtf(ss + EPS) * (kind == 0 ? 0.08838834764831845f : 1.f); }
;             u32x4 o; o.x = cvtpk_s(y[0] * sc, y[1] * sc); o.y = cvtpk_s(y[2] * sc, y[3] * sc); o.z = cvtpk_s(y[4] * sc, y[5] * sc); o.w = cvtpk_s(y[6] * sc, y[7] * sc);
.LBB0_148:
	v_pk_mul_f32 v[2:3], v[18:19], v[82:83]
	s_waitcnt vmcnt(0)
	v_lshlrev_b32_e32 v104, 16, v32
	v_pk_fma_f32 v[2:3], v[70:71], v[76:77], v[2:3]
	v_and_b32_e32 v105, 0xffff0000, v32
	v_pk_fma_f32 v[2:3], v[20:21], v[78:79], v[2:3]
	v_pk_mul_f32 v[36:37], v[64:65], v[36:37]
	v_pk_fma_f32 v[2:3], v[16:17], v[98:99], v[2:3]
	v_pk_fma_f32 v[36:37], v[8:9], v[84:85], v[36:37]
	v_pk_fma_f32 v[2:3], v[22:23], v[104:105], v[2:3]
	v_pk_fma_f32 v[36:37], v[62:63], v[88:89], v[36:37]
	v_mul_f32_e32 v0, 0xbfb8aa3b, v2
	v_exp_f32_e32 v38, v0
	v_mul_f32_e32 v0, 0xbfb8aa3b, v3
	v_exp_f32_e32 v39, v0
	v_pk_fma_f32 v[36:37], v[60:61], v[92:93], v[36:37]
	v_pk_mul_f32 v[94:95], v[56:57], v[94:95]
	v_mov_b32_e32 v0, 1.0
	v_pk_add_f32 v[38:39], v[38:39], 1.0 op_sel_hi:[1,0]
	v_pk_fma_f32 v[94:95], v[4:5], v[42:43], v[94:95]
	v_div_scale_f32 v82, s[42:43], v39, v39, v3
	v_rcp_f32_e32 v83, v82
	v_pk_fma_f32 v[94:95], v[54:55], v[90:91], v[94:95]
	v_fma_f32 v102, -v82, v83, 1.0
	v_fmac_f32_e32 v83, v102, v83
	v_div_scale_f32 v102, vcc, v3, v39, v3
	v_mul_f32_e32 v103, v102, v83
	v_fma_f32 v107, -v82, v103, v102
	v_fmac_f32_e32 v103, v107, v83
	v_fma_f32 v82, -v82, v103, v102
	v_div_fmas_f32 v82, v82, v83, v103
	v_div_fixup_f32 v3, v82, v39, v3
	v_pk_mul_f32 v[82:83], v[10:11], v[86:87]
	v_div_scale_f32 v107, s[42:43], v38, v38, v2
	v_pk_fma_f32 v[82:83], v[68:69], v[40:41], v[82:83]
	v_rcp_f32_e32 v110, v107
	v_pk_fma_f32 v[82:83], v[12:13], v[80:81], v[82:83]
	v_lshlrev_b32_e32 v102, 16, v33
	v_and_b32_e32 v103, 0xffff0000, v33
	v_pk_fma_f32 v[82:83], v[66:67], v[96:97], v[82:83]
	v_fma_f32 v39, -v107, v110, 1.0
	v_pk_fma_f32 v[82:83], v[14:15], v[102:103], v[82:83]
	v_fmac_f32_e32 v110, v39, v110
	v_mul_f32_e32 v86, 0xbfb8aa3b, v82
	v_mul_f32_e32 v87, 0xbfb8aa3b, v83
	v_exp_f32_e32 v86, v86
	v_exp_f32_e32 v87, v87
	v_div_scale_f32 v39, vcc, v2, v38, v2
	v_mul_f32_e32 v111, v39, v110
	v_fma_f32 v108, -v107, v111, v39
	v_fmac_f32_e32 v111, v108, v110
	v_pk_add_f32 v[108:109], v[86:87], 1.0 op_sel_hi:[1,0]
	v_fma_f32 v39, -v107, v111, v39
	v_div_scale_f32 v86, s[42:43], v109, v109, v83
	v_rcp_f32_e32 v87, v86
	v_div_fmas_f32 v39, v39, v110, v111
	v_div_fixup_f32 v2, v39, v38, v2
	v_pk_fma_f32 v[94:95], v[52:53], v[100:101], v[94:95]
	v_fma_f32 v38, -v86, v87, 1.0
	v_fmac_f32_e32 v87, v38, v87
	v_div_scale_f32 v38, vcc, v83, v109, v83
	v_mul_f32_e32 v39, v38, v87
	v_fma_f32 v107, -v86, v39, v38
	v_fmac_f32_e32 v39, v107, v87
	v_fma_f32 v38, -v86, v39, v38
	v_div_scale_f32 v107, s[42:43], v108, v108, v82
	v_rcp_f32_e32 v112, v107
	v_div_fmas_f32 v38, v38, v87, v39
	v_and_b32_e32 v86, 0xffff0000, v34
	v_lshlrev_b32_e32 v87, 16, v34
	v_pk_fma_f32 v[36:37], v[6:7], v[86:87], v[36:37]
	v_div_fixup_f32 v39, v38, v109, v83
	v_mul_f32_e32 v109, 0xbfb8aa3b, v37
	v_exp_f32_e32 v111, v109
	v_mul_f32_e32 v109, 0xbfb8aa3b, v36
	v_fma_f32 v38, -v107, v112, 1.0
	v_exp_f32_e32 v110, v109
	v_fmac_f32_e32 v112, v38, v112
	v_div_scale_f32 v38, vcc, v82, v108, v82
	v_mul_f32_e32 v83, v38, v112
	v_fma_f32 v109, -v107, v83, v38
	v_fmac_f32_e32 v83, v109, v112
	v_pk_add_f32 v[110:111], v[110:111], 1.0 op_sel_hi:[1,0]
	v_fma_f32 v38, -v107, v83, v38
	v_div_scale_f32 v107, s[42:43], v111, v111, v37
	v_rcp_f32_e32 v109, v107
	v_div_fmas_f32 v38, v38, v112, v83
	v_div_fixup_f32 v38, v38, v108, v82
	v_fma_f32 v82, -v107, v109, 1.0
	v_fmac_f32_e32 v109, v82, v109
	v_div_scale_f32 v82, vcc, v37, v111, v37
	v_mul_f32_e32 v83, v82, v109
	v_fma_f32 v108, -v107, v83, v82
	v_fmac_f32_e32 v83, v108, v109
	v_fma_f32 v82, -v107, v83, v82
	v_div_scale_f32 v107, s[42:43], v110, v110, v36
	v_rcp_f32_e32 v112, v107
	v_div_fmas_f32 v82, v82, v109, v83
	v_div_fixup_f32 v37, v82, v111, v37
	v_lshlrev_b32_e32 v83, 16, v35
	v_fma_f32 v82, -v107, v112, 1.0
	v_fmac_f32_e32 v112, v82, v112
	v_and_b32_e32 v82, 0xffff0000, v35
	v_pk_fma_f32 v[94:95], v[58:59], v[82:83], v[94:95]
	v_div_scale_f32 v111, vcc, v36, v110, v36
	v_mul_f32_e32 v108, 0xbfb8aa3b, v95
	v_exp_f32_e32 v109, v108
	v_mul_f32_e32 v108, 0xbfb8aa3b, v94
	v_exp_f32_e32 v108, v108
	v_mul_f32_e32 v113, v111, v112
	v_fma_f32 v114, -v107, v113, v111
	v_fmac_f32_e32 v113, v114, v112
	v_pk_add_f32 v[108:109], v[108:109], 1.0 op_sel_hi:[1,0]
	v_fma_f32 v107, -v107, v113, v111
	v_div_scale_f32 v111, s[42:43], v109, v109, v95
	v_rcp_f32_e32 v114, v111
	v_div_fmas_f32 v107, v107, v112, v113
	v_div_fixup_f32 v36, v107, v110, v36
	v_fma_f32 v107, -v111, v114, 1.0
	v_fmac_f32_e32 v114, v107, v114
	v_div_scale_f32 v107, vcc, v95, v109, v95
	v_mul_f32_e32 v110, v107, v114
	v_fma_f32 v112, -v111, v110, v107
	v_fmac_f32_e32 v110, v112, v114
	v_fma_f32 v107, -v111, v110, v107
	v_div_scale_f32 v111, s[42:43], v108, v108, v94
	v_rcp_f32_e32 v112, v111
	v_div_fmas_f32 v107, v107, v114, v110
	v_div_fixup_f32 v95, v107, v109, v95
	v_fma_f32 v107, -v111, v112, 1.0
	v_fmac_f32_e32 v112, v107, v112
	v_div_scale_f32 v107, vcc, v94, v108, v94
	v_mul_f32_e32 v109, v107, v112
	v_fma_f32 v110, -v111, v109, v107
	v_fmac_f32_e32 v109, v110, v112
	v_fma_f32 v107, -v111, v109, v107
	v_div_fmas_f32 v107, v107, v112, v109
	v_div_fixup_f32 v94, v107, v108, v94
	s_and_saveexec_b64 s[42:43], s[40:41]
	s_cbranch_execz .LBB0_150
	v_pk_mul_f32 v[108:109], v[2:3], v[2:3]
	v_pk_mul_f32 v[110:111], v[38:39], v[38:39]
	v_add_f32_e32 v0, v108, v109
	v_add_f32_e32 v0, v110, v0
	v_pk_mul_f32 v[112:113], v[36:37], v[36:37]
	v_add_f32_e32 v0, v111, v0
	v_and_b32_e32 v108, 64, v190
	v_add_f32_e32 v0, v113, v0
	v_xor_b32_e32 v107, 1, v190
	v_add_u32_e32 v108, 64, v108
	v_pk_mul_f32 v[114:115], v[94:95], v[94:95]
	v_add_f32_e32 v0, v112, v0
	v_cmp_lt_i32_e32 vcc, v107, v108
	v_add_f32_e32 v0, v115, v0
	v_add_f32_e32 v0, v114, v0
	s_nop 1
	v_add_f32_dpp v0, v0, v0 quad_perm:[1,0,3,2] row_mask:0xf bank_mask:0xf
	s_nop 1
	v_add_f32_dpp v0, v0, v0 quad_perm:[2,3,0,1] row_mask:0xf bank_mask:0xf
	s_nop 1
	v_add_f32_dpp v0, v0, v0 row_half_mirror row_mask:0xf bank_mask:0xf
	s_nop 1
	v_add_f32_dpp v0, v0, v0 row_mirror row_mask:0xf bank_mask:0xf
	v_add_f32_e32 v0, 0x358637bd, v0
	v_mul_f32_e32 v107, 0x4b800000, v0
	v_cmp_gt_f32_e32 vcc, s39, v0
	s_nop 1
	v_cndmask_b32_e32 v0, v0, v107, vcc
	v_rsq_f32_e32 v0, v0
	s_nop 0
	v_mul_f32_e32 v107, 0x45800000, v0
	v_cndmask_b32_e32 v0, v0, v107, vcc
	v_mul_f32_e32 v0, v106, v0

; __device__ __forceinline__ unsigned cvtpk_s(float lo, float hi) { f32x2_t v = {lo, hi}; bf16x2_t b = __builtin_convertvector(v, bf16x2_t); return __builtin_bit_cast(unsigned, b); }
; __device__ __forceinline__ float silu_f(float z) { return z / (1.f + __expf(-z)); }
; __device__ __forceinline__ void unpack8(const u32x4 v, float (&f)[8]) { f[0] = bf_lo(v.x); f[1] = bf_hi(v.x); f[2] = bf_lo(v.y); f[3] = bf_hi(v.y); f[4] = bf_lo(v.z); f[5] = bf_hi(v.z); f[6] = bf_lo(v.w); f[7] = bf_hi(v.w); }
; __device__ __forceinline__ void dn_conv_phase(bf16_t* P, const bf16_t* HALO, const float* conv_w, int G) {
;     ...
;             float x0[8], x1[8], x2[8], x3[8], x4[8], y[8];
;             unpack8(w0, x0); unpack8(w1, x1); unpack8(w2, x2); unpack8(w3, x3); unpack8(w4, x4);
;             float ss = 0.f;
; #pragma unroll
;             for (int c = 0; c < 8; ++c) { const float a = x0[c] * cw[c][0] + x1[c] * cw[c][1] + x2[c] * cw[c][2] + x3[c] * cw[c][3] + x4[c] * cw[c][4]; y[c] = silu_f(a); ss += y[c] * y[c]; }
;             float sc = 1.f;
;             if (kind < 2) { ss += __shfl_xor(ss, 1); ss += __shfl_xor(ss, 2); ss += __shfl_xor(ss, 4); ss += __shfl_xor(ss, 8); sc = rsqrtf(ss + EPS) * (kind == 0 ? 0.08838834764831845f : 1.f); }
;             u32x4 o; o.x = cvtpk_s(y[0] * sc, y[1] * sc); o.y = cvtpk_s(y[2] * sc, y[3] * sc); o.z = cvtpk_s(y[4] * sc, y[5] * sc); o.w = cvtpk_s(y[6] * sc, y[7] * sc);
.LBB0_155:
	v_pk_mul_f32 v[76:77], v[18:19], v[76:77]
	s_waitcnt vmcnt(0)
	v_lshlrev_b32_e32 v2, 16, v36
	v_pk_fma_f32 v[76:77], v[70:71], v[78:79], v[76:77]
	v_and_b32_e32 v3, 0xffff0000, v36
	v_pk_fma_f32 v[76:77], v[20:21], v[98:99], v[76:77]
	v_pk_mul_f32 v[40:41], v[10:11], v[40:41]
	v_pk_fma_f32 v[76:77], v[16:17], v[104:105], v[76:77]
	v_pk_fma_f32 v[40:41], v[68:69], v[80:81], v[40:41]
	v_pk_fma_f32 v[2:3], v[22:23], v[2:3], v[76:77]
	v_pk_fma_f32 v[40:41], v[12:13], v[96:97], v[40:41]
	v_mul_f32_e32 v0, 0xbfb8aa3b, v2
	v_exp_f32_e32 v76, v0
	v_mul_f32_e32 v0, 0xbfb8aa3b, v3
	v_exp_f32_e32 v77, v0
	v_pk_fma_f32 v[40:41], v[66:67], v[102:103], v[40:41]
	v_pk_mul_f32 v[42:43], v[56:57], v[42:43]
	v_mov_b32_e32 v0, 1.0
	v_pk_add_f32 v[76:77], v[76:77], 1.0 op_sel_hi:[1,0]
	v_pk_fma_f32 v[42:43], v[4:5], v[90:91], v[42:43]
	v_div_scale_f32 v78, s[0:1], v77, v77, v3
	v_rcp_f32_e32 v79, v78
	v_pk_fma_f32 v[42:43], v[54:55], v[100:101], v[42:43]
	v_fma_f32 v94, -v78, v79, 1.0
	v_fmac_f32_e32 v79, v94, v79
	v_div_scale_f32 v94, vcc, v3, v77, v3
	v_mul_f32_e32 v95, v94, v79
	v_fma_f32 v98, -v78, v95, v94
	v_fmac_f32_e32 v95, v98, v79
	v_fma_f32 v78, -v78, v95, v94
	v_div_scale_f32 v94, s[0:1], v76, v76, v2
	v_div_fmas_f32 v78, v78, v79, v95
	v_rcp_f32_e32 v98, v94
	v_div_fixup_f32 v3, v78, v77, v3
	v_lshlrev_b32_e32 v78, 16, v37
	v_and_b32_e32 v79, 0xffff0000, v37
	v_pk_fma_f32 v[40:41], v[14:15], v[78:79], v[40:41]
	v_fma_f32 v77, -v94, v98, 1.0
	v_mul_f32_e32 v78, 0xbfb8aa3b, v40
	v_mul_f32_e32 v79, 0xbfb8aa3b, v41
	v_exp_f32_e32 v78, v78
	v_exp_f32_e32 v79, v79
	v_fmac_f32_e32 v98, v77, v98
	v_div_scale_f32 v77, vcc, v2, v76, v2
	v_mul_f32_e32 v95, v77, v98
	v_fma_f32 v80, -v94, v95, v77
	v_pk_add_f32 v[78:79], v[78:79], 1.0 op_sel_hi:[1,0]
	v_fmac_f32_e32 v95, v80, v98
	v_div_scale_f32 v80, s[0:1], v79, v79, v41
	v_rcp_f32_e32 v81, v80
	v_fma_f32 v77, -v94, v95, v77
	v_div_fmas_f32 v77, v77, v98, v95
	v_div_fixup_f32 v2, v77, v76, v2
	v_fma_f32 v76, -v80, v81, 1.0
	v_fmac_f32_e32 v81, v76, v81
	v_div_scale_f32 v76, vcc, v41, v79, v41
	v_mul_f32_e32 v77, v76, v81
	v_fma_f32 v94, -v80, v77, v76
	v_fmac_f32_e32 v77, v94, v81
	v_div_scale_f32 v94, s[0:1], v78, v78, v40
	v_rcp_f32_e32 v95, v94
	v_fma_f32 v76, -v80, v77, v76
	v_div_fmas_f32 v76, v76, v81, v77
	v_pk_mul_f32 v[80:81], v[64:65], v[84:85]
	v_div_fixup_f32 v41, v76, v79, v41
	v_pk_fma_f32 v[80:81], v[8:9], v[88:89], v[80:81]
	v_fma_f32 v76, -v94, v95, 1.0
	v_pk_fma_f32 v[80:81], v[62:63], v[92:93], v[80:81]
	v_fmac_f32_e32 v95, v76, v95
	v_and_b32_e32 v76, 0xffff0000, v38
	v_lshlrev_b32_e32 v77, 16, v38
	v_pk_fma_f32 v[80:81], v[60:61], v[86:87], v[80:81]
	v_div_scale_f32 v79, vcc, v40, v78, v40
	v_pk_fma_f32 v[76:77], v[6:7], v[76:77], v[80:81]
	v_mul_f32_e32 v96, v79, v95
	v_mul_f32_e32 v80, 0xbfb8aa3b, v77
	v_exp_f32_e32 v81, v80
	v_mul_f32_e32 v80, 0xbfb8aa3b, v76
	v_exp_f32_e32 v80, v80
	v_fma_f32 v84, -v94, v96, v79
	v_fmac_f32_e32 v96, v84, v95
	v_fma_f32 v79, -v94, v96, v79
	v_pk_add_f32 v[80:81], v[80:81], 1.0 op_sel_hi:[1,0]
	v_div_fmas_f32 v79, v79, v95, v96
	v_div_scale_f32 v84, s[0:1], v81, v81, v77
	v_rcp_f32_e32 v85, v84
	v_div_fixup_f32 v40, v79, v78, v40
	v_pk_fma_f32 v[42:43], v[52:53], v[82:83], v[42:43]
	v_fma_f32 v78, -v84, v85, 1.0
	v_fmac_f32_e32 v85, v78, v85
	v_div_scale_f32 v78, vcc, v77, v81, v77
	v_mul_f32_e32 v79, v78, v85
	v_fma_f32 v86, -v84, v79, v78
	v_fmac_f32_e32 v79, v86, v85
	v_fma_f32 v78, -v84, v79, v78
	v_div_scale_f32 v84, s[0:1], v80, v80, v76
	v_rcp_f32_e32 v86, v84
	v_div_fmas_f32 v78, v78, v85, v79
	v_div_fixup_f32 v77, v78, v81, v77
	v_lshlrev_b32_e32 v79, 16, v39
	v_fma_f32 v78, -v84, v86, 1.0
	v_fmac_f32_e32 v86, v78, v86
	v_and_b32_e32 v78, 0xffff0000, v39
	v_pk_fma_f32 v[42:43], v[58:59], v[78:79], v[42:43]
	v_div_scale_f32 v81, vcc, v76, v80, v76
	v_mul_f32_e32 v78, 0xbfb8aa3b, v43
	v_exp_f32_e32 v79, v78
	v_mul_f32_e32 v78, 0xbfb8aa3b, v42
	v_exp_f32_e32 v78, v78
	v_mul_f32_e32 v85, v81, v86
	v_fma_f32 v82, -v84, v85, v81
	v_fmac_f32_e32 v85, v82, v86
	v_pk_add_f32 v[78:79], v[78:79], 1.0 op_sel_hi:[1,0]
	v_fma_f32 v81, -v84, v85, v81
	v_div_scale_f32 v82, s[0:1], v79, v79, v43
	v_rcp_f32_e32 v83, v82
	v_div_fmas_f32 v81, v81, v86, v85
	v_div_fixup_f32 v76, v81, v80, v76
	v_fma_f32 v80, -v82, v83, 1.0
	v_fmac_f32_e32 v83, v80, v83
	v_div_scale_f32 v80, vcc, v43, v79, v43
	v_mul_f32_e32 v81, v80, v83
	v_fma_f32 v84, -v82, v81, v80
	v_fmac_f32_e32 v81, v84, v83
	v_fma_f32 v80, -v82, v81, v80
	v_div_scale_f32 v82, s[0:1], v78, v78, v42
	v_rcp_f32_e32 v84, v82
	v_div_fmas_f32 v80, v80, v83, v81
	v_div_fixup_f32 v43, v80, v79, v43
	v_fma_f32 v79, -v82, v84, 1.0
	v_fmac_f32_e32 v84, v79, v84
	v_div_scale_f32 v79, vcc, v42, v78, v42
	v_mul_f32_e32 v80, v79, v84
	v_fma_f32 v81, -v82, v80, v79
	v_fmac_f32_e32 v80, v81, v84
	v_fma_f32 v79, -v82, v80, v79
	v_div_fmas_f32 v79, v79, v84, v80
	v_div_fixup_f32 v42, v79, v78, v42
	s_and_saveexec_b64 s[0:1], s[40:41]
	s_cbranch_execz .LBB0_138
	v_pk_mul_f32 v[78:79], v[2:3], v[2:3]
	v_pk_mul_f32 v[80:81], v[40:41], v[40:41]
	v_add_f32_e32 v0, v78, v79
	v_add_f32_e32 v0, v80, v0
	v_pk_mul_f32 v[82:83], v[76:77], v[76:77]
	v_add_f32_e32 v0, v81, v0
	v_and_b32_e32 v79, 64, v190
	v_add_f32_e32 v0, v83, v0
	v_xor_b32_e32 v78, 1, v190
	v_add_u32_e32 v79, 64, v79
	v_pk_mul_f32 v[84:85], v[42:43], v[42:43]
	v_add_f32_e32 v0, v82, v0
	v_cmp_lt_i32_e32 vcc, v78, v79
	v_add_f32_e32 v0, v85, v0
	v_add_f32_e32 v0, v84, v0
	s_nop 1
	v_add_f32_dpp v0, v0, v0 quad_perm:[1,0,3,2] row_mask:0xf bank_mask:0xf
	s_nop 1
	v_add_f32_dpp v0, v0, v0 quad_perm:[2,3,0,1] row_mask:0xf bank_mask:0xf
	s_nop 1
	v_add_f32_dpp v0, v0, v0 row_half_mirror row_mask:0xf bank_mask:0xf
	s_nop 1
	v_add_f32_dpp v0, v0, v0 row_mirror row_mask:0xf bank_mask:0xf
	v_add_f32_e32 v0, 0x358637bd, v0
	v_mul_f32_e32 v78, 0x4b800000, v0
	v_cmp_gt_f32_e32 vcc, s39, v0
	s_nop 1
	v_cndmask_b32_e32 v0, v0, v78, vcc
	v_rsq_f32_e32 v0, v0
	s_nop 0
	v_mul_f32_e32 v78, 0x45800000, v0
	v_cndmask_b32_e32 v0, v0, v78, vcc
	v_mul_f32_e32 v0, v106, v0
	s_branch .LBB0_138
